# P5 split: per-token selection+U writes {row,weight} records; V phase column-sliced per blockIdx&7 with slice-major fp8 V table (L2-resident 2MB per XCD); separate H3 pass
# speedup vs baseline: 1.1688x; 1.0137x over previous
; __device__ __forceinline__ void convert_item_fp8(const float* __restrict__ src, unsigned char* __restrict__ dst, size_t item, float scale) {
;   size_t base = item * 8192 + (size_t)threadIdx.x * 16;
;   float4 a[2][4];
; #pragma unroll
;   for (int i = 0; i < 2; i++) {
;     const float4* q = (const float4*)(src + base + i * 4096);
; #pragma unroll
;     for (int j = 0; j < 4; j++) a[i][j] = q[j];
;   }
; #pragma unroll
;   for (int i = 0; i < 2; i++) {
;     unsigned o[4];
; #pragma unroll
;     for (int j = 0; j < 4; j++) {
;       int pk = __builtin_amdgcn_cvt_pk_fp8_f32(a[i][j].x * scale, a[i][j].y * scale, 0, false);
;       pk = __builtin_amdgcn_cvt_pk_fp8_f32(a[i][j].z * scale, a[i][j].w * scale, pk, true);
;       o[j] = (unsigned)pk;
;     }
;     *(uint4*)(dst + base + i * 4096) = make_uint4(o[0], o[1], o[2], o[3]);
;   }
; __device__ __forceinline__ void phase4a(const Params& p, char* smem) {
;     ...
;       for (int ci = first; ci < NCONV; ci += stride) {
;         if (ci < 2048) convert_item_fp8(p.expert_u, (unsigned char*)(ws + OFF_EU), ci, EU_SCALE);
;         else convert_item_fp8(p.expert_v, (unsigned char*)(ws + OFF_EV), ci - 2048, EV_SCALE);
.LBB0_1179:
	s_add_u32 s8, s80, s8
	s_waitcnt lgkmcnt(0)
	v_accvgpr_read_b32 v0, a138
	s_addc_u32 s9, s81, s9
	s_lshl_b64 s[10:11], s[10:11], 13
	v_accvgpr_read_b32 v1, a139
	v_lshl_add_u64 v[40:41], s[10:11], 0, v[0:1]
	v_lshl_add_u64 v[24:25], v[40:41], 2, s[12:13]
	global_load_dwordx4 v[0:3], v[24:25], off
	global_load_dwordx4 v[4:7], v[24:25], off offset:16
	global_load_dwordx4 v[8:11], v[24:25], off offset:32
	global_load_dwordx4 v[12:15], v[24:25], off offset:48
	v_lshl_add_u64 v[28:29], v[24:25], 0, s[6:7]
	v_add_co_u32_e32 v24, vcc, s16, v24
	global_load_dwordx4 v[16:19], v[28:29], off offset:16
	global_load_dwordx4 v[20:23], v[28:29], off offset:32
	v_addc_co_u32_e32 v25, vcc, 0, v25, vcc
	global_load_dwordx4 v[24:27], v[24:25], off
	s_nop 0
	global_load_dwordx4 v[28:31], v[28:29], off offset:48
	v_mov_b32_e32 v32, 0
	v_mov_b32_e32 v34, 0
	v_mov_b32_e32 v37, 0
	v_mov_b32_e32 v33, 0
	v_mov_b32_e32 v35, 0
	v_mov_b32_e32 v36, 0
	v_mov_b32_e32 v38, 0
	v_mov_b32_e32 v39, 0
	s_mov_b32 s98, 0x1000
	s_cmp_eq_u32 s17, 0x41800000
	s_cbranch_scc0 .Lp4a_cv_eu
	v_and_b32_e32 v42, 0x380, v40
	v_lshrrev_b32_e32 v43, 3, v40
	v_lshlrev_b32_e32 v42, 14, v42
	v_and_b32_e32 v43, 0x1fff80, v43
	v_and_b32_e32 v40, 0x7f, v40
	v_or3_b32 v40, v40, v42, v43
	s_movk_i32 s98, 0x200
.Lp4a_cv_eu:
	s_add_u32 s0, s0, s14
	v_lshl_add_u64 v[40:41], s[8:9], 0, v[40:41]
	v_add_co_u32_e32 v42, vcc, s98, v40
	s_addc_u32 s1, s1, s15
	s_nop 0
	v_addc_co_u32_e32 v43, vcc, 0, v41, vcc
	s_cmpk_lt_i32 s0, 0x1000
	s_waitcnt vmcnt(7)
	v_mul_f32_e32 v0, s17, v0
	v_mul_f32_e32 v1, s17, v1
	s_waitcnt vmcnt(5)
	v_mul_f32_e32 v8, s17, v8
	v_mul_f32_e32 v9, s17, v9
	v_cvt_pk_fp8_f32 v32, v0, v1
	v_mul_f32_e32 v4, s17, v4
	s_waitcnt vmcnt(3)
	v_mul_f32_e32 v0, s17, v16
	v_mul_f32_e32 v1, s17, v17
	v_mul_f32_e32 v5, s17, v5
	v_mul_f32_e32 v12, s17, v12
	v_mul_f32_e32 v13, s17, v13
	v_cvt_pk_fp8_f32 v34, v8, v9
	s_waitcnt vmcnt(2)
	v_mul_f32_e32 v8, s17, v20
	v_mul_f32_e32 v9, s17, v21
	s_waitcnt vmcnt(1)
	v_mul_f32_e32 v16, s17, v24
	v_mul_f32_e32 v17, s17, v25
	v_cvt_pk_fp8_f32 v37, v0, v1
	s_waitcnt vmcnt(0)
	v_mul_f32_e32 v0, s17, v28
	v_mul_f32_e32 v1, s17, v29
	v_cvt_pk_fp8_f32 v33, v4, v5
	v_cvt_pk_fp8_f32 v35, v12, v13
	v_cvt_pk_fp8_f32 v38, v8, v9
	v_cvt_pk_fp8_f32 v36, v16, v17
	v_cvt_pk_fp8_f32 v39, v0, v1
	v_mul_f32_e32 v2, s17, v2
	v_mul_f32_e32 v3, s17, v3
	v_mul_f32_e32 v6, s17, v6
	v_mul_f32_e32 v7, s17, v7
	v_mul_f32_e32 v10, s17, v10
	v_mul_f32_e32 v11, s17, v11
	v_mul_f32_e32 v14, s17, v14
	v_mul_f32_e32 v15, s17, v15
	v_mul_f32_e32 v4, s17, v18
	v_mul_f32_e32 v5, s17, v19
	v_mul_f32_e32 v12, s17, v22
	v_mul_f32_e32 v13, s17, v23
	v_mul_f32_e32 v18, s17, v26
	v_mul_f32_e32 v19, s17, v27
	v_mul_f32_e32 v8, s17, v30
	v_mul_f32_e32 v9, s17, v31
	v_cvt_pk_fp8_f32 v32, v2, v3 op_sel:[0,0,1]
	v_cvt_pk_fp8_f32 v33, v6, v7 op_sel:[0,0,1]
	v_cvt_pk_fp8_f32 v34, v10, v11 op_sel:[0,0,1]
	v_cvt_pk_fp8_f32 v35, v14, v15 op_sel:[0,0,1]
	v_cvt_pk_fp8_f32 v37, v4, v5 op_sel:[0,0,1]
	v_cvt_pk_fp8_f32 v38, v12, v13 op_sel:[0,0,1]
	v_cvt_pk_fp8_f32 v36, v18, v19 op_sel:[0,0,1]
	v_cvt_pk_fp8_f32 v39, v8, v9 op_sel:[0,0,1]
	global_store_dwordx4 v[40:41], v[32:35], off
	global_store_dwordx4 v[42:43], v[36:39], off
	s_cbranch_scc0 .LBB0_1182

; __device__ __forceinline__ void phase5(const Params& p, char* smem, const bool store_x = true) {
;     ...
;   for (int it = blockIdx.x; it < NT / 4; it += gridDim.x) {
;     const int tok = it * 4 + w;
;     float* xr = X + (size_t)tok * 1024 + lane * 16;
;     const float4 xv0 = *(const float4*)(xr), xv1 = *(const float4*)(xr + 4), xv2 = *(const float4*)(xr + 8), xv3 = *(const float4*)(xr + 12);
;     ((uint4*)tsL)[lane] = pf_ts;
;     ((uint4*)tiL)[lane] = pf_ti;
;     const uint4 cur_ha = pf_ha, cur_hb = pf_hb; const float cur_rs = rsqrtf(pf_ss * (1.f / 1024.f) + EPSF);
;     {
;       const int itn = it + (int)gridDim.x;
;       if (itn < NT / 4) {
;         const int tokn = itn * 4 + w;
;         pf_ts = ((const uint4*)(TOPS + (size_t)tokn * 256))[lane];
;         pf_ti = ((const uint4*)(TOPI + (size_t)tokn * 256))[lane];
;         pf_ha = *(const uint4*)(X1B + (size_t)tokn * 1024 + lane * 16);
;         pf_hb = *(const uint4*)(X1B + (size_t)tokn * 1024 + lane * 16 + 8);
;         pf_ss = SSQ1[tokn];
;       }
;     }
.LBB0_1482:
	v_accvgpr_read_b32 v0, a129
	v_lshl_add_u32 v32, s44, 2, v0
	v_ashrrev_i32_e32 v33, 31, v32
	v_accvgpr_read_b32 v2, a70
	v_lshlrev_b64 v[0:1], 12, v[32:33]
	v_accvgpr_read_b32 v3, a71
	v_lshl_add_u64 v[198:199], v[2:3], 0, v[0:1]
	s_add_i32 s44, s44, s82
	s_cmpk_gt_i32 s44, 0x107f
	s_cselect_b64 s[34:35], -1, 0
	v_accvgpr_write_b32 a12, v96
	v_accvgpr_write_b32 a14, v98
	v_accvgpr_write_b32 a8, v100
	v_accvgpr_write_b32 a10, v102
	s_and_b64 vcc, exec, s[34:35]
	v_accvgpr_write_b32 a13, v97
	v_accvgpr_write_b32 a15, v99
	v_accvgpr_write_b32 a9, v101
	v_accvgpr_write_b32 a11, v103
	ds_write_b128 v177, a[0:3] offset:2048
	ds_write_b128 v177, a[4:7] offset:3072
	s_cbranch_vccnz .LBB0_1484
	v_accvgpr_read_b32 v0, a129
	v_lshl_add_u32 v0, s44, 2, v0
	v_ashrrev_i32_e32 v1, 31, v0
	v_accvgpr_read_b32 v4, a72
	v_accvgpr_read_b32 v6, a74
	v_lshlrev_b64 v[2:3], 10, v[0:1]
	v_accvgpr_read_b32 v5, a73
	v_accvgpr_read_b32 v7, a75
	v_lshl_add_u64 v[4:5], v[4:5], 0, v[2:3]
	v_lshl_add_u64 v[2:3], v[6:7], 0, v[2:3]
	global_load_dwordx4 a[0:3], v[4:5], off
	global_load_dwordx4 a[4:7], v[2:3], off
	v_lshlrev_b64 v[2:3], 11, v[0:1]
	v_lshl_add_u64 v[2:3], v[188:189], 0, v[2:3]
	v_lshl_add_u64 v[0:1], v[0:1], 2, s[94:95]
	global_load_dwordx4 a[12:15], v[2:3], off offset:16
	global_load_dwordx4 a[8:11], v[2:3], off
	global_load_dword v240, v[0:1], off

.Lp5_ev_skipped:
	s_waitcnt vmcnt(31)
	v_cvt_pk_f32_fp8_e32 v[0:1], v156
	v_cvt_pk_f32_fp8_sdwa v[2:3], v156 src0_sel:WORD_1
	v_pk_fma_f32 v[0:1], v[0:1], v[160:161], 0 op_sel_hi:[1,1,0]
	s_nop 0
	v_pk_fma_f32 v[0:1], v[2:3], v[162:163], v[0:1]
	v_cvt_pk_f32_fp8_e32 v[2:3], v157
	v_pk_fma_f32 v[0:1], v[2:3], v[164:165], v[0:1]
	v_cvt_pk_f32_fp8_sdwa v[2:3], v157 src0_sel:WORD_1
	v_pk_fma_f32 v[0:1], v[2:3], v[166:167], v[0:1]
	v_cvt_pk_f32_fp8_e32 v[2:3], v158
	v_pk_fma_f32 v[0:1], v[2:3], v[168:169], v[0:1]
	v_cvt_pk_f32_fp8_sdwa v[2:3], v158 src0_sel:WORD_1
	v_pk_fma_f32 v[0:1], v[2:3], v[170:171], v[0:1]
	v_cvt_pk_f32_fp8_e32 v[2:3], v159
	v_pk_fma_f32 v[0:1], v[2:3], v[172:173], v[0:1]
	v_cvt_pk_f32_fp8_sdwa v[2:3], v159 src0_sel:WORD_1
	v_pk_fma_f32 v[0:1], v[2:3], v[174:175], v[0:1]
	s_nop 0
	v_add_f32_e32 v156, v0, v1
	s_waitcnt vmcnt(30)
	v_cvt_pk_f32_fp8_e32 v[0:1], v152
	v_cvt_pk_f32_fp8_sdwa v[2:3], v152 src0_sel:WORD_1
	v_pk_fma_f32 v[0:1], v[0:1], v[160:161], 0 op_sel_hi:[1,1,0]
	s_nop 0
	v_pk_fma_f32 v[0:1], v[2:3], v[162:163], v[0:1]
	v_cvt_pk_f32_fp8_e32 v[2:3], v153
	v_pk_fma_f32 v[0:1], v[2:3], v[164:165], v[0:1]
	v_cvt_pk_f32_fp8_sdwa v[2:3], v153 src0_sel:WORD_1
	v_pk_fma_f32 v[0:1], v[2:3], v[166:167], v[0:1]
	v_cvt_pk_f32_fp8_e32 v[2:3], v154
	v_pk_fma_f32 v[0:1], v[2:3], v[168:169], v[0:1]
	v_cvt_pk_f32_fp8_sdwa v[2:3], v154 src0_sel:WORD_1
	v_pk_fma_f32 v[0:1], v[2:3], v[170:171], v[0:1]
	v_cvt_pk_f32_fp8_e32 v[2:3], v155
	v_pk_fma_f32 v[0:1], v[2:3], v[172:173], v[0:1]
	v_cvt_pk_f32_fp8_sdwa v[2:3], v155 src0_sel:WORD_1
	v_pk_fma_f32 v[0:1], v[2:3], v[174:175], v[0:1]
	s_nop 0
	v_add_f32_e32 v152, v0, v1
	s_waitcnt vmcnt(29)
	v_cvt_pk_f32_fp8_e32 v[0:1], v148
	v_cvt_pk_f32_fp8_sdwa v[2:3], v148 src0_sel:WORD_1
	v_pk_fma_f32 v[0:1], v[0:1], v[160:161], 0 op_sel_hi:[1,1,0]
	s_nop 0
	v_pk_fma_f32 v[0:1], v[2:3], v[162:163], v[0:1]
	v_cvt_pk_f32_fp8_e32 v[2:3], v149
	v_pk_fma_f32 v[0:1], v[2:3], v[164:165], v[0:1]
	v_cvt_pk_f32_fp8_sdwa v[2:3], v149 src0_sel:WORD_1
	v_pk_fma_f32 v[0:1], v[2:3], v[166:167], v[0:1]
	v_cvt_pk_f32_fp8_e32 v[2:3], v150
	v_pk_fma_f32 v[0:1], v[2:3], v[168:169], v[0:1]
	v_cvt_pk_f32_fp8_sdwa v[2:3], v150 src0_sel:WORD_1
	v_pk_fma_f32 v[0:1], v[2:3], v[170:171], v[0:1]
	v_cvt_pk_f32_fp8_e32 v[2:3], v151
	v_pk_fma_f32 v[0:1], v[2:3], v[172:173], v[0:1]
	v_cvt_pk_f32_fp8_sdwa v[2:3], v151 src0_sel:WORD_1
	v_pk_fma_f32 v[0:1], v[2:3], v[174:175], v[0:1]
	s_nop 0
	v_add_f32_e32 v148, v0, v1
	s_waitcnt vmcnt(28)
	v_cvt_pk_f32_fp8_e32 v[0:1], v144
	v_cvt_pk_f32_fp8_sdwa v[2:3], v144 src0_sel:WORD_1
	v_pk_fma_f32 v[0:1], v[0:1], v[160:161], 0 op_sel_hi:[1,1,0]
	s_nop 0
	v_pk_fma_f32 v[0:1], v[2:3], v[162:163], v[0:1]
	v_cvt_pk_f32_fp8_e32 v[2:3], v145
	v_pk_fma_f32 v[0:1], v[2:3], v[164:165], v[0:1]
	v_cvt_pk_f32_fp8_sdwa v[2:3], v145 src0_sel:WORD_1
	v_pk_fma_f32 v[0:1], v[2:3], v[166:167], v[0:1]
	v_cvt_pk_f32_fp8_e32 v[2:3], v146
	v_pk_fma_f32 v[0:1], v[2:3], v[168:169], v[0:1]
	v_cvt_pk_f32_fp8_sdwa v[2:3], v146 src0_sel:WORD_1
	v_pk_fma_f32 v[0:1], v[2:3], v[170:171], v[0:1]
	v_cvt_pk_f32_fp8_e32 v[2:3], v147
	v_pk_fma_f32 v[0:1], v[2:3], v[172:173], v[0:1]
	v_cvt_pk_f32_fp8_sdwa v[2:3], v147 src0_sel:WORD_1
	v_pk_fma_f32 v[0:1], v[2:3], v[174:175], v[0:1]
	s_nop 0
	v_add_f32_e32 v144, v0, v1
	s_waitcnt vmcnt(27)
	v_cvt_pk_f32_fp8_e32 v[0:1], v140
	v_cvt_pk_f32_fp8_sdwa v[2:3], v140 src0_sel:WORD_1
	v_pk_fma_f32 v[0:1], v[0:1], v[160:161], 0 op_sel_hi:[1,1,0]
	s_nop 0
	v_pk_fma_f32 v[0:1], v[2:3], v[162:163], v[0:1]
	v_cvt_pk_f32_fp8_e32 v[2:3], v141
	v_pk_fma_f32 v[0:1], v[2:3], v[164:165], v[0:1]
	v_cvt_pk_f32_fp8_sdwa v[2:3], v141 src0_sel:WORD_1
	v_pk_fma_f32 v[0:1], v[2:3], v[166:167], v[0:1]
	v_cvt_pk_f32_fp8_e32 v[2:3], v142
	v_pk_fma_f32 v[0:1], v[2:3], v[168:169], v[0:1]
	v_cvt_pk_f32_fp8_sdwa v[2:3], v142 src0_sel:WORD_1
	v_pk_fma_f32 v[0:1], v[2:3], v[170:171], v[0:1]
	v_cvt_pk_f32_fp8_e32 v[2:3], v143
	v_pk_fma_f32 v[0:1], v[2:3], v[172:173], v[0:1]
	v_cvt_pk_f32_fp8_sdwa v[2:3], v143 src0_sel:WORD_1
	v_pk_fma_f32 v[0:1], v[2:3], v[174:175], v[0:1]
	s_nop 0
	v_add_f32_e32 v140, v0, v1
	s_waitcnt vmcnt(26)
	v_cvt_pk_f32_fp8_e32 v[0:1], v136
	v_cvt_pk_f32_fp8_sdwa v[2:3], v136 src0_sel:WORD_1
	v_pk_fma_f32 v[0:1], v[0:1], v[160:161], 0 op_sel_hi:[1,1,0]
	s_nop 0
	v_pk_fma_f32 v[0:1], v[2:3], v[162:163], v[0:1]
	v_cvt_pk_f32_fp8_e32 v[2:3], v137
	v_pk_fma_f32 v[0:1], v[2:3], v[164:165], v[0:1]
	v_cvt_pk_f32_fp8_sdwa v[2:3], v137 src0_sel:WORD_1
	v_pk_fma_f32 v[0:1], v[2:3], v[166:167], v[0:1]
	v_cvt_pk_f32_fp8_e32 v[2:3], v138
	v_pk_fma_f32 v[0:1], v[2:3], v[168:169], v[0:1]
	v_cvt_pk_f32_fp8_sdwa v[2:3], v138 src0_sel:WORD_1
	v_pk_fma_f32 v[0:1], v[2:3], v[170:171], v[0:1]
	v_cvt_pk_f32_fp8_e32 v[2:3], v139
	v_pk_fma_f32 v[0:1], v[2:3], v[172:173], v[0:1]
	v_cvt_pk_f32_fp8_sdwa v[2:3], v139 src0_sel:WORD_1
	v_pk_fma_f32 v[0:1], v[2:3], v[174:175], v[0:1]
	s_nop 0
	v_add_f32_e32 v136, v0, v1
	s_waitcnt vmcnt(25)
	v_cvt_pk_f32_fp8_e32 v[0:1], v132
	v_cvt_pk_f32_fp8_sdwa v[2:3], v132 src0_sel:WORD_1
	v_pk_fma_f32 v[0:1], v[0:1], v[160:161], 0 op_sel_hi:[1,1,0]
	s_nop 0
	v_pk_fma_f32 v[0:1], v[2:3], v[162:163], v[0:1]
	v_cvt_pk_f32_fp8_e32 v[2:3], v133
	v_pk_fma_f32 v[0:1], v[2:3], v[164:165], v[0:1]
	v_cvt_pk_f32_fp8_sdwa v[2:3], v133 src0_sel:WORD_1
	v_pk_fma_f32 v[0:1], v[2:3], v[166:167], v[0:1]
	v_cvt_pk_f32_fp8_e32 v[2:3], v134
	v_pk_fma_f32 v[0:1], v[2:3], v[168:169], v[0:1]
	v_cvt_pk_f32_fp8_sdwa v[2:3], v134 src0_sel:WORD_1
	v_pk_fma_f32 v[0:1], v[2:3], v[170:171], v[0:1]
	v_cvt_pk_f32_fp8_e32 v[2:3], v135
	v_pk_fma_f32 v[0:1], v[2:3], v[172:173], v[0:1]
	v_cvt_pk_f32_fp8_sdwa v[2:3], v135 src0_sel:WORD_1
	v_pk_fma_f32 v[0:1], v[2:3], v[174:175], v[0:1]
	s_nop 0
	v_add_f32_e32 v132, v0, v1
	s_waitcnt vmcnt(24)
	v_cvt_pk_f32_fp8_e32 v[0:1], v128
	v_cvt_pk_f32_fp8_sdwa v[2:3], v128 src0_sel:WORD_1
	v_pk_fma_f32 v[0:1], v[0:1], v[160:161], 0 op_sel_hi:[1,1,0]
	s_nop 0
	v_pk_fma_f32 v[0:1], v[2:3], v[162:163], v[0:1]
	v_cvt_pk_f32_fp8_e32 v[2:3], v129
	v_pk_fma_f32 v[0:1], v[2:3], v[164:165], v[0:1]
	v_cvt_pk_f32_fp8_sdwa v[2:3], v129 src0_sel:WORD_1
	v_pk_fma_f32 v[0:1], v[2:3], v[166:167], v[0:1]
	v_cvt_pk_f32_fp8_e32 v[2:3], v130
	v_pk_fma_f32 v[0:1], v[2:3], v[168:169], v[0:1]
	v_cvt_pk_f32_fp8_sdwa v[2:3], v130 src0_sel:WORD_1
	v_pk_fma_f32 v[0:1], v[2:3], v[170:171], v[0:1]
	v_cvt_pk_f32_fp8_e32 v[2:3], v131
	v_pk_fma_f32 v[0:1], v[2:3], v[172:173], v[0:1]
	v_cvt_pk_f32_fp8_sdwa v[2:3], v131 src0_sel:WORD_1
	v_pk_fma_f32 v[0:1], v[2:3], v[174:175], v[0:1]
	s_nop 0
	v_add_f32_e32 v4, v0, v1
	s_waitcnt vmcnt(23)
	v_cvt_pk_f32_fp8_e32 v[0:1], v124
	v_cvt_pk_f32_fp8_sdwa v[2:3], v124 src0_sel:WORD_1
	v_pk_fma_f32 v[0:1], v[0:1], v[160:161], 0 op_sel_hi:[1,1,0]
	s_nop 0
	v_pk_fma_f32 v[0:1], v[2:3], v[162:163], v[0:1]
	v_cvt_pk_f32_fp8_e32 v[2:3], v125
	v_pk_fma_f32 v[0:1], v[2:3], v[164:165], v[0:1]
	v_cvt_pk_f32_fp8_sdwa v[2:3], v125 src0_sel:WORD_1
	v_pk_fma_f32 v[0:1], v[2:3], v[166:167], v[0:1]
	v_cvt_pk_f32_fp8_e32 v[2:3], v126
	v_pk_fma_f32 v[0:1], v[2:3], v[168:169], v[0:1]
	v_cvt_pk_f32_fp8_sdwa v[2:3], v126 src0_sel:WORD_1
	v_pk_fma_f32 v[0:1], v[2:3], v[170:171], v[0:1]
	v_cvt_pk_f32_fp8_e32 v[2:3], v127
	v_pk_fma_f32 v[0:1], v[2:3], v[172:173], v[0:1]
	v_cvt_pk_f32_fp8_sdwa v[2:3], v127 src0_sel:WORD_1
	v_pk_fma_f32 v[0:1], v[2:3], v[174:175], v[0:1]
	s_nop 0
	v_add_f32_e32 v5, v0, v1
	s_waitcnt vmcnt(22)
	v_cvt_pk_f32_fp8_e32 v[0:1], v120
	v_cvt_pk_f32_fp8_sdwa v[2:3], v120 src0_sel:WORD_1
	v_pk_fma_f32 v[0:1], v[0:1], v[160:161], 0 op_sel_hi:[1,1,0]
	s_nop 0
	v_pk_fma_f32 v[0:1], v[2:3], v[162:163], v[0:1]
	v_cvt_pk_f32_fp8_e32 v[2:3], v121
	v_pk_fma_f32 v[0:1], v[2:3], v[164:165], v[0:1]
	v_cvt_pk_f32_fp8_sdwa v[2:3], v121 src0_sel:WORD_1
	v_pk_fma_f32 v[0:1], v[2:3], v[166:167], v[0:1]
	v_cvt_pk_f32_fp8_e32 v[2:3], v122
	v_pk_fma_f32 v[0:1], v[2:3], v[168:169], v[0:1]
	v_cvt_pk_f32_fp8_sdwa v[2:3], v122 src0_sel:WORD_1
	v_pk_fma_f32 v[0:1], v[2:3], v[170:171], v[0:1]
	v_cvt_pk_f32_fp8_e32 v[2:3], v123
	v_pk_fma_f32 v[0:1], v[2:3], v[172:173], v[0:1]
	v_cvt_pk_f32_fp8_sdwa v[2:3], v123 src0_sel:WORD_1
	v_pk_fma_f32 v[0:1], v[2:3], v[174:175], v[0:1]
	s_nop 0
	v_add_f32_e32 v6, v0, v1
	s_waitcnt vmcnt(21)
	v_cvt_pk_f32_fp8_e32 v[0:1], v116
	v_cvt_pk_f32_fp8_sdwa v[2:3], v116 src0_sel:WORD_1
	v_pk_fma_f32 v[0:1], v[0:1], v[160:161], 0 op_sel_hi:[1,1,0]
	s_nop 0
	v_pk_fma_f32 v[0:1], v[2:3], v[162:163], v[0:1]
	v_cvt_pk_f32_fp8_e32 v[2:3], v117
	v_pk_fma_f32 v[0:1], v[2:3], v[164:165], v[0:1]
	v_cvt_pk_f32_fp8_sdwa v[2:3], v117 src0_sel:WORD_1
	v_pk_fma_f32 v[0:1], v[2:3], v[166:167], v[0:1]
	v_cvt_pk_f32_fp8_e32 v[2:3], v118
	v_pk_fma_f32 v[0:1], v[2:3], v[168:169], v[0:1]
	v_cvt_pk_f32_fp8_sdwa v[2:3], v118 src0_sel:WORD_1
	v_pk_fma_f32 v[0:1], v[2:3], v[170:171], v[0:1]
	v_cvt_pk_f32_fp8_e32 v[2:3], v119
	v_pk_fma_f32 v[0:1], v[2:3], v[172:173], v[0:1]
	v_cvt_pk_f32_fp8_sdwa v[2:3], v119 src0_sel:WORD_1
	v_pk_fma_f32 v[0:1], v[2:3], v[174:175], v[0:1]
	s_nop 0
	v_add_f32_e32 v7, v0, v1
	s_waitcnt vmcnt(20)
	v_cvt_pk_f32_fp8_e32 v[0:1], v112
	v_cvt_pk_f32_fp8_sdwa v[2:3], v112 src0_sel:WORD_1
	v_pk_fma_f32 v[0:1], v[0:1], v[160:161], 0 op_sel_hi:[1,1,0]
	s_nop 0
	v_pk_fma_f32 v[0:1], v[2:3], v[162:163], v[0:1]
	v_cvt_pk_f32_fp8_e32 v[2:3], v113
	v_pk_fma_f32 v[0:1], v[2:3], v[164:165], v[0:1]
	v_cvt_pk_f32_fp8_sdwa v[2:3], v113 src0_sel:WORD_1
	v_pk_fma_f32 v[0:1], v[2:3], v[166:167], v[0:1]
	v_cvt_pk_f32_fp8_e32 v[2:3], v114
	v_pk_fma_f32 v[0:1], v[2:3], v[168:169], v[0:1]
	v_cvt_pk_f32_fp8_sdwa v[2:3], v114 src0_sel:WORD_1
	v_pk_fma_f32 v[0:1], v[2:3], v[170:171], v[0:1]
	v_cvt_pk_f32_fp8_e32 v[2:3], v115
	v_pk_fma_f32 v[0:1], v[2:3], v[172:173], v[0:1]
	v_cvt_pk_f32_fp8_sdwa v[2:3], v115 src0_sel:WORD_1
	v_pk_fma_f32 v[0:1], v[2:3], v[174:175], v[0:1]
	s_nop 0
	v_add_f32_e32 v112, v0, v1
	s_waitcnt vmcnt(19)
	v_cvt_pk_f32_fp8_e32 v[0:1], v108
	v_cvt_pk_f32_fp8_sdwa v[2:3], v108 src0_sel:WORD_1
	v_pk_fma_f32 v[0:1], v[0:1], v[160:161], 0 op_sel_hi:[1,1,0]
	s_nop 0
	v_pk_fma_f32 v[0:1], v[2:3], v[162:163], v[0:1]
	v_cvt_pk_f32_fp8_e32 v[2:3], v109
	v_pk_fma_f32 v[0:1], v[2:3], v[164:165], v[0:1]
	v_cvt_pk_f32_fp8_sdwa v[2:3], v109 src0_sel:WORD_1
	v_pk_fma_f32 v[0:1], v[2:3], v[166:167], v[0:1]
	v_cvt_pk_f32_fp8_e32 v[2:3], v110
	v_pk_fma_f32 v[0:1], v[2:3], v[168:169], v[0:1]
	v_cvt_pk_f32_fp8_sdwa v[2:3], v110 src0_sel:WORD_1
	v_pk_fma_f32 v[0:1], v[2:3], v[170:171], v[0:1]
	v_cvt_pk_f32_fp8_e32 v[2:3], v111
	v_pk_fma_f32 v[0:1], v[2:3], v[172:173], v[0:1]
	v_cvt_pk_f32_fp8_sdwa v[2:3], v111 src0_sel:WORD_1
	v_pk_fma_f32 v[0:1], v[2:3], v[174:175], v[0:1]
	s_nop 0
	v_add_f32_e32 v108, v0, v1
	s_waitcnt vmcnt(18)
	v_cvt_pk_f32_fp8_e32 v[0:1], v104
	v_cvt_pk_f32_fp8_sdwa v[2:3], v104 src0_sel:WORD_1
	v_pk_fma_f32 v[0:1], v[0:1], v[160:161], 0 op_sel_hi:[1,1,0]
	s_nop 0
	v_pk_fma_f32 v[0:1], v[2:3], v[162:163], v[0:1]
	v_cvt_pk_f32_fp8_e32 v[2:3], v105
	v_pk_fma_f32 v[0:1], v[2:3], v[164:165], v[0:1]
	v_cvt_pk_f32_fp8_sdwa v[2:3], v105 src0_sel:WORD_1
	v_pk_fma_f32 v[0:1], v[2:3], v[166:167], v[0:1]
	v_cvt_pk_f32_fp8_e32 v[2:3], v106
	v_pk_fma_f32 v[0:1], v[2:3], v[168:169], v[0:1]
	v_cvt_pk_f32_fp8_sdwa v[2:3], v106 src0_sel:WORD_1
	v_pk_fma_f32 v[0:1], v[2:3], v[170:171], v[0:1]
	v_cvt_pk_f32_fp8_e32 v[2:3], v107
	v_pk_fma_f32 v[0:1], v[2:3], v[172:173], v[0:1]
	v_cvt_pk_f32_fp8_sdwa v[2:3], v107 src0_sel:WORD_1
	v_pk_fma_f32 v[0:1], v[2:3], v[174:175], v[0:1]
	s_nop 0
	v_add_f32_e32 v104, v0, v1
	s_waitcnt vmcnt(17)
; __device__ __forceinline__ float gelu_tanh(float x) {
;   float u = 0.7978845608028654f * (x + 0.044715f * x * x * x);
;   return 0.5f * x * (1.f + tanhf(u));
; }
	v_cvt_pk_f32_fp8_e32 v[0:1], v100
	v_cvt_pk_f32_fp8_sdwa v[2:3], v100 src0_sel:WORD_1
	v_pk_fma_f32 v[0:1], v[0:1], v[160:161], 0 op_sel_hi:[1,1,0]
	s_nop 0
	v_pk_fma_f32 v[0:1], v[2:3], v[162:163], v[0:1]
	v_cvt_pk_f32_fp8_e32 v[2:3], v101
	v_pk_fma_f32 v[0:1], v[2:3], v[164:165], v[0:1]
	v_cvt_pk_f32_fp8_sdwa v[2:3], v101 src0_sel:WORD_1
	v_pk_fma_f32 v[0:1], v[2:3], v[166:167], v[0:1]
	v_cvt_pk_f32_fp8_e32 v[2:3], v102
	v_pk_fma_f32 v[0:1], v[2:3], v[168:169], v[0:1]
	v_cvt_pk_f32_fp8_sdwa v[2:3], v102 src0_sel:WORD_1
	v_pk_fma_f32 v[0:1], v[2:3], v[170:171], v[0:1]
	v_cvt_pk_f32_fp8_e32 v[2:3], v103
	v_pk_fma_f32 v[0:1], v[2:3], v[172:173], v[0:1]
	v_cvt_pk_f32_fp8_sdwa v[2:3], v103 src0_sel:WORD_1
	v_pk_fma_f32 v[0:1], v[2:3], v[174:175], v[0:1]
	s_nop 0
	v_add_f32_e32 v100, v0, v1
	s_waitcnt vmcnt(16)
	v_cvt_pk_f32_fp8_e32 v[0:1], v96
	v_cvt_pk_f32_fp8_sdwa v[2:3], v96 src0_sel:WORD_1
	v_cndmask_b32_e64 v96, v104, v136, s[6:7]
	v_pk_fma_f32 v[0:1], v[0:1], v[160:161], 0 op_sel_hi:[1,1,0]
	s_nop 0
	v_pk_fma_f32 v[0:1], v[2:3], v[162:163], v[0:1]
	v_cvt_pk_f32_fp8_e32 v[2:3], v97
	v_pk_fma_f32 v[0:1], v[2:3], v[164:165], v[0:1]
	v_cvt_pk_f32_fp8_sdwa v[2:3], v97 src0_sel:WORD_1
	v_cndmask_b32_e64 v97, v100, v132, s[6:7]
	v_pk_fma_f32 v[0:1], v[2:3], v[166:167], v[0:1]
	v_cvt_pk_f32_fp8_e32 v[2:3], v98
	v_pk_fma_f32 v[0:1], v[2:3], v[168:169], v[0:1]
	v_cvt_pk_f32_fp8_sdwa v[2:3], v98 src0_sel:WORD_1
	v_pk_fma_f32 v[0:1], v[2:3], v[170:171], v[0:1]
	v_cvt_pk_f32_fp8_e32 v[2:3], v99
	v_pk_fma_f32 v[0:1], v[2:3], v[172:173], v[0:1]
	v_cvt_pk_f32_fp8_sdwa v[2:3], v99 src0_sel:WORD_1
	v_pk_fma_f32 v[0:1], v[2:3], v[174:175], v[0:1]
	s_nop 0
	v_add_f32_e32 v0, v0, v1
	v_cndmask_b32_e64 v1, v156, v5, s[6:7]
	ds_bpermute_b32 v1, v241, v1
	v_cndmask_b32_e64 v2, v5, v156, s[6:7]
	v_cndmask_b32_e64 v3, v6, v152, s[6:7]
	v_cndmask_b32_e64 v5, v7, v148, s[6:7]
	s_waitcnt lgkmcnt(0)
	v_add_f32_e32 v1, v2, v1
	v_cndmask_b32_e64 v2, v152, v6, s[6:7]
	ds_bpermute_b32 v2, v241, v2
	v_cndmask_b32_e64 v6, v112, v144, s[6:7]
	s_waitcnt lgkmcnt(0)
	v_add_f32_e32 v2, v3, v2
	v_cndmask_b32_e64 v3, v148, v7, s[6:7]
	ds_bpermute_b32 v3, v241, v3
	v_cndmask_b32_e64 v7, v108, v140, s[6:7]
	s_waitcnt lgkmcnt(0)
	v_add_f32_e32 v3, v5, v3
	v_cndmask_b32_e64 v5, v144, v112, s[6:7]
	ds_bpermute_b32 v5, v241, v5
	s_waitcnt lgkmcnt(0)
	v_add_f32_e32 v5, v6, v5
	v_cndmask_b32_e64 v6, v140, v108, s[6:7]
	ds_bpermute_b32 v6, v241, v6
	s_waitcnt lgkmcnt(0)
	v_add_f32_e32 v6, v7, v6
	v_cndmask_b32_e64 v7, v136, v104, s[6:7]
	ds_bpermute_b32 v7, v241, v7
	s_waitcnt lgkmcnt(0)
	v_add_f32_e32 v7, v96, v7
	v_cndmask_b32_e64 v96, v132, v100, s[6:7]
	ds_bpermute_b32 v96, v241, v96
	s_waitcnt lgkmcnt(0)
	v_add_f32_e32 v96, v97, v96
	v_cndmask_b32_e64 v97, v4, v0, s[6:7]
	v_cndmask_b32_e64 v0, v0, v4, s[6:7]
	ds_bpermute_b32 v4, v241, v97
	s_waitcnt lgkmcnt(0)
	v_add_f32_e32 v0, v0, v4
	v_cndmask_b32_e64 v4, v1, v6, s[8:9]
	ds_bpermute_b32 v4, v242, v4
	v_cndmask_b32_e64 v1, v6, v1, s[8:9]
	s_waitcnt lgkmcnt(0)
	v_add_f32_e32 v1, v1, v4
	v_cndmask_b32_e64 v4, v2, v7, s[8:9]
	ds_bpermute_b32 v4, v242, v4
	v_cndmask_b32_e64 v2, v7, v2, s[8:9]
	s_waitcnt lgkmcnt(0)
	v_add_f32_e32 v2, v2, v4
	v_cndmask_b32_e64 v4, v3, v96, s[8:9]
	ds_bpermute_b32 v4, v242, v4
	v_cndmask_b32_e64 v3, v96, v3, s[8:9]
	s_waitcnt lgkmcnt(0)
	v_add_f32_e32 v3, v3, v4
	v_cndmask_b32_e64 v4, v5, v0, s[8:9]
	ds_bpermute_b32 v4, v242, v4
	v_cndmask_b32_e64 v0, v0, v5, s[8:9]
	s_waitcnt lgkmcnt(0)
	v_add_f32_e32 v0, v0, v4
	v_cndmask_b32_e64 v4, v1, v3, s[10:11]
	v_cndmask_b32_e64 v1, v3, v1, s[10:11]
	ds_bpermute_b32 v3, v243, v4
	s_waitcnt lgkmcnt(0)
	v_add_f32_e32 v1, v1, v3
	v_cndmask_b32_e64 v3, v2, v0, s[10:11]
	v_cndmask_b32_e64 v0, v0, v2, s[10:11]
	ds_bpermute_b32 v2, v243, v3
	s_waitcnt lgkmcnt(0)
	v_add_f32_e32 v0, v0, v2
	v_cndmask_b32_e64 v2, v1, v0, s[12:13]
	v_cndmask_b32_e64 v0, v0, v1, s[12:13]
	ds_bpermute_b32 v1, v244, v2
	s_waitcnt lgkmcnt(0)
	v_add_f32_e32 v0, v0, v1
	s_nop 1
	v_add_f32_dpp v96, v0, v0 quad_perm:[2,3,0,1] row_mask:0xf bank_mask:0xf bound_ctrl:1
	s_nop 1
	v_mov_b32_dpp v97, v96 quad_perm:[1,0,3,2] row_mask:0xf bank_mask:0xf bound_ctrl:1
	s_and_saveexec_b64 s[18:19], s[14:15]
	s_cbranch_execz .LBB0_1498
	v_add_f32_e32 v0, v96, v97
	v_mul_f32_e32 v97, 0x3c800000, v0
	ds_read_b32 v96, v237 offset:576
	v_mul_f32_e32 v0, 0x3d372713, v97
	v_mul_f32_e32 v0, v97, v0
	v_fma_f32 v0, v97, v0, v97
	v_mul_f32_e32 v98, 0x3f4c422a, v0
	v_cmp_nlt_f32_e64 s[20:21], |v98|, s40
	s_and_saveexec_b64 s[24:25], s[20:21]
	s_xor_b64 s[20:21], exec, s[24:25]
	s_cbranch_execz .LBB0_1510
	v_add_f32_e64 v0, |v98|, |v98|
	v_mul_f32_e32 v1, 0x3fb8aa3b, v0
	v_rndne_f32_e32 v2, v1
	v_sub_f32_e32 v3, v1, v2
	v_fma_f32 v1, v0, s38, -v1
	v_fmac_f32_e32 v1, 0x32a5705f, v0
	v_add_f32_e32 v1, v3, v1
	v_cvt_i32_f32_e32 v2, v2
	v_exp_f32_e32 v1, v1
	v_cmp_ngt_f32_e32 vcc, s41, v0
	v_ldexp_f32 v1, v1, v2
	s_nop 0
	v_cndmask_b32_e32 v1, 0, v1, vcc
	v_cmp_nlt_f32_e32 vcc, s42, v0
	s_nop 1
	v_cndmask_b32_e32 v0, v186, v1, vcc
	v_add_f32_e32 v0, 1.0, v0
	v_rcp_f32_e32 v0, v0
	s_nop 0
	v_fma_f32 v99, v0, -2.0, 1.0

; #define P5_LOAD(A, TAB, j0)                                                                \
;   _Pragma("unroll") for (int q = 0; q < 16; q++) {                                         \
;     A[q] = ((const uint4*)((TAB) + (size_t)widx[(j0) + q] * 1024))[lane];                  \
;   }
; __device__ __forceinline__ void phase5(const Params& p, char* smem, const bool store_x = true) {
;     ...
;     float2v o2[8];
; #pragma unroll
;     for (int i = 0; i < 8; i++) o2[i] = float2v{0.f, 0.f};
; #pragma unroll 1
;     for (int j0 = 0; j0 < 128; j0 += 32) {
;       P5_LOAD(A1, EV, j0 + 16)
;       P5_COMPUTE_V(A0, j0)
;       if (j0 + 32 < 128) { P5_LOAD(A0, EV, j0 + 32) }
;       P5_COMPUTE_V(A1, j0 + 16)
;     }
.LBB0_1512:
	v_mbcnt_lo_u32_b32 v0, -1, 0
	v_mbcnt_hi_u32_b32 v0, -1, v0
	v_lshl_add_u32 v1, v0, 2, v176
	ds_read2st64_b32 v[2:3], v1 offset1:1
	ds_read2st64_b32 v[4:5], v1 offset0:4 offset1:5
	s_add_u32 s98, s80, 0x3bb5000
	s_addc_u32 s99, s81, 0
	v_lshl_add_u32 v6, v0, 3, v200
	v_lshrrev_b32_e32 v7, 8, v200
	v_add_u32_e32 v7, 0x1100000, v7
	v_mov_b32_e32 v20, 0
	s_waitcnt lgkmcnt(0)
	v_lshlrev_b32_e32 v16, 7, v2
	v_mov_b32_e32 v17, v4
	v_lshlrev_b32_e32 v18, 7, v3
	v_mov_b32_e32 v19, v5
	global_store_dwordx2 v6, v[16:17], s[98:99]
	global_store_dwordx2 v6, v[18:19], s[98:99] offset:512
	s_mov_b64 exec, 1
	global_store_dword v7, v20, s[98:99]
	s_mov_b64 exec, -1
	v_mov_b32_e32 v105, 0x358637bd
	v_accvgpr_read_b32 v96, a12
	v_accvgpr_read_b32 v97, a13
	v_accvgpr_read_b32 v98, a14
	v_accvgpr_read_b32 v99, a15
	v_accvgpr_read_b32 v100, a8
	v_accvgpr_read_b32 v101, a9
	v_accvgpr_read_b32 v102, a10
	v_accvgpr_read_b32 v103, a11
	v_mov_b32_e32 v104, v240
	s_and_b64 vcc, exec, s[34:35]
	s_cbranch_vccnz .Lp5a_done
	s_branch .LBB0_1482

; __device__ __forceinline__ void xcd_barrier(const XcdBarrier& b) {
;     asm volatile("s_waitcnt vmcnt(0)" ::: "memory");
;     __syncthreads();
;     if (threadIdx.x == 0) {
.Lp5_skip_ev:
	s_waitcnt vmcnt(0) lgkmcnt(0)
	s_branch .Lp5_ev_skipped
.Lp5a_done:
.Lpb1_1523:
	s_waitcnt vmcnt(0)
	s_barrier
	s_and_saveexec_b64 s[0:1], s[72:73]
	s_cbranch_execz .Lpb1_1575

; __device__ __forceinline__ void xcd_barrier(const XcdBarrier& b) {
;     ...
;         __builtin_amdgcn_s_waitcnt(0);
;         unsigned nloc = b.st[0], nx = b.st[1];
;         if (nloc == 0u) { xcd_barrier_complete(bar, b.x, nloc, nx); b.st[0] = nloc; b.st[1] = nx; }
	v_mov_b32_e32 v0, 0x23800
	s_waitcnt vmcnt(0) expcnt(0) lgkmcnt(0)
	ds_read_b32 v2, v0
	v_mov_b32_e32 v0, 0x23804
	ds_read_b32 v0, v0
	s_waitcnt lgkmcnt(1)
	v_cmp_ne_u32_e32 vcc, 0, v2
	s_cbranch_vccnz .Lpb1_1539

; __device__ __forceinline__ unsigned xb_ld(unsigned* p)              { return __hip_atomic_load(p, __ATOMIC_RELAXED, __HIP_MEMORY_SCOPE_AGENT); }
; __device__ __forceinline__ void xcd_barrier_complete(unsigned* bar, unsigned x, unsigned& nloc, unsigned& nx) {
;     const unsigned G = gridDim.x * gridDim.y * gridDim.z;
;     unsigned sum, cnt, mine, sp = 0u;
;     for (;;) {
;         sum = 0u; cnt = 0u; mine = 0u;
; #pragma unroll
;         for (unsigned j = 0; j < 16; ++j) { const unsigned c = xb_ld(&bar[XB_XCNT(j)]); sum += c; cnt += (c > 0u) ? 1u : 0u; mine = (j == x) ? c : mine; }
	v_readlane_b32 s4, v254, 0
	s_mul_i32 s33, s83, s4
	s_add_u32 s4, s80, 0x12f35200
	s_addc_u32 s5, s81, 0
	s_add_u32 s6, s80, 0x12f35400
	s_addc_u32 s7, s81, 0
	s_add_u32 s8, s80, 0x12f35500
	s_addc_u32 s9, s81, 0
	s_add_u32 s10, s80, 0x12f35600
	s_addc_u32 s11, s81, 0
	s_add_u32 s12, s80, 0x12f35700
	s_addc_u32 s13, s81, 0
	s_add_u32 s14, s80, 0x12f35800
	s_addc_u32 s15, s81, 0
	s_add_u32 s16, s80, 0x12f35900
	s_addc_u32 s17, s81, 0
	s_add_u32 s18, s80, 0x12f35a00
	s_addc_u32 s19, s81, 0
	s_add_u32 s20, s80, 0x12f35b00
	s_addc_u32 s21, s81, 0
	s_add_u32 s22, s80, 0x12f35c00
	s_addc_u32 s23, s81, 0
	s_add_u32 s24, s80, 0x12f35d00
	s_addc_u32 s25, s81, 0
	s_add_u32 s26, s80, 0x12f35e00
	s_addc_u32 s27, s81, 0
	s_add_u32 s28, s80, 0x12f35f00
	s_addc_u32 s29, s81, 0
	s_add_u32 s34, s80, 0x12f36000
	s_addc_u32 s35, s81, 0
	s_add_u32 s36, s80, 0x12f36100
	s_addc_u32 s37, s81, 0
	s_add_u32 s38, s80, 0x12f36200
	s_addc_u32 s39, s81, 0
	s_add_u32 s40, s80, 0x12f36300
	s_mul_i32 s33, s33, s82
	s_addc_u32 s41, s81, 0
	s_mov_b32 s48, 1
	v_mov_b32_e32 v16, 0
	s_branch .Lpb1_1527

; __device__ __forceinline__ unsigned xb_ld(unsigned* p)              { return __hip_atomic_load(p, __ATOMIC_RELAXED, __HIP_MEMORY_SCOPE_AGENT); }
; __device__ __forceinline__ void xcd_barrier_complete(unsigned* bar, unsigned x, unsigned& nloc, unsigned& nx) {
;     ...
;     for (;;) {
;         sum = 0u; cnt = 0u; mine = 0u;
; #pragma unroll
;         for (unsigned j = 0; j < 16; ++j) { const unsigned c = xb_ld(&bar[XB_XCNT(j)]); sum += c; cnt += (c > 0u) ? 1u : 0u; mine = (j == x) ? c : mine; }
;         if (sum == G) break;
.Lpb1_1527:
	global_load_dword v15, v16, s[6:7] sc1
	s_waitcnt lgkmcnt(0)
	global_load_dword v0, v16, s[8:9] sc1
	global_load_dword v1, v16, s[10:11] sc1
	global_load_dword v2, v16, s[12:13] sc1
	global_load_dword v3, v16, s[14:15] sc1
	global_load_dword v4, v16, s[16:17] sc1
	global_load_dword v5, v16, s[18:19] sc1
	global_load_dword v6, v16, s[20:21] sc1
	global_load_dword v7, v16, s[22:23] sc1
	global_load_dword v8, v16, s[24:25] sc1
	global_load_dword v9, v16, s[26:27] sc1
	global_load_dword v10, v16, s[28:29] sc1
	global_load_dword v11, v16, s[34:35] sc1
	global_load_dword v12, v16, s[36:37] sc1
	global_load_dword v13, v16, s[38:39] sc1
	global_load_dword v14, v16, s[40:41] sc1
	s_mov_b64 s[42:43], -1
	s_mov_b64 s[44:45], -1
	s_waitcnt vmcnt(14)
	v_add_u32_e32 v17, v0, v15
	s_waitcnt vmcnt(13)
	v_add_u32_e32 v17, v17, v1
	s_waitcnt vmcnt(12)
	v_add_u32_e32 v17, v17, v2
	s_waitcnt vmcnt(11)
	v_add_u32_e32 v17, v17, v3
	s_waitcnt vmcnt(10)
	v_add_u32_e32 v17, v17, v4
	s_waitcnt vmcnt(9)
	v_add_u32_e32 v17, v17, v5
	s_waitcnt vmcnt(8)
	v_add_u32_e32 v17, v17, v6
	s_waitcnt vmcnt(7)
	v_add_u32_e32 v17, v17, v7
	s_waitcnt vmcnt(6)
	v_add_u32_e32 v17, v17, v8
	s_waitcnt vmcnt(5)
	v_add_u32_e32 v17, v17, v9
	s_waitcnt vmcnt(4)
	v_add_u32_e32 v17, v17, v10
	s_waitcnt vmcnt(3)
	v_add_u32_e32 v17, v17, v11
	s_waitcnt vmcnt(2)
	v_add_u32_e32 v17, v17, v12
	s_waitcnt vmcnt(1)
	v_add_u32_e32 v17, v17, v13
	s_waitcnt vmcnt(0)
	v_add_u32_e32 v17, v17, v14
	v_cmp_eq_u32_e32 vcc, s33, v17
	s_cbranch_vccnz .Lpb1_1526

; __device__ __forceinline__ unsigned xb_ld(unsigned* p)              { return __hip_atomic_load(p, __ATOMIC_RELAXED, __HIP_MEMORY_SCOPE_AGENT); }
; __device__ __forceinline__ void xcd_barrier_complete(unsigned* bar, unsigned x, unsigned& nloc, unsigned& nx) {
;     ...
;         __builtin_amdgcn_s_sleep(1);
;         if ((++sp & 255u) == 0u) { if (xb_ld(&bar[XB_TMO])) break; if (sp > XB_SPIN_CAP) { atomicAdd(&bar[XB_TMO], 1u); break; } }
	s_and_b32 s42, s48, 0xff
	s_cmp_eq_u32 s42, 0
	s_mov_b64 s[42:43], -1
	s_mov_b64 s[46:47], -1
	s_sleep 1
	s_cbranch_scc0 .Lpb1_1531

; __device__ __forceinline__ unsigned xb_ld(unsigned* p)              { return __hip_atomic_load(p, __ATOMIC_RELAXED, __HIP_MEMORY_SCOPE_AGENT); }
; __device__ __forceinline__ void xcd_barrier_complete(unsigned* bar, unsigned x, unsigned& nloc, unsigned& nx) {
;     ...
;         if ((++sp & 255u) == 0u) { if (xb_ld(&bar[XB_TMO])) break; if (sp > XB_SPIN_CAP) { atomicAdd(&bar[XB_TMO], 1u); break; } }
	global_load_dword v17, v16, s[4:5] sc1
	s_waitcnt vmcnt(0)
	v_cmp_eq_u32_e32 vcc, 0, v17
	s_cbranch_vccnz .Lpb1_1533

; __device__ __forceinline__ unsigned xb_ld(unsigned* p)              { return __hip_atomic_load(p, __ATOMIC_RELAXED, __HIP_MEMORY_SCOPE_AGENT); }
; __device__ __forceinline__ void xcd_barrier_complete(unsigned* bar, unsigned x, unsigned& nloc, unsigned& nx) {
;     ...
;         if ((++sp & 255u) == 0u) { if (xb_ld(&bar[XB_TMO])) break; if (sp > XB_SPIN_CAP) { atomicAdd(&bar[XB_TMO], 1u); break; } }
	s_mov_b64 s[46:47], 0

; __device__ __forceinline__ unsigned xb_ld(unsigned* p)              { return __hip_atomic_load(p, __ATOMIC_RELAXED, __HIP_MEMORY_SCOPE_AGENT); }
; __device__ __forceinline__ void xcd_barrier_complete(unsigned* bar, unsigned x, unsigned& nloc, unsigned& nx) {
;     ...
;     for (;;) {
;         sum = 0u; cnt = 0u; mine = 0u;
; #pragma unroll
;         for (unsigned j = 0; j < 16; ++j) { const unsigned c = xb_ld(&bar[XB_XCNT(j)]); sum += c; cnt += (c > 0u) ? 1u : 0u; mine = (j == x) ? c : mine; }
;         if (sum == G) break;
;         __builtin_amdgcn_s_sleep(1);
;         if ((++sp & 255u) == 0u) { if (xb_ld(&bar[XB_TMO])) break; if (sp > XB_SPIN_CAP) { atomicAdd(&bar[XB_TMO], 1u); break; } }
.Lpb1_1534:
	s_andn2_b64 vcc, exec, s[42:43]
	s_cbranch_vccz .Lpb1_1538

; __device__ __forceinline__ unsigned xb_ld(unsigned* p)              { return __hip_atomic_load(p, __ATOMIC_RELAXED, __HIP_MEMORY_SCOPE_AGENT); }
; __device__ __forceinline__ void xcd_barrier_complete(unsigned* bar, unsigned x, unsigned& nloc, unsigned& nx) {
;     ...
;         if ((++sp & 255u) == 0u) { if (xb_ld(&bar[XB_TMO])) break; if (sp > XB_SPIN_CAP) { atomicAdd(&bar[XB_TMO], 1u); break; } }
	s_mov_b64 s[8:9], exec
	v_mbcnt_lo_u32_b32 v16, s8, 0
	v_mbcnt_hi_u32_b32 v16, s9, v16
	v_cmp_eq_u32_e32 vcc, 0, v16
	s_and_saveexec_b64 s[6:7], vcc
	s_cbranch_execz .Lpb1_1537

; __device__ __forceinline__ unsigned xb_ld(unsigned* p)              { return __hip_atomic_load(p, __ATOMIC_RELAXED, __HIP_MEMORY_SCOPE_AGENT); }
; __device__ __forceinline__ void xcd_barrier_complete(unsigned* bar, unsigned x, unsigned& nloc, unsigned& nx) {
;     ...
;         if ((++sp & 255u) == 0u) { if (xb_ld(&bar[XB_TMO])) break; if (sp > XB_SPIN_CAP) { atomicAdd(&bar[XB_TMO], 1u); break; } }
	s_bcnt1_i32_b64 s8, s[8:9]
	v_mov_b32_e32 v16, 0
	v_mov_b32_e32 v17, s8
	global_atomic_add v16, v17, s[4:5]

; __device__ __forceinline__ unsigned xb_add(unsigned* p, unsigned v) { return __hip_atomic_fetch_add(p, v, __ATOMIC_RELAXED, __HIP_MEMORY_SCOPE_AGENT); }
; __device__ __forceinline__ void xcd_barrier(const XcdBarrier& b) {
;     ...
;         const unsigned old = xb_add(&bar[XB_XSUB(b.x)], 1u);
.Lpb1_1539:
	s_mov_b64 s[6:7], exec
	s_lshl_b32 s4, s74, 8
	v_mbcnt_lo_u32_b32 v1, s6, 0
	s_add_u32 s4, s88, s4
	v_mbcnt_hi_u32_b32 v1, s7, v1
	s_addc_u32 s5, s89, 0
	v_cmp_eq_u32_e32 vcc, 0, v1

; __device__ __forceinline__ unsigned xb_add(unsigned* p, unsigned v) { return __hip_atomic_fetch_add(p, v, __ATOMIC_RELAXED, __HIP_MEMORY_SCOPE_AGENT); }
; __device__ __forceinline__ void xcd_barrier(const XcdBarrier& b) {
;     ...
;         const unsigned old = xb_add(&bar[XB_XSUB(b.x)], 1u);
	s_and_saveexec_b64 s[8:9], vcc
	s_cbranch_execz .Lpb1_1541

; __device__ __forceinline__ unsigned xb_add(unsigned* p, unsigned v) { return __hip_atomic_fetch_add(p, v, __ATOMIC_RELAXED, __HIP_MEMORY_SCOPE_AGENT); }
; __device__ __forceinline__ void xcd_barrier(const XcdBarrier& b) {
;     ...
;         const unsigned old = xb_add(&bar[XB_XSUB(b.x)], 1u);
;         const unsigned gen = old / nloc;
;         if (old + 1u == (gen + 1u) * nloc) {
	s_bcnt1_i32_b64 s6, s[6:7]
	v_mov_b32_e32 v3, 0x1000
	v_mov_b32_e32 v4, s6
	global_atomic_add v3, v3, v4, s[4:5] offset:1024 sc0
.Lpb1_1541:
	s_or_b64 exec, exec, s[8:9]
	v_cvt_f32_u32_e32 v4, v2
	s_waitcnt vmcnt(0)
	v_readfirstlane_b32 s6, v3
	v_sub_u32_e32 v3, 0, v2
	v_rcp_iflag_f32_e32 v4, v4
	v_add_u32_e32 v5, s6, v1
	v_mul_f32_e32 v4, 0x4f7ffffe, v4
	v_cvt_u32_f32_e32 v4, v4
	v_mul_lo_u32 v1, v3, v4
	v_mul_hi_u32 v1, v4, v1
	v_add_u32_e32 v1, v4, v1
	v_mul_hi_u32 v1, v5, v1
	v_mul_lo_u32 v3, v1, v2
	v_sub_u32_e32 v3, v5, v3
	v_add_u32_e32 v4, 1, v1
	v_cmp_ge_u32_e32 vcc, v3, v2
	s_nop 1
	v_cndmask_b32_e32 v1, v1, v4, vcc
	v_sub_u32_e32 v4, v3, v2
	v_cndmask_b32_e32 v3, v3, v4, vcc
	v_add_u32_e32 v4, 1, v1
	v_cmp_ge_u32_e32 vcc, v3, v2
	v_add_u32_e32 v3, 1, v5
	s_nop 0
	v_cndmask_b32_e32 v1, v1, v4, vcc
	v_mul_lo_u32 v4, v2, v1
	v_add_u32_e32 v2, v4, v2
	v_cmp_ne_u32_e32 vcc, v3, v2
	s_and_saveexec_b64 s[6:7], vcc
	s_xor_b64 s[6:7], exec, s[6:7]
	s_cbranch_execz .Lpb1_1555

; __device__ __forceinline__ unsigned xb_ld(unsigned* p)              { return __hip_atomic_load(p, __ATOMIC_RELAXED, __HIP_MEMORY_SCOPE_AGENT); }
; #define XB_SPIN(cond, bar) do { unsigned _sp = 0; while (cond) { __builtin_amdgcn_s_sleep(1); \
;     if ((++_sp & 255u) == 0u) { if (xb_ld(&(bar)[XB_TMO])) break; if (_sp > XB_SPIN_CAP) { atomicAdd(&(bar)[XB_TMO], 1u); break; } } } } while (0)
; __device__ __forceinline__ void xcd_barrier(const XcdBarrier& b) {
;     ...
;             XB_SPIN(xb_ld(&bar[XB_XGEN(b.x)]) == gen, bar);
	s_waitcnt lgkmcnt(0)
	v_mov_b32_e32 v0, 0x2000
	global_load_dword v0, v0, s[4:5] offset:1024 sc1
	s_add_u32 s12, s4, 0x2400
	s_addc_u32 s13, s5, 0
	s_waitcnt vmcnt(0)
	v_cmp_eq_u32_e32 vcc, v0, v1
	s_and_saveexec_b64 s[8:9], vcc
	s_cbranch_execz .Lpb1_1554

	s_add_u32 s10, s80, 0x12f35200
	s_addc_u32 s11, s81, 0
	s_mov_b32 s24, 1
	s_mov_b64 s[14:15], 0
	v_mov_b32_e32 v0, 0

	s_branch .Lpb1_1545

.Lpb1_1545:
	s_and_b32 s20, s24, 0xff
	s_mov_b64 s[18:19], -1
	s_cmp_lg_u32 s20, 0
	s_mov_b64 s[22:23], -1
	s_sleep 1

	s_cbranch_scc1 .Lpb1_1548

	global_load_dword v2, v0, s[10:11] sc1
	s_waitcnt vmcnt(0)
	v_cmp_eq_u32_e32 vcc, 0, v2
	s_cbranch_vccnz .Lpb1_1550

	s_mov_b64 s[22:23], 0
	s_mov_b64 s[20:21], -1

.Lpb1_1551:
	s_or_b64 exec, exec, s[14:15]
	s_xor_b64 s[12:13], s[16:17], -1
	s_and_saveexec_b64 s[14:15], s[12:13]
	s_xor_b64 s[14:15], exec, s[14:15]
	s_cbranch_execz .Lpb1_1554

	s_mov_b64 s[12:13], exec
	v_mbcnt_lo_u32_b32 v0, s12, 0
	v_mbcnt_hi_u32_b32 v0, s13, v0
	v_cmp_eq_u32_e32 vcc, 0, v0
	s_and_b64 s[14:15], exec, vcc
	s_mov_b64 exec, s[14:15]
	s_cbranch_execz .Lpb1_1554

; __device__ __forceinline__ void xcd_barrier(const XcdBarrier& b) {
;     ...
;             __builtin_amdgcn_fence(__ATOMIC_ACQUIRE, "agent");
;             asm volatile("s_waitcnt vmcnt(0)" ::: "memory");
	s_bcnt1_i32_b64 s12, s[12:13]
	v_mov_b32_e32 v0, 0
	v_mov_b32_e32 v1, s12
	global_atomic_add v0, v1, s[10:11]
.Lpb1_1554:
	s_or_b64 exec, exec, s[8:9]
	s_waitcnt vmcnt(0)
	buffer_inv sc1
	s_waitcnt vmcnt(0)

; __device__ __forceinline__ void xcd_barrier(const XcdBarrier& b) {
;     ...
;         if (old + 1u == (gen + 1u) * nloc) {
.Lpb1_1555:
	s_andn2_saveexec_b64 s[6:7], s[6:7]
	s_cbranch_execz .Lpb1_1575

; __device__ __forceinline__ unsigned xb_add(unsigned* p, unsigned v) { return __hip_atomic_fetch_add(p, v, __ATOMIC_RELAXED, __HIP_MEMORY_SCOPE_AGENT); }
; __device__ __forceinline__ void xcd_barrier(const XcdBarrier& b) {
;     ...
;             __builtin_amdgcn_fence(__ATOMIC_RELEASE, "agent");
;             asm volatile("s_waitcnt vmcnt(0)" ::: "memory");
;             const unsigned og = xb_add(&bar[XB_TOP], 1u);
	s_mov_b64 s[6:7], exec
	buffer_wbl2 sc1
	s_waitcnt lgkmcnt(0)
	s_waitcnt vmcnt(0)
	v_mbcnt_lo_u32_b32 v1, s6, 0
	v_mbcnt_hi_u32_b32 v1, s7, v1
	v_cmp_eq_u32_e32 vcc, 0, v1

; __device__ __forceinline__ unsigned xb_add(unsigned* p, unsigned v) { return __hip_atomic_fetch_add(p, v, __ATOMIC_RELAXED, __HIP_MEMORY_SCOPE_AGENT); }
; __device__ __forceinline__ void xcd_barrier(const XcdBarrier& b) {
;     ...
;             const unsigned og = xb_add(&bar[XB_TOP], 1u);
	s_and_saveexec_b64 s[8:9], vcc
	s_cbranch_execz .Lpb1_1558

; __device__ __forceinline__ unsigned xb_ld(unsigned* p)              { return __hip_atomic_load(p, __ATOMIC_RELAXED, __HIP_MEMORY_SCOPE_AGENT); }
; __device__ __forceinline__ unsigned xb_add(unsigned* p, unsigned v) { return __hip_atomic_fetch_add(p, v, __ATOMIC_RELAXED, __HIP_MEMORY_SCOPE_AGENT); }
; #define XB_SPIN(cond, bar) do { unsigned _sp = 0; while (cond) { __builtin_amdgcn_s_sleep(1); \
;     if ((++_sp & 255u) == 0u) { if (xb_ld(&(bar)[XB_TMO])) break; if (_sp > XB_SPIN_CAP) { atomicAdd(&(bar)[XB_TMO], 1u); break; } } } } while (0)
; __device__ __forceinline__ void xcd_barrier(const XcdBarrier& b) {
;     ...
;             const unsigned og = xb_add(&bar[XB_TOP], 1u);
;             const unsigned tg = og / nx;
;             if (og + 1u == (tg + 1u) * nx) xb_add(&bar[XB_TOPGEN], 1u);
;             else XB_SPIN(xb_ld(&bar[XB_TOPGEN]) == tg, bar);
	s_bcnt1_i32_b64 s6, s[6:7]
	v_mov_b32_e32 v2, 0x12f38000
	v_mov_b32_e32 v3, s6
	global_atomic_add v2, v2, v3, s[80:81] offset:1024 sc0
.Lpb1_1558:
	s_or_b64 exec, exec, s[8:9]
	v_cvt_f32_u32_e32 v3, v0
	s_waitcnt vmcnt(0)
	v_readfirstlane_b32 s6, v2
	s_add_u32 s8, s80, 0x12f38500
	s_addc_u32 s9, s81, 0
	v_rcp_iflag_f32_e32 v3, v3
	v_add_u32_e32 v1, s6, v1
	v_add_u32_e32 v4, 1, v1
	s_mov_b64 s[10:11], -1
	v_mul_f32_e32 v2, 0x4f7ffffe, v3
	v_cvt_u32_f32_e32 v2, v2
	v_sub_u32_e32 v3, 0, v0
	v_mul_lo_u32 v3, v3, v2
	v_mul_hi_u32 v3, v2, v3
	v_add_u32_e32 v2, v2, v3
	v_mul_hi_u32 v2, v1, v2
	v_mul_lo_u32 v3, v2, v0
	v_sub_u32_e32 v1, v1, v3
	v_add_u32_e32 v5, 1, v2
	v_cmp_ge_u32_e32 vcc, v1, v0
	v_sub_u32_e32 v3, v1, v0
	s_nop 0
	v_cndmask_b32_e32 v2, v2, v5, vcc
	v_cndmask_b32_e32 v1, v1, v3, vcc
	v_add_u32_e32 v3, 1, v2
	v_cmp_ge_u32_e32 vcc, v1, v0
	s_nop 1
	v_cndmask_b32_e32 v2, v2, v3, vcc
	v_mul_lo_u32 v1, v0, v2
	v_add_u32_e32 v0, v1, v0
	v_cmp_ne_u32_e32 vcc, v4, v0
	v_mov_b64_e32 v[0:1], s[8:9]
	s_and_saveexec_b64 s[6:7], vcc
	s_cbranch_execz .Lpb1_1570

; __device__ __forceinline__ unsigned xb_ld(unsigned* p)              { return __hip_atomic_load(p, __ATOMIC_RELAXED, __HIP_MEMORY_SCOPE_AGENT); }
; #define XB_SPIN(cond, bar) do { unsigned _sp = 0; while (cond) { __builtin_amdgcn_s_sleep(1); \
;     if ((++_sp & 255u) == 0u) { if (xb_ld(&(bar)[XB_TMO])) break; if (_sp > XB_SPIN_CAP) { atomicAdd(&(bar)[XB_TMO], 1u); break; } } } } while (0)
; __device__ __forceinline__ void xcd_barrier(const XcdBarrier& b) {
;     ...
;             else XB_SPIN(xb_ld(&bar[XB_TOPGEN]) == tg, bar);
	v_mov_b32_e32 v0, 0
	global_load_dword v1, v0, s[8:9] sc1
	s_mov_b64 s[14:15], 0

; __device__ __forceinline__ unsigned xb_ld(unsigned* p)              { return __hip_atomic_load(p, __ATOMIC_RELAXED, __HIP_MEMORY_SCOPE_AGENT); }
; #define XB_SPIN(cond, bar) do { unsigned _sp = 0; while (cond) { __builtin_amdgcn_s_sleep(1); \
;     if ((++_sp & 255u) == 0u) { if (xb_ld(&(bar)[XB_TMO])) break; if (_sp > XB_SPIN_CAP) { atomicAdd(&(bar)[XB_TMO], 1u); break; } } } } while (0)
; __device__ __forceinline__ void xcd_barrier(const XcdBarrier& b) {
;     ...
;             else XB_SPIN(xb_ld(&bar[XB_TOPGEN]) == tg, bar);
	s_waitcnt vmcnt(0)
	v_cmp_eq_u32_e32 vcc, v1, v2
	s_and_saveexec_b64 s[12:13], vcc
	s_cbranch_execz .Lpb1_1569

	s_add_u32 s10, s80, 0x12f35200
	s_addc_u32 s11, s81, 0
	s_mov_b32 s24, 1

	s_branch .Lpb1_1562

.Lpb1_1562:
	s_and_b32 s18, s24, 0xff
	s_cmp_lg_u32 s18, 0
	s_mov_b64 s[20:21], -1
	s_sleep 1

	s_cbranch_scc1 .Lpb1_1565

	global_load_dword v1, v0, s[10:11] sc1
	s_waitcnt vmcnt(0)
	v_cmp_eq_u32_e32 vcc, 0, v1
	s_cbranch_vccnz .Lpb1_1567

	s_mov_b64 s[20:21], 0
	s_mov_b64 s[18:19], -1

; __device__ __forceinline__ unsigned xb_ld(unsigned* p)              { return __hip_atomic_load(p, __ATOMIC_RELAXED, __HIP_MEMORY_SCOPE_AGENT); }
; __device__ __forceinline__ unsigned xb_add(unsigned* p, unsigned v) { return __hip_atomic_fetch_add(p, v, __ATOMIC_RELAXED, __HIP_MEMORY_SCOPE_AGENT); }
; #define XB_SPIN(cond, bar) do { unsigned _sp = 0; while (cond) { __builtin_amdgcn_s_sleep(1); \
;     if ((++_sp & 255u) == 0u) { if (xb_ld(&(bar)[XB_TMO])) break; if (_sp > XB_SPIN_CAP) { atomicAdd(&(bar)[XB_TMO], 1u); break; } } } } while (0)
; __device__ __forceinline__ void xcd_barrier(const XcdBarrier& b) {
;     ...
;             if (og + 1u == (tg + 1u) * nx) xb_add(&bar[XB_TOPGEN], 1u);
;             else XB_SPIN(xb_ld(&bar[XB_TOPGEN]) == tg, bar);
;             __builtin_amdgcn_fence(__ATOMIC_ACQUIRE, "agent");
;             xb_add(&bar[XB_XGEN(b.x)], 1u);
.Lpb1_1570:
	s_or_b64 exec, exec, s[6:7]
	s_and_saveexec_b64 s[6:7], s[10:11]
	s_cbranch_execz .Lpb1_1572

; __device__ __forceinline__ unsigned xb_ld(unsigned* p)              { return __hip_atomic_load(p, __ATOMIC_RELAXED, __HIP_MEMORY_SCOPE_AGENT); }
; __device__ __forceinline__ unsigned xb_add(unsigned* p, unsigned v) { return __hip_atomic_fetch_add(p, v, __ATOMIC_RELAXED, __HIP_MEMORY_SCOPE_AGENT); }
; #define XB_SPIN(cond, bar) do { unsigned _sp = 0; while (cond) { __builtin_amdgcn_s_sleep(1); \
;     if ((++_sp & 255u) == 0u) { if (xb_ld(&(bar)[XB_TMO])) break; if (_sp > XB_SPIN_CAP) { atomicAdd(&(bar)[XB_TMO], 1u); break; } } } } while (0)
; __device__ __forceinline__ void xcd_barrier(const XcdBarrier& b) {
;     ...
;             if (og + 1u == (tg + 1u) * nx) xb_add(&bar[XB_TOPGEN], 1u);
;             else XB_SPIN(xb_ld(&bar[XB_TOPGEN]) == tg, bar);
;             __builtin_amdgcn_fence(__ATOMIC_ACQUIRE, "agent");
;             xb_add(&bar[XB_XGEN(b.x)], 1u);
;             asm volatile("s_waitcnt vmcnt(0)" ::: "memory");
	v_mov_b32_e32 v2, 1
	global_atomic_add v[0:1], v2, off
.Lpb1_1572:
	s_or_b64 exec, exec, s[6:7]
	s_mov_b64 s[6:7], exec
	v_mbcnt_lo_u32_b32 v0, s6, 0
	v_mbcnt_hi_u32_b32 v0, s7, v0
	v_cmp_eq_u32_e32 vcc, 0, v0
	s_waitcnt vmcnt(0)
	buffer_inv sc1
	s_and_saveexec_b64 s[8:9], vcc
	s_cbranch_execz .Lpb1_1574

; #define P5_LOAD(A, TAB, j0)                                                                \
;   _Pragma("unroll") for (int q = 0; q < 16; q++) {                                         \
;     A[q] = ((const uint4*)((TAB) + (size_t)widx[(j0) + q] * 1024))[lane];                  \
;   }
; __device__ __forceinline__ void phase5(const Params& p, char* smem, const bool store_x = true) {
;     ...
; #pragma unroll 1
;     for (int j0 = 0; j0 < 128; j0 += 32) {
;       P5_LOAD(A1, EV, j0 + 16)
;       P5_COMPUTE_V(A0, j0)
;       if (j0 + 32 < 128) { P5_LOAD(A0, EV, j0 + 32) }
;       P5_COMPUTE_V(A1, j0 + 16)
;     }
	s_bcnt1_i32_b64 s6, s[6:7]
	v_mov_b32_e32 v0, 0x2000
	v_mov_b32_e32 v1, s6
	global_atomic_add v0, v1, s[4:5] offset:1024
.Lpb1_1574:
	s_or_b64 exec, exec, s[8:9]
	s_waitcnt vmcnt(0)
.Lpb1_1575:
	s_or_b64 exec, exec, s[0:1]
	s_waitcnt lgkmcnt(0)
	s_barrier
.Lp5v_start:
	v_mbcnt_lo_u32_b32 v0, -1, 0
	v_mbcnt_hi_u32_b32 v0, -1, v0
	v_accvgpr_read_b32 v4, a129
	s_and_b32 s0, s96, 7
	s_lshr_b32 s1, s96, 3
	v_and_b32_e32 v1, 7, v0
	v_lshrrev_b32_e32 v2, 3, v0
	v_lshlrev_b32_e32 v3, 1, v2
	v_lshl_add_u32 v3, v1, 4, v3
	v_lshlrev_b32_e32 v3, 2, v3
	v_lshlrev_b32_e32 v1, 4, v1
	v_lshlrev_b32_e32 v2, 7, v2
	v_readfirstlane_b32 s8, v4
	s_lshl_b32 s10, s1, 2
	s_add_u32 s8, s8, s10
	s_lshr_b32 s9, s82, 1
	s_lshl_b32 s10, s0, 21
	s_add_u32 s2, s80, 0xbf35000
	s_addc_u32 s3, s81, 0
	s_add_u32 s2, s2, s10
	s_addc_u32 s3, s3, 0
	s_add_u32 s4, s80, 0x3bb5000
	s_addc_u32 s5, s81, 0
	s_lshl_b32 s10, s0, 9
	s_add_u32 s6, s78, s10
	s_addc_u32 s7, s79, 0
	s_movk_i32 s13, 0x41ff
	s_mov_b32 s14, 0xff00ff00
	s_mov_b32 s15, 0xff00ff00
	s_mul_i32 s20, s9, 1
	s_mul_i32 s21, s9, 2
	s_mul_i32 s22, s9, 3
	s_mul_i32 s23, s9, 4
	s_mul_i32 s24, s9, 5
	s_mul_i32 s25, s9, 6
	s_min_u32 s10, s8, s13
	s_lshl_b32 s11, s10, 10
	v_add_u32_e32 v5, s11, v2
	global_load_dwordx4 a[0:3], v5, s[4:5] offset:0
	global_load_dwordx4 a[4:7], v5, s[4:5] offset:16
	global_load_dwordx4 a[8:11], v5, s[4:5] offset:32
	global_load_dwordx4 a[12:15], v5, s[4:5] offset:48
	global_load_dwordx4 a[16:19], v5, s[4:5] offset:64
	global_load_dwordx4 a[20:23], v5, s[4:5] offset:80
	global_load_dwordx4 a[24:27], v5, s[4:5] offset:96
	global_load_dwordx4 a[28:31], v5, s[4:5] offset:112
	s_lshl_b32 s11, s10, 12
	v_add_u32_e32 v6, s11, v3
	global_load_dwordx2 a[68:69], v6, s[6:7]
	s_add_u32 s10, s8, s20
	s_min_u32 s10, s10, s13
	s_lshl_b32 s11, s10, 10
	v_add_u32_e32 v5, s11, v2
	global_load_dwordx4 a[32:35], v5, s[4:5] offset:0
	global_load_dwordx4 a[36:39], v5, s[4:5] offset:16
	global_load_dwordx4 a[40:43], v5, s[4:5] offset:32
	global_load_dwordx4 a[44:47], v5, s[4:5] offset:48
	global_load_dwordx4 a[48:51], v5, s[4:5] offset:64
	global_load_dwordx4 a[52:55], v5, s[4:5] offset:80
	global_load_dwordx4 a[56:59], v5, s[4:5] offset:96
	global_load_dwordx4 a[60:63], v5, s[4:5] offset:112
	s_lshl_b32 s11, s10, 12
	v_add_u32_e32 v6, s11, v3
	global_load_dwordx2 a[70:71], v6, s[6:7]
	s_add_u32 s10, s8, s21
	s_min_u32 s10, s10, s13
	s_lshl_b32 s11, s10, 10
	v_add_u32_e32 v5, s11, v2
	global_load_dwordx4 a[196:199], v5, s[4:5] offset:0
	global_load_dwordx4 a[200:203], v5, s[4:5] offset:16
	global_load_dwordx4 a[204:207], v5, s[4:5] offset:32
	global_load_dwordx4 a[208:211], v5, s[4:5] offset:48
	global_load_dwordx4 a[212:215], v5, s[4:5] offset:64
	global_load_dwordx4 a[216:219], v5, s[4:5] offset:80
	global_load_dwordx4 a[220:223], v5, s[4:5] offset:96
	global_load_dwordx4 a[224:227], v5, s[4:5] offset:112
	s_lshl_b32 s11, s10, 12
	v_add_u32_e32 v6, s11, v3
	global_load_dwordx2 a[72:73], v6, s[6:7]
	s_waitcnt vmcnt(0)
	v_accvgpr_read_b32 v10, a0
	v_add_u32_e32 v10, v10, v1
	global_load_dwordx4 v[64:67], v10, s[2:3]
	v_accvgpr_read_b32 v11, a2
	v_add_u32_e32 v11, v11, v1
	global_load_dwordx4 v[68:71], v11, s[2:3]
	v_accvgpr_read_b32 v12, a4
	v_add_u32_e32 v12, v12, v1
	global_load_dwordx4 v[72:75], v12, s[2:3]
	v_accvgpr_read_b32 v13, a6
	v_add_u32_e32 v13, v13, v1
	global_load_dwordx4 v[76:79], v13, s[2:3]
	v_accvgpr_read_b32 v10, a8
	v_add_u32_e32 v10, v10, v1
	global_load_dwordx4 v[80:83], v10, s[2:3]
	v_accvgpr_read_b32 v11, a10
	v_add_u32_e32 v11, v11, v1
	global_load_dwordx4 v[84:87], v11, s[2:3]
	v_accvgpr_read_b32 v12, a12
	v_add_u32_e32 v12, v12, v1
	global_load_dwordx4 v[88:91], v12, s[2:3]
	v_accvgpr_read_b32 v13, a14
	v_add_u32_e32 v13, v13, v1
	global_load_dwordx4 v[92:95], v13, s[2:3]
	v_accvgpr_read_b32 v10, a16
	v_add_u32_e32 v10, v10, v1
	global_load_dwordx4 v[96:99], v10, s[2:3]
	v_accvgpr_read_b32 v11, a18
	v_add_u32_e32 v11, v11, v1
	global_load_dwordx4 v[100:103], v11, s[2:3]
	v_accvgpr_read_b32 v12, a20
	v_add_u32_e32 v12, v12, v1
	global_load_dwordx4 v[104:107], v12, s[2:3]
	v_accvgpr_read_b32 v13, a22
	v_add_u32_e32 v13, v13, v1
	global_load_dwordx4 v[108:111], v13, s[2:3]
	v_accvgpr_read_b32 v10, a24
	v_add_u32_e32 v10, v10, v1
	global_load_dwordx4 v[112:115], v10, s[2:3]
	v_accvgpr_read_b32 v11, a26
	v_add_u32_e32 v11, v11, v1
	global_load_dwordx4 v[116:119], v11, s[2:3]
	v_accvgpr_read_b32 v12, a28
	v_add_u32_e32 v12, v12, v1
	global_load_dwordx4 v[120:123], v12, s[2:3]
	v_accvgpr_read_b32 v13, a30
	v_add_u32_e32 v13, v13, v1
	global_load_dwordx4 v[124:127], v13, s[2:3]
	global_load_dword a76, v5, s[4:5]
	global_load_dword a76, v5, s[4:5]
.Lp5v_loop:
	s_add_u32 s10, s8, s22
	s_min_u32 s10, s10, s13
	s_lshl_b32 s11, s10, 10
	v_add_u32_e32 v5, s11, v2
	global_load_dwordx4 a[228:231], v5, s[4:5] offset:0
	global_load_dwordx4 a[232:235], v5, s[4:5] offset:16
	global_load_dwordx4 a[236:239], v5, s[4:5] offset:32
	global_load_dwordx4 a[240:243], v5, s[4:5] offset:48
	global_load_dwordx4 a[244:247], v5, s[4:5] offset:64
	global_load_dwordx4 a[248:251], v5, s[4:5] offset:80
	global_load_dwordx4 a[252:255], v5, s[4:5] offset:96
	global_load_dwordx4 a[64:67], v5, s[4:5] offset:112
	s_lshl_b32 s11, s10, 12
	v_add_u32_e32 v6, s11, v3
	global_load_dwordx2 a[74:75], v6, s[6:7]
	v_accvgpr_read_b32 v10, a32
	v_add_u32_e32 v10, v10, v1
	global_load_dwordx4 v[128:131], v10, s[2:3]
	v_accvgpr_read_b32 v11, a34
	v_add_u32_e32 v11, v11, v1
	global_load_dwordx4 v[132:135], v11, s[2:3]
	v_accvgpr_read_b32 v12, a36
	v_add_u32_e32 v12, v12, v1
	global_load_dwordx4 v[136:139], v12, s[2:3]
	v_accvgpr_read_b32 v13, a38
	v_add_u32_e32 v13, v13, v1
	global_load_dwordx4 v[140:143], v13, s[2:3]
	v_accvgpr_read_b32 v10, a40
	v_add_u32_e32 v10, v10, v1
	global_load_dwordx4 v[144:147], v10, s[2:3]
	v_accvgpr_read_b32 v11, a42
	v_add_u32_e32 v11, v11, v1
	global_load_dwordx4 v[148:151], v11, s[2:3]
	v_accvgpr_read_b32 v12, a44
	v_add_u32_e32 v12, v12, v1
	global_load_dwordx4 v[152:155], v12, s[2:3]
	v_accvgpr_read_b32 v13, a46
	v_add_u32_e32 v13, v13, v1
	global_load_dwordx4 v[156:159], v13, s[2:3]
	v_accvgpr_read_b32 v10, a48
	v_add_u32_e32 v10, v10, v1
	global_load_dwordx4 v[160:163], v10, s[2:3]
	v_accvgpr_read_b32 v11, a50
	v_add_u32_e32 v11, v11, v1
	global_load_dwordx4 v[164:167], v11, s[2:3]
	v_accvgpr_read_b32 v12, a52
	v_add_u32_e32 v12, v12, v1
	global_load_dwordx4 v[168:171], v12, s[2:3]
	v_accvgpr_read_b32 v13, a54
	v_add_u32_e32 v13, v13, v1
	global_load_dwordx4 v[172:175], v13, s[2:3]
	v_accvgpr_read_b32 v10, a56
	v_add_u32_e32 v10, v10, v1
	global_load_dwordx4 v[176:179], v10, s[2:3]
	v_accvgpr_read_b32 v11, a58
	v_add_u32_e32 v11, v11, v1
	global_load_dwordx4 v[180:183], v11, s[2:3]
	v_accvgpr_read_b32 v12, a60
	v_add_u32_e32 v12, v12, v1
	global_load_dwordx4 v[184:187], v12, s[2:3]
	v_accvgpr_read_b32 v13, a62
	v_add_u32_e32 v13, v13, v1
	global_load_dwordx4 v[188:191], v13, s[2:3]
	s_mov_b32 s12, s8
	s_waitcnt vmcnt(27)
	s_cmp_lt_u32 s12, 0x4200
	s_cbranch_scc0 .Lp5v_skip0
	v_accvgpr_read_b32 v40, a1
	v_cvt_pk_f32_fp8_e32 v[32:33], v64
	v_cvt_pk_f32_fp8_sdwa v[34:35], v64 src0_sel:WORD_1
	v_pk_mul_f32 v[16:17], v[32:33], v[40:41] op_sel_hi:[1,0]
	v_pk_mul_f32 v[18:19], v[34:35], v[40:41] op_sel_hi:[1,0]
	v_cvt_pk_f32_fp8_e32 v[36:37], v65
	v_cvt_pk_f32_fp8_sdwa v[38:39], v65 src0_sel:WORD_1
	v_pk_mul_f32 v[20:21], v[36:37], v[40:41] op_sel_hi:[1,0]
	v_pk_mul_f32 v[22:23], v[38:39], v[40:41] op_sel_hi:[1,0]
	v_cvt_pk_f32_fp8_e32 v[32:33], v66
	v_cvt_pk_f32_fp8_sdwa v[34:35], v66 src0_sel:WORD_1
	v_pk_mul_f32 v[24:25], v[32:33], v[40:41] op_sel_hi:[1,0]
	v_pk_mul_f32 v[26:27], v[34:35], v[40:41] op_sel_hi:[1,0]
	v_cvt_pk_f32_fp8_e32 v[36:37], v67
	v_cvt_pk_f32_fp8_sdwa v[38:39], v67 src0_sel:WORD_1
	v_pk_mul_f32 v[28:29], v[36:37], v[40:41] op_sel_hi:[1,0]
	v_pk_mul_f32 v[30:31], v[38:39], v[40:41] op_sel_hi:[1,0]
	v_accvgpr_read_b32 v42, a3
	v_cvt_pk_f32_fp8_e32 v[32:33], v68
	v_cvt_pk_f32_fp8_sdwa v[34:35], v68 src0_sel:WORD_1
	v_pk_fma_f32 v[16:17], v[32:33], v[42:43], v[16:17] op_sel_hi:[1,0,1]
	v_pk_fma_f32 v[18:19], v[34:35], v[42:43], v[18:19] op_sel_hi:[1,0,1]
	v_cvt_pk_f32_fp8_e32 v[36:37], v69
	v_cvt_pk_f32_fp8_sdwa v[38:39], v69 src0_sel:WORD_1
	v_pk_fma_f32 v[20:21], v[36:37], v[42:43], v[20:21] op_sel_hi:[1,0,1]
	v_pk_fma_f32 v[22:23], v[38:39], v[42:43], v[22:23] op_sel_hi:[1,0,1]
	v_cvt_pk_f32_fp8_e32 v[32:33], v70
	v_cvt_pk_f32_fp8_sdwa v[34:35], v70 src0_sel:WORD_1
	v_pk_fma_f32 v[24:25], v[32:33], v[42:43], v[24:25] op_sel_hi:[1,0,1]
	v_pk_fma_f32 v[26:27], v[34:35], v[42:43], v[26:27] op_sel_hi:[1,0,1]
	v_cvt_pk_f32_fp8_e32 v[36:37], v71
	v_cvt_pk_f32_fp8_sdwa v[38:39], v71 src0_sel:WORD_1
	v_pk_fma_f32 v[28:29], v[36:37], v[42:43], v[28:29] op_sel_hi:[1,0,1]
	v_pk_fma_f32 v[30:31], v[38:39], v[42:43], v[30:31] op_sel_hi:[1,0,1]
	v_accvgpr_read_b32 v40, a5
	v_cvt_pk_f32_fp8_e32 v[32:33], v72
	v_cvt_pk_f32_fp8_sdwa v[34:35], v72 src0_sel:WORD_1
	v_pk_fma_f32 v[16:17], v[32:33], v[40:41], v[16:17] op_sel_hi:[1,0,1]
	v_pk_fma_f32 v[18:19], v[34:35], v[40:41], v[18:19] op_sel_hi:[1,0,1]
	v_cvt_pk_f32_fp8_e32 v[36:37], v73
	v_cvt_pk_f32_fp8_sdwa v[38:39], v73 src0_sel:WORD_1
	v_pk_fma_f32 v[20:21], v[36:37], v[40:41], v[20:21] op_sel_hi:[1,0,1]
	v_pk_fma_f32 v[22:23], v[38:39], v[40:41], v[22:23] op_sel_hi:[1,0,1]
	v_cvt_pk_f32_fp8_e32 v[32:33], v74
	v_cvt_pk_f32_fp8_sdwa v[34:35], v74 src0_sel:WORD_1
	v_pk_fma_f32 v[24:25], v[32:33], v[40:41], v[24:25] op_sel_hi:[1,0,1]
	v_pk_fma_f32 v[26:27], v[34:35], v[40:41], v[26:27] op_sel_hi:[1,0,1]
	v_cvt_pk_f32_fp8_e32 v[36:37], v75
	v_cvt_pk_f32_fp8_sdwa v[38:39], v75 src0_sel:WORD_1
	v_pk_fma_f32 v[28:29], v[36:37], v[40:41], v[28:29] op_sel_hi:[1,0,1]
	v_pk_fma_f32 v[30:31], v[38:39], v[40:41], v[30:31] op_sel_hi:[1,0,1]
	v_accvgpr_read_b32 v42, a7
	v_cvt_pk_f32_fp8_e32 v[32:33], v76
	v_cvt_pk_f32_fp8_sdwa v[34:35], v76 src0_sel:WORD_1
	v_pk_fma_f32 v[16:17], v[32:33], v[42:43], v[16:17] op_sel_hi:[1,0,1]
	v_pk_fma_f32 v[18:19], v[34:35], v[42:43], v[18:19] op_sel_hi:[1,0,1]
	v_cvt_pk_f32_fp8_e32 v[36:37], v77
	v_cvt_pk_f32_fp8_sdwa v[38:39], v77 src0_sel:WORD_1
	v_pk_fma_f32 v[20:21], v[36:37], v[42:43], v[20:21] op_sel_hi:[1,0,1]
	v_pk_fma_f32 v[22:23], v[38:39], v[42:43], v[22:23] op_sel_hi:[1,0,1]
	v_cvt_pk_f32_fp8_e32 v[32:33], v78
	v_cvt_pk_f32_fp8_sdwa v[34:35], v78 src0_sel:WORD_1
	v_pk_fma_f32 v[24:25], v[32:33], v[42:43], v[24:25] op_sel_hi:[1,0,1]
	v_pk_fma_f32 v[26:27], v[34:35], v[42:43], v[26:27] op_sel_hi:[1,0,1]
	v_cvt_pk_f32_fp8_e32 v[36:37], v79
	v_cvt_pk_f32_fp8_sdwa v[38:39], v79 src0_sel:WORD_1
	v_pk_fma_f32 v[28:29], v[36:37], v[42:43], v[28:29] op_sel_hi:[1,0,1]
	v_pk_fma_f32 v[30:31], v[38:39], v[42:43], v[30:31] op_sel_hi:[1,0,1]
	v_accvgpr_read_b32 v40, a9
	v_cvt_pk_f32_fp8_e32 v[32:33], v80
	v_cvt_pk_f32_fp8_sdwa v[34:35], v80 src0_sel:WORD_1
	v_pk_fma_f32 v[16:17], v[32:33], v[40:41], v[16:17] op_sel_hi:[1,0,1]
	v_pk_fma_f32 v[18:19], v[34:35], v[40:41], v[18:19] op_sel_hi:[1,0,1]
	v_cvt_pk_f32_fp8_e32 v[36:37], v81
	v_cvt_pk_f32_fp8_sdwa v[38:39], v81 src0_sel:WORD_1
	v_pk_fma_f32 v[20:21], v[36:37], v[40:41], v[20:21] op_sel_hi:[1,0,1]
	v_pk_fma_f32 v[22:23], v[38:39], v[40:41], v[22:23] op_sel_hi:[1,0,1]
	v_cvt_pk_f32_fp8_e32 v[32:33], v82
	v_cvt_pk_f32_fp8_sdwa v[34:35], v82 src0_sel:WORD_1
	v_pk_fma_f32 v[24:25], v[32:33], v[40:41], v[24:25] op_sel_hi:[1,0,1]
	v_pk_fma_f32 v[26:27], v[34:35], v[40:41], v[26:27] op_sel_hi:[1,0,1]
	v_cvt_pk_f32_fp8_e32 v[36:37], v83
	v_cvt_pk_f32_fp8_sdwa v[38:39], v83 src0_sel:WORD_1
	v_pk_fma_f32 v[28:29], v[36:37], v[40:41], v[28:29] op_sel_hi:[1,0,1]
	v_pk_fma_f32 v[30:31], v[38:39], v[40:41], v[30:31] op_sel_hi:[1,0,1]
	v_accvgpr_read_b32 v42, a11
	v_cvt_pk_f32_fp8_e32 v[32:33], v84
	v_cvt_pk_f32_fp8_sdwa v[34:35], v84 src0_sel:WORD_1
	v_pk_fma_f32 v[16:17], v[32:33], v[42:43], v[16:17] op_sel_hi:[1,0,1]
	v_pk_fma_f32 v[18:19], v[34:35], v[42:43], v[18:19] op_sel_hi:[1,0,1]
	v_cvt_pk_f32_fp8_e32 v[36:37], v85
	v_cvt_pk_f32_fp8_sdwa v[38:39], v85 src0_sel:WORD_1
	v_pk_fma_f32 v[20:21], v[36:37], v[42:43], v[20:21] op_sel_hi:[1,0,1]
	v_pk_fma_f32 v[22:23], v[38:39], v[42:43], v[22:23] op_sel_hi:[1,0,1]
	v_cvt_pk_f32_fp8_e32 v[32:33], v86
	v_cvt_pk_f32_fp8_sdwa v[34:35], v86 src0_sel:WORD_1
	v_pk_fma_f32 v[24:25], v[32:33], v[42:43], v[24:25] op_sel_hi:[1,0,1]
	v_pk_fma_f32 v[26:27], v[34:35], v[42:43], v[26:27] op_sel_hi:[1,0,1]
	v_cvt_pk_f32_fp8_e32 v[36:37], v87
	v_cvt_pk_f32_fp8_sdwa v[38:39], v87 src0_sel:WORD_1
	v_pk_fma_f32 v[28:29], v[36:37], v[42:43], v[28:29] op_sel_hi:[1,0,1]
	v_pk_fma_f32 v[30:31], v[38:39], v[42:43], v[30:31] op_sel_hi:[1,0,1]
	v_accvgpr_read_b32 v40, a13
	v_cvt_pk_f32_fp8_e32 v[32:33], v88
	v_cvt_pk_f32_fp8_sdwa v[34:35], v88 src0_sel:WORD_1
	v_pk_fma_f32 v[16:17], v[32:33], v[40:41], v[16:17] op_sel_hi:[1,0,1]
	v_pk_fma_f32 v[18:19], v[34:35], v[40:41], v[18:19] op_sel_hi:[1,0,1]
	v_cvt_pk_f32_fp8_e32 v[36:37], v89
	v_cvt_pk_f32_fp8_sdwa v[38:39], v89 src0_sel:WORD_1
	v_pk_fma_f32 v[20:21], v[36:37], v[40:41], v[20:21] op_sel_hi:[1,0,1]
	v_pk_fma_f32 v[22:23], v[38:39], v[40:41], v[22:23] op_sel_hi:[1,0,1]
	v_cvt_pk_f32_fp8_e32 v[32:33], v90
	v_cvt_pk_f32_fp8_sdwa v[34:35], v90 src0_sel:WORD_1
	v_pk_fma_f32 v[24:25], v[32:33], v[40:41], v[24:25] op_sel_hi:[1,0,1]
	v_pk_fma_f32 v[26:27], v[34:35], v[40:41], v[26:27] op_sel_hi:[1,0,1]
	v_cvt_pk_f32_fp8_e32 v[36:37], v91
	v_cvt_pk_f32_fp8_sdwa v[38:39], v91 src0_sel:WORD_1
	v_pk_fma_f32 v[28:29], v[36:37], v[40:41], v[28:29] op_sel_hi:[1,0,1]
	v_pk_fma_f32 v[30:31], v[38:39], v[40:41], v[30:31] op_sel_hi:[1,0,1]
	v_accvgpr_read_b32 v42, a15
	v_cvt_pk_f32_fp8_e32 v[32:33], v92
	v_cvt_pk_f32_fp8_sdwa v[34:35], v92 src0_sel:WORD_1
	v_pk_fma_f32 v[16:17], v[32:33], v[42:43], v[16:17] op_sel_hi:[1,0,1]
	v_pk_fma_f32 v[18:19], v[34:35], v[42:43], v[18:19] op_sel_hi:[1,0,1]
	v_cvt_pk_f32_fp8_e32 v[36:37], v93
	v_cvt_pk_f32_fp8_sdwa v[38:39], v93 src0_sel:WORD_1
	v_pk_fma_f32 v[20:21], v[36:37], v[42:43], v[20:21] op_sel_hi:[1,0,1]
	v_pk_fma_f32 v[22:23], v[38:39], v[42:43], v[22:23] op_sel_hi:[1,0,1]
	v_cvt_pk_f32_fp8_e32 v[32:33], v94
	v_cvt_pk_f32_fp8_sdwa v[34:35], v94 src0_sel:WORD_1
	v_pk_fma_f32 v[24:25], v[32:33], v[42:43], v[24:25] op_sel_hi:[1,0,1]
	v_pk_fma_f32 v[26:27], v[34:35], v[42:43], v[26:27] op_sel_hi:[1,0,1]
	v_cvt_pk_f32_fp8_e32 v[36:37], v95
	v_cvt_pk_f32_fp8_sdwa v[38:39], v95 src0_sel:WORD_1
	v_pk_fma_f32 v[28:29], v[36:37], v[42:43], v[28:29] op_sel_hi:[1,0,1]
	v_pk_fma_f32 v[30:31], v[38:39], v[42:43], v[30:31] op_sel_hi:[1,0,1]
	v_accvgpr_read_b32 v40, a17
	v_cvt_pk_f32_fp8_e32 v[32:33], v96
	v_cvt_pk_f32_fp8_sdwa v[34:35], v96 src0_sel:WORD_1
	v_pk_fma_f32 v[16:17], v[32:33], v[40:41], v[16:17] op_sel_hi:[1,0,1]
	v_pk_fma_f32 v[18:19], v[34:35], v[40:41], v[18:19] op_sel_hi:[1,0,1]
	v_cvt_pk_f32_fp8_e32 v[36:37], v97
	v_cvt_pk_f32_fp8_sdwa v[38:39], v97 src0_sel:WORD_1
	v_pk_fma_f32 v[20:21], v[36:37], v[40:41], v[20:21] op_sel_hi:[1,0,1]
	v_pk_fma_f32 v[22:23], v[38:39], v[40:41], v[22:23] op_sel_hi:[1,0,1]
	v_cvt_pk_f32_fp8_e32 v[32:33], v98
	v_cvt_pk_f32_fp8_sdwa v[34:35], v98 src0_sel:WORD_1
	v_pk_fma_f32 v[24:25], v[32:33], v[40:41], v[24:25] op_sel_hi:[1,0,1]
	v_pk_fma_f32 v[26:27], v[34:35], v[40:41], v[26:27] op_sel_hi:[1,0,1]
	v_cvt_pk_f32_fp8_e32 v[36:37], v99
	v_cvt_pk_f32_fp8_sdwa v[38:39], v99 src0_sel:WORD_1
	v_pk_fma_f32 v[28:29], v[36:37], v[40:41], v[28:29] op_sel_hi:[1,0,1]
	v_pk_fma_f32 v[30:31], v[38:39], v[40:41], v[30:31] op_sel_hi:[1,0,1]
	v_accvgpr_read_b32 v42, a19
	v_cvt_pk_f32_fp8_e32 v[32:33], v100
	v_cvt_pk_f32_fp8_sdwa v[34:35], v100 src0_sel:WORD_1
	v_pk_fma_f32 v[16:17], v[32:33], v[42:43], v[16:17] op_sel_hi:[1,0,1]
	v_pk_fma_f32 v[18:19], v[34:35], v[42:43], v[18:19] op_sel_hi:[1,0,1]
	v_cvt_pk_f32_fp8_e32 v[36:37], v101
	v_cvt_pk_f32_fp8_sdwa v[38:39], v101 src0_sel:WORD_1
	v_pk_fma_f32 v[20:21], v[36:37], v[42:43], v[20:21] op_sel_hi:[1,0,1]
	v_pk_fma_f32 v[22:23], v[38:39], v[42:43], v[22:23] op_sel_hi:[1,0,1]
	v_cvt_pk_f32_fp8_e32 v[32:33], v102
	v_cvt_pk_f32_fp8_sdwa v[34:35], v102 src0_sel:WORD_1
	v_pk_fma_f32 v[24:25], v[32:33], v[42:43], v[24:25] op_sel_hi:[1,0,1]
	v_pk_fma_f32 v[26:27], v[34:35], v[42:43], v[26:27] op_sel_hi:[1,0,1]
	v_cvt_pk_f32_fp8_e32 v[36:37], v103
	v_cvt_pk_f32_fp8_sdwa v[38:39], v103 src0_sel:WORD_1
	v_pk_fma_f32 v[28:29], v[36:37], v[42:43], v[28:29] op_sel_hi:[1,0,1]
	v_pk_fma_f32 v[30:31], v[38:39], v[42:43], v[30:31] op_sel_hi:[1,0,1]
	v_accvgpr_read_b32 v40, a21
	v_cvt_pk_f32_fp8_e32 v[32:33], v104
	v_cvt_pk_f32_fp8_sdwa v[34:35], v104 src0_sel:WORD_1
	v_pk_fma_f32 v[16:17], v[32:33], v[40:41], v[16:17] op_sel_hi:[1,0,1]
	v_pk_fma_f32 v[18:19], v[34:35], v[40:41], v[18:19] op_sel_hi:[1,0,1]
	v_cvt_pk_f32_fp8_e32 v[36:37], v105
	v_cvt_pk_f32_fp8_sdwa v[38:39], v105 src0_sel:WORD_1
	v_pk_fma_f32 v[20:21], v[36:37], v[40:41], v[20:21] op_sel_hi:[1,0,1]
	v_pk_fma_f32 v[22:23], v[38:39], v[40:41], v[22:23] op_sel_hi:[1,0,1]
	v_cvt_pk_f32_fp8_e32 v[32:33], v106
	v_cvt_pk_f32_fp8_sdwa v[34:35], v106 src0_sel:WORD_1
	v_pk_fma_f32 v[24:25], v[32:33], v[40:41], v[24:25] op_sel_hi:[1,0,1]
	v_pk_fma_f32 v[26:27], v[34:35], v[40:41], v[26:27] op_sel_hi:[1,0,1]
	v_cvt_pk_f32_fp8_e32 v[36:37], v107
	v_cvt_pk_f32_fp8_sdwa v[38:39], v107 src0_sel:WORD_1
	v_pk_fma_f32 v[28:29], v[36:37], v[40:41], v[28:29] op_sel_hi:[1,0,1]
	v_pk_fma_f32 v[30:31], v[38:39], v[40:41], v[30:31] op_sel_hi:[1,0,1]
	v_accvgpr_read_b32 v42, a23
	v_cvt_pk_f32_fp8_e32 v[32:33], v108
	v_cvt_pk_f32_fp8_sdwa v[34:35], v108 src0_sel:WORD_1
	v_pk_fma_f32 v[16:17], v[32:33], v[42:43], v[16:17] op_sel_hi:[1,0,1]
	v_pk_fma_f32 v[18:19], v[34:35], v[42:43], v[18:19] op_sel_hi:[1,0,1]
	v_cvt_pk_f32_fp8_e32 v[36:37], v109
	v_cvt_pk_f32_fp8_sdwa v[38:39], v109 src0_sel:WORD_1
	v_pk_fma_f32 v[20:21], v[36:37], v[42:43], v[20:21] op_sel_hi:[1,0,1]
	v_pk_fma_f32 v[22:23], v[38:39], v[42:43], v[22:23] op_sel_hi:[1,0,1]
	v_cvt_pk_f32_fp8_e32 v[32:33], v110
	v_cvt_pk_f32_fp8_sdwa v[34:35], v110 src0_sel:WORD_1
	v_pk_fma_f32 v[24:25], v[32:33], v[42:43], v[24:25] op_sel_hi:[1,0,1]
	v_pk_fma_f32 v[26:27], v[34:35], v[42:43], v[26:27] op_sel_hi:[1,0,1]
	v_cvt_pk_f32_fp8_e32 v[36:37], v111
	v_cvt_pk_f32_fp8_sdwa v[38:39], v111 src0_sel:WORD_1
	v_pk_fma_f32 v[28:29], v[36:37], v[42:43], v[28:29] op_sel_hi:[1,0,1]
	v_pk_fma_f32 v[30:31], v[38:39], v[42:43], v[30:31] op_sel_hi:[1,0,1]
	v_accvgpr_read_b32 v40, a25
	v_cvt_pk_f32_fp8_e32 v[32:33], v112
	v_cvt_pk_f32_fp8_sdwa v[34:35], v112 src0_sel:WORD_1
	v_pk_fma_f32 v[16:17], v[32:33], v[40:41], v[16:17] op_sel_hi:[1,0,1]
	v_pk_fma_f32 v[18:19], v[34:35], v[40:41], v[18:19] op_sel_hi:[1,0,1]
	v_cvt_pk_f32_fp8_e32 v[36:37], v113
	v_cvt_pk_f32_fp8_sdwa v[38:39], v113 src0_sel:WORD_1
	v_pk_fma_f32 v[20:21], v[36:37], v[40:41], v[20:21] op_sel_hi:[1,0,1]
	v_pk_fma_f32 v[22:23], v[38:39], v[40:41], v[22:23] op_sel_hi:[1,0,1]
	v_cvt_pk_f32_fp8_e32 v[32:33], v114
	v_cvt_pk_f32_fp8_sdwa v[34:35], v114 src0_sel:WORD_1
	v_pk_fma_f32 v[24:25], v[32:33], v[40:41], v[24:25] op_sel_hi:[1,0,1]
	v_pk_fma_f32 v[26:27], v[34:35], v[40:41], v[26:27] op_sel_hi:[1,0,1]
	v_cvt_pk_f32_fp8_e32 v[36:37], v115
	v_cvt_pk_f32_fp8_sdwa v[38:39], v115 src0_sel:WORD_1
	v_pk_fma_f32 v[28:29], v[36:37], v[40:41], v[28:29] op_sel_hi:[1,0,1]
	v_pk_fma_f32 v[30:31], v[38:39], v[40:41], v[30:31] op_sel_hi:[1,0,1]
	v_accvgpr_read_b32 v42, a27
	v_cvt_pk_f32_fp8_e32 v[32:33], v116
	v_cvt_pk_f32_fp8_sdwa v[34:35], v116 src0_sel:WORD_1
	v_pk_fma_f32 v[16:17], v[32:33], v[42:43], v[16:17] op_sel_hi:[1,0,1]
	v_pk_fma_f32 v[18:19], v[34:35], v[42:43], v[18:19] op_sel_hi:[1,0,1]
	v_cvt_pk_f32_fp8_e32 v[36:37], v117
	v_cvt_pk_f32_fp8_sdwa v[38:39], v117 src0_sel:WORD_1
	v_pk_fma_f32 v[20:21], v[36:37], v[42:43], v[20:21] op_sel_hi:[1,0,1]
	v_pk_fma_f32 v[22:23], v[38:39], v[42:43], v[22:23] op_sel_hi:[1,0,1]
	v_cvt_pk_f32_fp8_e32 v[32:33], v118
	v_cvt_pk_f32_fp8_sdwa v[34:35], v118 src0_sel:WORD_1
	v_pk_fma_f32 v[24:25], v[32:33], v[42:43], v[24:25] op_sel_hi:[1,0,1]
	v_pk_fma_f32 v[26:27], v[34:35], v[42:43], v[26:27] op_sel_hi:[1,0,1]
	v_cvt_pk_f32_fp8_e32 v[36:37], v119
	v_cvt_pk_f32_fp8_sdwa v[38:39], v119 src0_sel:WORD_1
	v_pk_fma_f32 v[28:29], v[36:37], v[42:43], v[28:29] op_sel_hi:[1,0,1]
	v_pk_fma_f32 v[30:31], v[38:39], v[42:43], v[30:31] op_sel_hi:[1,0,1]
	v_accvgpr_read_b32 v40, a29
	v_cvt_pk_f32_fp8_e32 v[32:33], v120
	v_cvt_pk_f32_fp8_sdwa v[34:35], v120 src0_sel:WORD_1
	v_pk_fma_f32 v[16:17], v[32:33], v[40:41], v[16:17] op_sel_hi:[1,0,1]
	v_pk_fma_f32 v[18:19], v[34:35], v[40:41], v[18:19] op_sel_hi:[1,0,1]
	v_cvt_pk_f32_fp8_e32 v[36:37], v121
	v_cvt_pk_f32_fp8_sdwa v[38:39], v121 src0_sel:WORD_1
	v_pk_fma_f32 v[20:21], v[36:37], v[40:41], v[20:21] op_sel_hi:[1,0,1]
	v_pk_fma_f32 v[22:23], v[38:39], v[40:41], v[22:23] op_sel_hi:[1,0,1]
	v_cvt_pk_f32_fp8_e32 v[32:33], v122
	v_cvt_pk_f32_fp8_sdwa v[34:35], v122 src0_sel:WORD_1
	v_pk_fma_f32 v[24:25], v[32:33], v[40:41], v[24:25] op_sel_hi:[1,0,1]
	v_pk_fma_f32 v[26:27], v[34:35], v[40:41], v[26:27] op_sel_hi:[1,0,1]
	v_cvt_pk_f32_fp8_e32 v[36:37], v123
	v_cvt_pk_f32_fp8_sdwa v[38:39], v123 src0_sel:WORD_1
	v_pk_fma_f32 v[28:29], v[36:37], v[40:41], v[28:29] op_sel_hi:[1,0,1]
	v_pk_fma_f32 v[30:31], v[38:39], v[40:41], v[30:31] op_sel_hi:[1,0,1]
	v_accvgpr_read_b32 v42, a31
	v_cvt_pk_f32_fp8_e32 v[32:33], v124
	v_cvt_pk_f32_fp8_sdwa v[34:35], v124 src0_sel:WORD_1
	v_pk_fma_f32 v[16:17], v[32:33], v[42:43], v[16:17] op_sel_hi:[1,0,1]
	v_pk_fma_f32 v[18:19], v[34:35], v[42:43], v[18:19] op_sel_hi:[1,0,1]
	v_cvt_pk_f32_fp8_e32 v[36:37], v125
; __device__ __forceinline__ float wsum(float v) { v = dpp_row_sum16(v); v += __shfl_xor(v, 16); v += __shfl_xor(v, 32); return v; }
; __device__ __forceinline__ void phase5(const Params& p, char* smem, const bool store_x = true) {
;     ...
;     float x2[16];
; #pragma unroll
;     for (int i = 0; i < 4; i++) {
;       const float4 xv = i == 0 ? xv0 : i == 1 ? xv1 : i == 2 ? xv2 : xv3;
;       x2[4 * i] = xv.x + o2[2 * i].x; x2[4 * i + 1] = xv.y + o2[2 * i].y; x2[4 * i + 2] = xv.z + o2[2 * i + 1].x; x2[4 * i + 3] = xv.w + o2[2 * i + 1].y;
;     }
;     float ss = 0.f;
; #pragma unroll
;     for (int i = 0; i < 16; i++) ss += x2[i] * x2[i];
;     ss = wsum(ss);
;     const float rs = rsqrtf(ss * (1.f / 1024.f) + EPSF);
;     if (store_x) {
; #pragma unroll
;       for (int i = 0; i < 4; i++) *(float4*)(xr + i * 4) = make_float4(x2[4 * i], x2[4 * i + 1], x2[4 * i + 2], x2[4 * i + 3]);
;     }
	v_cvt_pk_f32_fp8_sdwa v[38:39], v125 src0_sel:WORD_1
	v_pk_fma_f32 v[20:21], v[36:37], v[42:43], v[20:21] op_sel_hi:[1,0,1]
	v_pk_fma_f32 v[22:23], v[38:39], v[42:43], v[22:23] op_sel_hi:[1,0,1]
	v_cvt_pk_f32_fp8_e32 v[32:33], v126
	v_cvt_pk_f32_fp8_sdwa v[34:35], v126 src0_sel:WORD_1
	v_pk_fma_f32 v[24:25], v[32:33], v[42:43], v[24:25] op_sel_hi:[1,0,1]
	v_pk_fma_f32 v[26:27], v[34:35], v[42:43], v[26:27] op_sel_hi:[1,0,1]
	v_cvt_pk_f32_fp8_e32 v[36:37], v127
	v_cvt_pk_f32_fp8_sdwa v[38:39], v127 src0_sel:WORD_1
	v_pk_fma_f32 v[28:29], v[36:37], v[42:43], v[28:29] op_sel_hi:[1,0,1]
	v_pk_fma_f32 v[30:31], v[38:39], v[42:43], v[30:31] op_sel_hi:[1,0,1]
	s_nop 1
	v_permlane32_swap_b32_e32 v16, v24
	v_permlane32_swap_b32_e32 v17, v25
	v_permlane32_swap_b32_e32 v18, v26
	v_permlane32_swap_b32_e32 v19, v27
	v_permlane32_swap_b32_e32 v20, v28
	v_permlane32_swap_b32_e32 v21, v29
	v_permlane32_swap_b32_e32 v22, v30
	v_permlane32_swap_b32_e32 v23, v31
	v_add_f32_e32 v16, v16, v24
	v_add_f32_e32 v17, v17, v25
	v_add_f32_e32 v18, v18, v26
	v_add_f32_e32 v19, v19, v27
	v_add_f32_e32 v20, v20, v28
	v_add_f32_e32 v21, v21, v29
	v_add_f32_e32 v22, v22, v30
	v_add_f32_e32 v23, v23, v31
	s_nop 1
	v_permlane16_swap_b32_e32 v16, v20
	v_permlane16_swap_b32_e32 v17, v21
	v_permlane16_swap_b32_e32 v18, v22
	v_permlane16_swap_b32_e32 v19, v23
	v_add_f32_e32 v16, v16, v20
	v_add_f32_e32 v17, v17, v21
	v_add_f32_e32 v18, v18, v22
	v_add_f32_e32 v19, v19, v23
	v_accvgpr_read_b32 v50, a68
	v_accvgpr_read_b32 v51, a69
	v_add_f32_dpp v44, v16, v16 row_ror:8 row_mask:0xf bank_mask:0xf
	v_add_f32_dpp v45, v18, v18 row_ror:8 row_mask:0xf bank_mask:0xf
	v_add_f32_dpp v46, v17, v17 row_ror:8 row_mask:0xf bank_mask:0xf
	v_add_f32_dpp v47, v19, v19 row_ror:8 row_mask:0xf bank_mask:0xf
	v_cndmask_b32_e64 v48, v44, v45, s[14:15]
	v_cndmask_b32_e64 v49, v46, v47, s[14:15]
	v_add_f32_e32 v48, v50, v48
	v_add_f32_e32 v49, v51, v49
	s_lshl_b32 s11, s12, 12
	v_add_u32_e32 v6, s11, v3
	global_store_dwordx2 v6, v[48:49], s[6:7]
	v_mul_f32_e32 v52, v48, v48
	v_fmac_f32_e32 v52, v49, v49
	s_lshl_b32 s11, s12, 2
	s_add_u32 s11, s11, 0x1100000
	v_mov_b32_e32 v7, s11
	v_add_f32_dpp v52, v52, v52 quad_perm:[1,0,3,2] row_mask:0xf bank_mask:0xf
	s_nop 1
	v_add_f32_dpp v52, v52, v52 quad_perm:[2,3,0,1] row_mask:0xf bank_mask:0xf
	s_nop 1
	v_add_f32_dpp v52, v52, v52 row_half_mirror row_mask:0xf bank_mask:0xf
	s_nop 1
	v_add_f32_dpp v52, v52, v52 row_mirror row_mask:0xf bank_mask:0xf
	s_nop 1
	v_add_f32_dpp v52, v52, v52 row_bcast:15 row_mask:0xa bank_mask:0xf
	s_nop 1
	v_add_f32_dpp v52, v52, v52 row_bcast:31 row_mask:0xc bank_mask:0xf
	s_mov_b32 exec_lo, 0
	s_brev_b32 exec_hi, 1
	global_atomic_add_f32 v7, v52, s[4:5]
	s_mov_b64 exec, -1
.Lp5v_skip0:
	s_add_u32 s10, s8, s23
	s_min_u32 s10, s10, s13
	s_lshl_b32 s11, s10, 10
	v_add_u32_e32 v5, s11, v2
	global_load_dwordx4 a[0:3], v5, s[4:5] offset:0
	global_load_dwordx4 a[4:7], v5, s[4:5] offset:16
	global_load_dwordx4 a[8:11], v5, s[4:5] offset:32
	global_load_dwordx4 a[12:15], v5, s[4:5] offset:48
	global_load_dwordx4 a[16:19], v5, s[4:5] offset:64
	global_load_dwordx4 a[20:23], v5, s[4:5] offset:80
	global_load_dwordx4 a[24:27], v5, s[4:5] offset:96
	global_load_dwordx4 a[28:31], v5, s[4:5] offset:112
	s_lshl_b32 s11, s10, 12
	v_add_u32_e32 v6, s11, v3
	global_load_dwordx2 a[68:69], v6, s[6:7]
	v_accvgpr_read_b32 v10, a196
	v_add_u32_e32 v10, v10, v1
	global_load_dwordx4 v[64:67], v10, s[2:3]
	v_accvgpr_read_b32 v11, a198
	v_add_u32_e32 v11, v11, v1
	global_load_dwordx4 v[68:71], v11, s[2:3]
	v_accvgpr_read_b32 v12, a200
	v_add_u32_e32 v12, v12, v1
	global_load_dwordx4 v[72:75], v12, s[2:3]
	v_accvgpr_read_b32 v13, a202
	v_add_u32_e32 v13, v13, v1
	global_load_dwordx4 v[76:79], v13, s[2:3]
	v_accvgpr_read_b32 v10, a204
	v_add_u32_e32 v10, v10, v1
	global_load_dwordx4 v[80:83], v10, s[2:3]
	v_accvgpr_read_b32 v11, a206
	v_add_u32_e32 v11, v11, v1
	global_load_dwordx4 v[84:87], v11, s[2:3]
	v_accvgpr_read_b32 v12, a208
	v_add_u32_e32 v12, v12, v1
	global_load_dwordx4 v[88:91], v12, s[2:3]
	v_accvgpr_read_b32 v13, a210
	v_add_u32_e32 v13, v13, v1
	global_load_dwordx4 v[92:95], v13, s[2:3]
	v_accvgpr_read_b32 v10, a212
	v_add_u32_e32 v10, v10, v1
	global_load_dwordx4 v[96:99], v10, s[2:3]
	v_accvgpr_read_b32 v11, a214
	v_add_u32_e32 v11, v11, v1
	global_load_dwordx4 v[100:103], v11, s[2:3]
	v_accvgpr_read_b32 v12, a216
	v_add_u32_e32 v12, v12, v1
	global_load_dwordx4 v[104:107], v12, s[2:3]
	v_accvgpr_read_b32 v13, a218
	v_add_u32_e32 v13, v13, v1
	global_load_dwordx4 v[108:111], v13, s[2:3]
	v_accvgpr_read_b32 v10, a220
	v_add_u32_e32 v10, v10, v1
	global_load_dwordx4 v[112:115], v10, s[2:3]
	v_accvgpr_read_b32 v11, a222
	v_add_u32_e32 v11, v11, v1
	global_load_dwordx4 v[116:119], v11, s[2:3]
	v_accvgpr_read_b32 v12, a224
	v_add_u32_e32 v12, v12, v1
	global_load_dwordx4 v[120:123], v12, s[2:3]
	v_accvgpr_read_b32 v13, a226
	v_add_u32_e32 v13, v13, v1
	global_load_dwordx4 v[124:127], v13, s[2:3]
	s_add_u32 s12, s8, s20
	s_waitcnt vmcnt(27)
	s_cmp_lt_u32 s12, 0x4200
	s_cbranch_scc0 .Lp5v_skip1
	v_accvgpr_read_b32 v40, a33
	v_cvt_pk_f32_fp8_e32 v[32:33], v128
	v_cvt_pk_f32_fp8_sdwa v[34:35], v128 src0_sel:WORD_1
	v_pk_mul_f32 v[16:17], v[32:33], v[40:41] op_sel_hi:[1,0]
	v_pk_mul_f32 v[18:19], v[34:35], v[40:41] op_sel_hi:[1,0]
	v_cvt_pk_f32_fp8_e32 v[36:37], v129
	v_cvt_pk_f32_fp8_sdwa v[38:39], v129 src0_sel:WORD_1
	v_pk_mul_f32 v[20:21], v[36:37], v[40:41] op_sel_hi:[1,0]
	v_pk_mul_f32 v[22:23], v[38:39], v[40:41] op_sel_hi:[1,0]
	v_cvt_pk_f32_fp8_e32 v[32:33], v130
	v_cvt_pk_f32_fp8_sdwa v[34:35], v130 src0_sel:WORD_1
	v_pk_mul_f32 v[24:25], v[32:33], v[40:41] op_sel_hi:[1,0]
	v_pk_mul_f32 v[26:27], v[34:35], v[40:41] op_sel_hi:[1,0]
	v_cvt_pk_f32_fp8_e32 v[36:37], v131
	v_cvt_pk_f32_fp8_sdwa v[38:39], v131 src0_sel:WORD_1
	v_pk_mul_f32 v[28:29], v[36:37], v[40:41] op_sel_hi:[1,0]
	v_pk_mul_f32 v[30:31], v[38:39], v[40:41] op_sel_hi:[1,0]
	v_accvgpr_read_b32 v42, a35
	v_cvt_pk_f32_fp8_e32 v[32:33], v132
	v_cvt_pk_f32_fp8_sdwa v[34:35], v132 src0_sel:WORD_1
	v_pk_fma_f32 v[16:17], v[32:33], v[42:43], v[16:17] op_sel_hi:[1,0,1]
	v_pk_fma_f32 v[18:19], v[34:35], v[42:43], v[18:19] op_sel_hi:[1,0,1]
	v_cvt_pk_f32_fp8_e32 v[36:37], v133
	v_cvt_pk_f32_fp8_sdwa v[38:39], v133 src0_sel:WORD_1
	v_pk_fma_f32 v[20:21], v[36:37], v[42:43], v[20:21] op_sel_hi:[1,0,1]
	v_pk_fma_f32 v[22:23], v[38:39], v[42:43], v[22:23] op_sel_hi:[1,0,1]
	v_cvt_pk_f32_fp8_e32 v[32:33], v134
	v_cvt_pk_f32_fp8_sdwa v[34:35], v134 src0_sel:WORD_1
	v_pk_fma_f32 v[24:25], v[32:33], v[42:43], v[24:25] op_sel_hi:[1,0,1]
	v_pk_fma_f32 v[26:27], v[34:35], v[42:43], v[26:27] op_sel_hi:[1,0,1]
	v_cvt_pk_f32_fp8_e32 v[36:37], v135
	v_cvt_pk_f32_fp8_sdwa v[38:39], v135 src0_sel:WORD_1
	v_pk_fma_f32 v[28:29], v[36:37], v[42:43], v[28:29] op_sel_hi:[1,0,1]
	v_pk_fma_f32 v[30:31], v[38:39], v[42:43], v[30:31] op_sel_hi:[1,0,1]
	v_accvgpr_read_b32 v40, a37
	v_cvt_pk_f32_fp8_e32 v[32:33], v136
	v_cvt_pk_f32_fp8_sdwa v[34:35], v136 src0_sel:WORD_1
	v_pk_fma_f32 v[16:17], v[32:33], v[40:41], v[16:17] op_sel_hi:[1,0,1]
	v_pk_fma_f32 v[18:19], v[34:35], v[40:41], v[18:19] op_sel_hi:[1,0,1]
	v_cvt_pk_f32_fp8_e32 v[36:37], v137
	v_cvt_pk_f32_fp8_sdwa v[38:39], v137 src0_sel:WORD_1
	v_pk_fma_f32 v[20:21], v[36:37], v[40:41], v[20:21] op_sel_hi:[1,0,1]
	v_pk_fma_f32 v[22:23], v[38:39], v[40:41], v[22:23] op_sel_hi:[1,0,1]
	v_cvt_pk_f32_fp8_e32 v[32:33], v138
	v_cvt_pk_f32_fp8_sdwa v[34:35], v138 src0_sel:WORD_1
	v_pk_fma_f32 v[24:25], v[32:33], v[40:41], v[24:25] op_sel_hi:[1,0,1]
	v_pk_fma_f32 v[26:27], v[34:35], v[40:41], v[26:27] op_sel_hi:[1,0,1]
	v_cvt_pk_f32_fp8_e32 v[36:37], v139
	v_cvt_pk_f32_fp8_sdwa v[38:39], v139 src0_sel:WORD_1
	v_pk_fma_f32 v[28:29], v[36:37], v[40:41], v[28:29] op_sel_hi:[1,0,1]
	v_pk_fma_f32 v[30:31], v[38:39], v[40:41], v[30:31] op_sel_hi:[1,0,1]
	v_accvgpr_read_b32 v42, a39
	v_cvt_pk_f32_fp8_e32 v[32:33], v140
	v_cvt_pk_f32_fp8_sdwa v[34:35], v140 src0_sel:WORD_1
	v_pk_fma_f32 v[16:17], v[32:33], v[42:43], v[16:17] op_sel_hi:[1,0,1]
	v_pk_fma_f32 v[18:19], v[34:35], v[42:43], v[18:19] op_sel_hi:[1,0,1]
	v_cvt_pk_f32_fp8_e32 v[36:37], v141
	v_cvt_pk_f32_fp8_sdwa v[38:39], v141 src0_sel:WORD_1
	v_pk_fma_f32 v[20:21], v[36:37], v[42:43], v[20:21] op_sel_hi:[1,0,1]
	v_pk_fma_f32 v[22:23], v[38:39], v[42:43], v[22:23] op_sel_hi:[1,0,1]
	v_cvt_pk_f32_fp8_e32 v[32:33], v142
	v_cvt_pk_f32_fp8_sdwa v[34:35], v142 src0_sel:WORD_1
	v_pk_fma_f32 v[24:25], v[32:33], v[42:43], v[24:25] op_sel_hi:[1,0,1]
	v_pk_fma_f32 v[26:27], v[34:35], v[42:43], v[26:27] op_sel_hi:[1,0,1]
	v_cvt_pk_f32_fp8_e32 v[36:37], v143
	v_cvt_pk_f32_fp8_sdwa v[38:39], v143 src0_sel:WORD_1
	v_pk_fma_f32 v[28:29], v[36:37], v[42:43], v[28:29] op_sel_hi:[1,0,1]
	v_pk_fma_f32 v[30:31], v[38:39], v[42:43], v[30:31] op_sel_hi:[1,0,1]
	v_accvgpr_read_b32 v40, a41
	v_cvt_pk_f32_fp8_e32 v[32:33], v144
	v_cvt_pk_f32_fp8_sdwa v[34:35], v144 src0_sel:WORD_1
	v_pk_fma_f32 v[16:17], v[32:33], v[40:41], v[16:17] op_sel_hi:[1,0,1]
	v_pk_fma_f32 v[18:19], v[34:35], v[40:41], v[18:19] op_sel_hi:[1,0,1]
	v_cvt_pk_f32_fp8_e32 v[36:37], v145
	v_cvt_pk_f32_fp8_sdwa v[38:39], v145 src0_sel:WORD_1
	v_pk_fma_f32 v[20:21], v[36:37], v[40:41], v[20:21] op_sel_hi:[1,0,1]
	v_pk_fma_f32 v[22:23], v[38:39], v[40:41], v[22:23] op_sel_hi:[1,0,1]
	v_cvt_pk_f32_fp8_e32 v[32:33], v146
	v_cvt_pk_f32_fp8_sdwa v[34:35], v146 src0_sel:WORD_1
	v_pk_fma_f32 v[24:25], v[32:33], v[40:41], v[24:25] op_sel_hi:[1,0,1]
	v_pk_fma_f32 v[26:27], v[34:35], v[40:41], v[26:27] op_sel_hi:[1,0,1]
	v_cvt_pk_f32_fp8_e32 v[36:37], v147
	v_cvt_pk_f32_fp8_sdwa v[38:39], v147 src0_sel:WORD_1
	v_pk_fma_f32 v[28:29], v[36:37], v[40:41], v[28:29] op_sel_hi:[1,0,1]
	v_pk_fma_f32 v[30:31], v[38:39], v[40:41], v[30:31] op_sel_hi:[1,0,1]
	v_accvgpr_read_b32 v42, a43
	v_cvt_pk_f32_fp8_e32 v[32:33], v148
	v_cvt_pk_f32_fp8_sdwa v[34:35], v148 src0_sel:WORD_1
	v_pk_fma_f32 v[16:17], v[32:33], v[42:43], v[16:17] op_sel_hi:[1,0,1]
	v_pk_fma_f32 v[18:19], v[34:35], v[42:43], v[18:19] op_sel_hi:[1,0,1]
	v_cvt_pk_f32_fp8_e32 v[36:37], v149
	v_cvt_pk_f32_fp8_sdwa v[38:39], v149 src0_sel:WORD_1
	v_pk_fma_f32 v[20:21], v[36:37], v[42:43], v[20:21] op_sel_hi:[1,0,1]
	v_pk_fma_f32 v[22:23], v[38:39], v[42:43], v[22:23] op_sel_hi:[1,0,1]
	v_cvt_pk_f32_fp8_e32 v[32:33], v150
	v_cvt_pk_f32_fp8_sdwa v[34:35], v150 src0_sel:WORD_1
	v_pk_fma_f32 v[24:25], v[32:33], v[42:43], v[24:25] op_sel_hi:[1,0,1]
	v_pk_fma_f32 v[26:27], v[34:35], v[42:43], v[26:27] op_sel_hi:[1,0,1]
	v_cvt_pk_f32_fp8_e32 v[36:37], v151
	v_cvt_pk_f32_fp8_sdwa v[38:39], v151 src0_sel:WORD_1
	v_pk_fma_f32 v[28:29], v[36:37], v[42:43], v[28:29] op_sel_hi:[1,0,1]
	v_pk_fma_f32 v[30:31], v[38:39], v[42:43], v[30:31] op_sel_hi:[1,0,1]
	v_accvgpr_read_b32 v40, a45
	v_cvt_pk_f32_fp8_e32 v[32:33], v152
	v_cvt_pk_f32_fp8_sdwa v[34:35], v152 src0_sel:WORD_1
	v_pk_fma_f32 v[16:17], v[32:33], v[40:41], v[16:17] op_sel_hi:[1,0,1]
	v_pk_fma_f32 v[18:19], v[34:35], v[40:41], v[18:19] op_sel_hi:[1,0,1]
	v_cvt_pk_f32_fp8_e32 v[36:37], v153
	v_cvt_pk_f32_fp8_sdwa v[38:39], v153 src0_sel:WORD_1
	v_pk_fma_f32 v[20:21], v[36:37], v[40:41], v[20:21] op_sel_hi:[1,0,1]
	v_pk_fma_f32 v[22:23], v[38:39], v[40:41], v[22:23] op_sel_hi:[1,0,1]
	v_cvt_pk_f32_fp8_e32 v[32:33], v154
	v_cvt_pk_f32_fp8_sdwa v[34:35], v154 src0_sel:WORD_1
	v_pk_fma_f32 v[24:25], v[32:33], v[40:41], v[24:25] op_sel_hi:[1,0,1]
	v_pk_fma_f32 v[26:27], v[34:35], v[40:41], v[26:27] op_sel_hi:[1,0,1]
	v_cvt_pk_f32_fp8_e32 v[36:37], v155
	v_cvt_pk_f32_fp8_sdwa v[38:39], v155 src0_sel:WORD_1
	v_pk_fma_f32 v[28:29], v[36:37], v[40:41], v[28:29] op_sel_hi:[1,0,1]
	v_pk_fma_f32 v[30:31], v[38:39], v[40:41], v[30:31] op_sel_hi:[1,0,1]
	v_accvgpr_read_b32 v42, a47
	v_cvt_pk_f32_fp8_e32 v[32:33], v156
	v_cvt_pk_f32_fp8_sdwa v[34:35], v156 src0_sel:WORD_1
	v_pk_fma_f32 v[16:17], v[32:33], v[42:43], v[16:17] op_sel_hi:[1,0,1]
	v_pk_fma_f32 v[18:19], v[34:35], v[42:43], v[18:19] op_sel_hi:[1,0,1]
	v_cvt_pk_f32_fp8_e32 v[36:37], v157
	v_cvt_pk_f32_fp8_sdwa v[38:39], v157 src0_sel:WORD_1
	v_pk_fma_f32 v[20:21], v[36:37], v[42:43], v[20:21] op_sel_hi:[1,0,1]
	v_pk_fma_f32 v[22:23], v[38:39], v[42:43], v[22:23] op_sel_hi:[1,0,1]
	v_cvt_pk_f32_fp8_e32 v[32:33], v158
	v_cvt_pk_f32_fp8_sdwa v[34:35], v158 src0_sel:WORD_1
	v_pk_fma_f32 v[24:25], v[32:33], v[42:43], v[24:25] op_sel_hi:[1,0,1]
	v_pk_fma_f32 v[26:27], v[34:35], v[42:43], v[26:27] op_sel_hi:[1,0,1]
	v_cvt_pk_f32_fp8_e32 v[36:37], v159
	v_cvt_pk_f32_fp8_sdwa v[38:39], v159 src0_sel:WORD_1
	v_pk_fma_f32 v[28:29], v[36:37], v[42:43], v[28:29] op_sel_hi:[1,0,1]
	v_pk_fma_f32 v[30:31], v[38:39], v[42:43], v[30:31] op_sel_hi:[1,0,1]
	v_accvgpr_read_b32 v40, a49
	v_cvt_pk_f32_fp8_e32 v[32:33], v160
	v_cvt_pk_f32_fp8_sdwa v[34:35], v160 src0_sel:WORD_1
	v_pk_fma_f32 v[16:17], v[32:33], v[40:41], v[16:17] op_sel_hi:[1,0,1]
	v_pk_fma_f32 v[18:19], v[34:35], v[40:41], v[18:19] op_sel_hi:[1,0,1]
	v_cvt_pk_f32_fp8_e32 v[36:37], v161
	v_cvt_pk_f32_fp8_sdwa v[38:39], v161 src0_sel:WORD_1
	v_pk_fma_f32 v[20:21], v[36:37], v[40:41], v[20:21] op_sel_hi:[1,0,1]
	v_pk_fma_f32 v[22:23], v[38:39], v[40:41], v[22:23] op_sel_hi:[1,0,1]
	v_cvt_pk_f32_fp8_e32 v[32:33], v162
	v_cvt_pk_f32_fp8_sdwa v[34:35], v162 src0_sel:WORD_1
	v_pk_fma_f32 v[24:25], v[32:33], v[40:41], v[24:25] op_sel_hi:[1,0,1]
	v_pk_fma_f32 v[26:27], v[34:35], v[40:41], v[26:27] op_sel_hi:[1,0,1]
	v_cvt_pk_f32_fp8_e32 v[36:37], v163
	v_cvt_pk_f32_fp8_sdwa v[38:39], v163 src0_sel:WORD_1
	v_pk_fma_f32 v[28:29], v[36:37], v[40:41], v[28:29] op_sel_hi:[1,0,1]
	v_pk_fma_f32 v[30:31], v[38:39], v[40:41], v[30:31] op_sel_hi:[1,0,1]
	v_accvgpr_read_b32 v42, a51
	v_cvt_pk_f32_fp8_e32 v[32:33], v164
	v_cvt_pk_f32_fp8_sdwa v[34:35], v164 src0_sel:WORD_1
	v_pk_fma_f32 v[16:17], v[32:33], v[42:43], v[16:17] op_sel_hi:[1,0,1]
	v_pk_fma_f32 v[18:19], v[34:35], v[42:43], v[18:19] op_sel_hi:[1,0,1]
	v_cvt_pk_f32_fp8_e32 v[36:37], v165
	v_cvt_pk_f32_fp8_sdwa v[38:39], v165 src0_sel:WORD_1
	v_pk_fma_f32 v[20:21], v[36:37], v[42:43], v[20:21] op_sel_hi:[1,0,1]
	v_pk_fma_f32 v[22:23], v[38:39], v[42:43], v[22:23] op_sel_hi:[1,0,1]
	v_cvt_pk_f32_fp8_e32 v[32:33], v166
	v_cvt_pk_f32_fp8_sdwa v[34:35], v166 src0_sel:WORD_1
	v_pk_fma_f32 v[24:25], v[32:33], v[42:43], v[24:25] op_sel_hi:[1,0,1]
	v_pk_fma_f32 v[26:27], v[34:35], v[42:43], v[26:27] op_sel_hi:[1,0,1]
	v_cvt_pk_f32_fp8_e32 v[36:37], v167
	v_cvt_pk_f32_fp8_sdwa v[38:39], v167 src0_sel:WORD_1
	v_pk_fma_f32 v[28:29], v[36:37], v[42:43], v[28:29] op_sel_hi:[1,0,1]
	v_pk_fma_f32 v[30:31], v[38:39], v[42:43], v[30:31] op_sel_hi:[1,0,1]
	v_accvgpr_read_b32 v40, a53
	v_cvt_pk_f32_fp8_e32 v[32:33], v168
	v_cvt_pk_f32_fp8_sdwa v[34:35], v168 src0_sel:WORD_1
	v_pk_fma_f32 v[16:17], v[32:33], v[40:41], v[16:17] op_sel_hi:[1,0,1]
	v_pk_fma_f32 v[18:19], v[34:35], v[40:41], v[18:19] op_sel_hi:[1,0,1]
	v_cvt_pk_f32_fp8_e32 v[36:37], v169
	v_cvt_pk_f32_fp8_sdwa v[38:39], v169 src0_sel:WORD_1
	v_pk_fma_f32 v[20:21], v[36:37], v[40:41], v[20:21] op_sel_hi:[1,0,1]
	v_pk_fma_f32 v[22:23], v[38:39], v[40:41], v[22:23] op_sel_hi:[1,0,1]
	v_cvt_pk_f32_fp8_e32 v[32:33], v170
	v_cvt_pk_f32_fp8_sdwa v[34:35], v170 src0_sel:WORD_1
	v_pk_fma_f32 v[24:25], v[32:33], v[40:41], v[24:25] op_sel_hi:[1,0,1]
	v_pk_fma_f32 v[26:27], v[34:35], v[40:41], v[26:27] op_sel_hi:[1,0,1]
	v_cvt_pk_f32_fp8_e32 v[36:37], v171
	v_cvt_pk_f32_fp8_sdwa v[38:39], v171 src0_sel:WORD_1
	v_pk_fma_f32 v[28:29], v[36:37], v[40:41], v[28:29] op_sel_hi:[1,0,1]
	v_pk_fma_f32 v[30:31], v[38:39], v[40:41], v[30:31] op_sel_hi:[1,0,1]
	v_accvgpr_read_b32 v42, a55
	v_cvt_pk_f32_fp8_e32 v[32:33], v172
	v_cvt_pk_f32_fp8_sdwa v[34:35], v172 src0_sel:WORD_1
	v_pk_fma_f32 v[16:17], v[32:33], v[42:43], v[16:17] op_sel_hi:[1,0,1]
	v_pk_fma_f32 v[18:19], v[34:35], v[42:43], v[18:19] op_sel_hi:[1,0,1]
	v_cvt_pk_f32_fp8_e32 v[36:37], v173
	v_cvt_pk_f32_fp8_sdwa v[38:39], v173 src0_sel:WORD_1
	v_pk_fma_f32 v[20:21], v[36:37], v[42:43], v[20:21] op_sel_hi:[1,0,1]
	v_pk_fma_f32 v[22:23], v[38:39], v[42:43], v[22:23] op_sel_hi:[1,0,1]
	v_cvt_pk_f32_fp8_e32 v[32:33], v174
	v_cvt_pk_f32_fp8_sdwa v[34:35], v174 src0_sel:WORD_1
	v_pk_fma_f32 v[24:25], v[32:33], v[42:43], v[24:25] op_sel_hi:[1,0,1]
	v_pk_fma_f32 v[26:27], v[34:35], v[42:43], v[26:27] op_sel_hi:[1,0,1]
	v_cvt_pk_f32_fp8_e32 v[36:37], v175
	v_cvt_pk_f32_fp8_sdwa v[38:39], v175 src0_sel:WORD_1
; __device__ __forceinline__ float wsum(float v) { v = dpp_row_sum16(v); v += __shfl_xor(v, 16); v += __shfl_xor(v, 32); return v; }
; __device__ __forceinline__ void phase5(const Params& p, char* smem, const bool store_x = true) {
;     ...
;     float x2[16];
; #pragma unroll
;     for (int i = 0; i < 4; i++) {
;       const float4 xv = i == 0 ? xv0 : i == 1 ? xv1 : i == 2 ? xv2 : xv3;
;       x2[4 * i] = xv.x + o2[2 * i].x; x2[4 * i + 1] = xv.y + o2[2 * i].y; x2[4 * i + 2] = xv.z + o2[2 * i + 1].x; x2[4 * i + 3] = xv.w + o2[2 * i + 1].y;
;     }
;     float ss = 0.f;
; #pragma unroll
;     for (int i = 0; i < 16; i++) ss += x2[i] * x2[i];
;     ss = wsum(ss);
;     const float rs = rsqrtf(ss * (1.f / 1024.f) + EPSF);
;     if (store_x) {
; #pragma unroll
;       for (int i = 0; i < 4; i++) *(float4*)(xr + i * 4) = make_float4(x2[4 * i], x2[4 * i + 1], x2[4 * i + 2], x2[4 * i + 3]);
;     }
	v_pk_fma_f32 v[28:29], v[36:37], v[42:43], v[28:29] op_sel_hi:[1,0,1]
	v_pk_fma_f32 v[30:31], v[38:39], v[42:43], v[30:31] op_sel_hi:[1,0,1]
	v_accvgpr_read_b32 v40, a57
	v_cvt_pk_f32_fp8_e32 v[32:33], v176
	v_cvt_pk_f32_fp8_sdwa v[34:35], v176 src0_sel:WORD_1
	v_pk_fma_f32 v[16:17], v[32:33], v[40:41], v[16:17] op_sel_hi:[1,0,1]
	v_pk_fma_f32 v[18:19], v[34:35], v[40:41], v[18:19] op_sel_hi:[1,0,1]
	v_cvt_pk_f32_fp8_e32 v[36:37], v177
	v_cvt_pk_f32_fp8_sdwa v[38:39], v177 src0_sel:WORD_1
	v_pk_fma_f32 v[20:21], v[36:37], v[40:41], v[20:21] op_sel_hi:[1,0,1]
	v_pk_fma_f32 v[22:23], v[38:39], v[40:41], v[22:23] op_sel_hi:[1,0,1]
	v_cvt_pk_f32_fp8_e32 v[32:33], v178
	v_cvt_pk_f32_fp8_sdwa v[34:35], v178 src0_sel:WORD_1
	v_pk_fma_f32 v[24:25], v[32:33], v[40:41], v[24:25] op_sel_hi:[1,0,1]
	v_pk_fma_f32 v[26:27], v[34:35], v[40:41], v[26:27] op_sel_hi:[1,0,1]
	v_cvt_pk_f32_fp8_e32 v[36:37], v179
	v_cvt_pk_f32_fp8_sdwa v[38:39], v179 src0_sel:WORD_1
	v_pk_fma_f32 v[28:29], v[36:37], v[40:41], v[28:29] op_sel_hi:[1,0,1]
	v_pk_fma_f32 v[30:31], v[38:39], v[40:41], v[30:31] op_sel_hi:[1,0,1]
	v_accvgpr_read_b32 v42, a59
	v_cvt_pk_f32_fp8_e32 v[32:33], v180
	v_cvt_pk_f32_fp8_sdwa v[34:35], v180 src0_sel:WORD_1
	v_pk_fma_f32 v[16:17], v[32:33], v[42:43], v[16:17] op_sel_hi:[1,0,1]
	v_pk_fma_f32 v[18:19], v[34:35], v[42:43], v[18:19] op_sel_hi:[1,0,1]
	v_cvt_pk_f32_fp8_e32 v[36:37], v181
	v_cvt_pk_f32_fp8_sdwa v[38:39], v181 src0_sel:WORD_1
	v_pk_fma_f32 v[20:21], v[36:37], v[42:43], v[20:21] op_sel_hi:[1,0,1]
	v_pk_fma_f32 v[22:23], v[38:39], v[42:43], v[22:23] op_sel_hi:[1,0,1]
	v_cvt_pk_f32_fp8_e32 v[32:33], v182
	v_cvt_pk_f32_fp8_sdwa v[34:35], v182 src0_sel:WORD_1
	v_pk_fma_f32 v[24:25], v[32:33], v[42:43], v[24:25] op_sel_hi:[1,0,1]
	v_pk_fma_f32 v[26:27], v[34:35], v[42:43], v[26:27] op_sel_hi:[1,0,1]
	v_cvt_pk_f32_fp8_e32 v[36:37], v183
	v_cvt_pk_f32_fp8_sdwa v[38:39], v183 src0_sel:WORD_1
	v_pk_fma_f32 v[28:29], v[36:37], v[42:43], v[28:29] op_sel_hi:[1,0,1]
	v_pk_fma_f32 v[30:31], v[38:39], v[42:43], v[30:31] op_sel_hi:[1,0,1]
	v_accvgpr_read_b32 v40, a61
	v_cvt_pk_f32_fp8_e32 v[32:33], v184
	v_cvt_pk_f32_fp8_sdwa v[34:35], v184 src0_sel:WORD_1
	v_pk_fma_f32 v[16:17], v[32:33], v[40:41], v[16:17] op_sel_hi:[1,0,1]
	v_pk_fma_f32 v[18:19], v[34:35], v[40:41], v[18:19] op_sel_hi:[1,0,1]
	v_cvt_pk_f32_fp8_e32 v[36:37], v185
	v_cvt_pk_f32_fp8_sdwa v[38:39], v185 src0_sel:WORD_1
	v_pk_fma_f32 v[20:21], v[36:37], v[40:41], v[20:21] op_sel_hi:[1,0,1]
	v_pk_fma_f32 v[22:23], v[38:39], v[40:41], v[22:23] op_sel_hi:[1,0,1]
	v_cvt_pk_f32_fp8_e32 v[32:33], v186
	v_cvt_pk_f32_fp8_sdwa v[34:35], v186 src0_sel:WORD_1
	v_pk_fma_f32 v[24:25], v[32:33], v[40:41], v[24:25] op_sel_hi:[1,0,1]
	v_pk_fma_f32 v[26:27], v[34:35], v[40:41], v[26:27] op_sel_hi:[1,0,1]
	v_cvt_pk_f32_fp8_e32 v[36:37], v187
	v_cvt_pk_f32_fp8_sdwa v[38:39], v187 src0_sel:WORD_1
	v_pk_fma_f32 v[28:29], v[36:37], v[40:41], v[28:29] op_sel_hi:[1,0,1]
	v_pk_fma_f32 v[30:31], v[38:39], v[40:41], v[30:31] op_sel_hi:[1,0,1]
	v_accvgpr_read_b32 v42, a63
	v_cvt_pk_f32_fp8_e32 v[32:33], v188
	v_cvt_pk_f32_fp8_sdwa v[34:35], v188 src0_sel:WORD_1
	v_pk_fma_f32 v[16:17], v[32:33], v[42:43], v[16:17] op_sel_hi:[1,0,1]
	v_pk_fma_f32 v[18:19], v[34:35], v[42:43], v[18:19] op_sel_hi:[1,0,1]
	v_cvt_pk_f32_fp8_e32 v[36:37], v189
	v_cvt_pk_f32_fp8_sdwa v[38:39], v189 src0_sel:WORD_1
	v_pk_fma_f32 v[20:21], v[36:37], v[42:43], v[20:21] op_sel_hi:[1,0,1]
	v_pk_fma_f32 v[22:23], v[38:39], v[42:43], v[22:23] op_sel_hi:[1,0,1]
	v_cvt_pk_f32_fp8_e32 v[32:33], v190
	v_cvt_pk_f32_fp8_sdwa v[34:35], v190 src0_sel:WORD_1
	v_pk_fma_f32 v[24:25], v[32:33], v[42:43], v[24:25] op_sel_hi:[1,0,1]
	v_pk_fma_f32 v[26:27], v[34:35], v[42:43], v[26:27] op_sel_hi:[1,0,1]
	v_cvt_pk_f32_fp8_e32 v[36:37], v191
	v_cvt_pk_f32_fp8_sdwa v[38:39], v191 src0_sel:WORD_1
	v_pk_fma_f32 v[28:29], v[36:37], v[42:43], v[28:29] op_sel_hi:[1,0,1]
	v_pk_fma_f32 v[30:31], v[38:39], v[42:43], v[30:31] op_sel_hi:[1,0,1]
	s_nop 1
	v_permlane32_swap_b32_e32 v16, v24
	v_permlane32_swap_b32_e32 v17, v25
	v_permlane32_swap_b32_e32 v18, v26
	v_permlane32_swap_b32_e32 v19, v27
	v_permlane32_swap_b32_e32 v20, v28
	v_permlane32_swap_b32_e32 v21, v29
	v_permlane32_swap_b32_e32 v22, v30
	v_permlane32_swap_b32_e32 v23, v31
	v_add_f32_e32 v16, v16, v24
	v_add_f32_e32 v17, v17, v25
	v_add_f32_e32 v18, v18, v26
	v_add_f32_e32 v19, v19, v27
	v_add_f32_e32 v20, v20, v28
	v_add_f32_e32 v21, v21, v29
	v_add_f32_e32 v22, v22, v30
	v_add_f32_e32 v23, v23, v31
	s_nop 1
	v_permlane16_swap_b32_e32 v16, v20
	v_permlane16_swap_b32_e32 v17, v21
	v_permlane16_swap_b32_e32 v18, v22
	v_permlane16_swap_b32_e32 v19, v23
	v_add_f32_e32 v16, v16, v20
	v_add_f32_e32 v17, v17, v21
	v_add_f32_e32 v18, v18, v22
	v_add_f32_e32 v19, v19, v23
	v_accvgpr_read_b32 v50, a70
	v_accvgpr_read_b32 v51, a71
	v_add_f32_dpp v44, v16, v16 row_ror:8 row_mask:0xf bank_mask:0xf
	v_add_f32_dpp v45, v18, v18 row_ror:8 row_mask:0xf bank_mask:0xf
	v_add_f32_dpp v46, v17, v17 row_ror:8 row_mask:0xf bank_mask:0xf
	v_add_f32_dpp v47, v19, v19 row_ror:8 row_mask:0xf bank_mask:0xf
	v_cndmask_b32_e64 v48, v44, v45, s[14:15]
	v_cndmask_b32_e64 v49, v46, v47, s[14:15]
	v_add_f32_e32 v48, v50, v48
	v_add_f32_e32 v49, v51, v49
	s_lshl_b32 s11, s12, 12
	v_add_u32_e32 v6, s11, v3
	global_store_dwordx2 v6, v[48:49], s[6:7]
	v_mul_f32_e32 v52, v48, v48
	v_fmac_f32_e32 v52, v49, v49
	s_lshl_b32 s11, s12, 2
	s_add_u32 s11, s11, 0x1100000
	v_mov_b32_e32 v7, s11
	v_add_f32_dpp v52, v52, v52 quad_perm:[1,0,3,2] row_mask:0xf bank_mask:0xf
	s_nop 1
	v_add_f32_dpp v52, v52, v52 quad_perm:[2,3,0,1] row_mask:0xf bank_mask:0xf
	s_nop 1
	v_add_f32_dpp v52, v52, v52 row_half_mirror row_mask:0xf bank_mask:0xf
	s_nop 1
	v_add_f32_dpp v52, v52, v52 row_mirror row_mask:0xf bank_mask:0xf
	s_nop 1
	v_add_f32_dpp v52, v52, v52 row_bcast:15 row_mask:0xa bank_mask:0xf
	s_nop 1
	v_add_f32_dpp v52, v52, v52 row_bcast:31 row_mask:0xc bank_mask:0xf
	s_mov_b32 exec_lo, 0
	s_brev_b32 exec_hi, 1
	global_atomic_add_f32 v7, v52, s[4:5]
	s_mov_b64 exec, -1
.Lp5v_skip1:
	s_add_u32 s10, s8, s24
	s_min_u32 s10, s10, s13
	s_lshl_b32 s11, s10, 10
	v_add_u32_e32 v5, s11, v2
	global_load_dwordx4 a[32:35], v5, s[4:5] offset:0
	global_load_dwordx4 a[36:39], v5, s[4:5] offset:16
	global_load_dwordx4 a[40:43], v5, s[4:5] offset:32
	global_load_dwordx4 a[44:47], v5, s[4:5] offset:48
	global_load_dwordx4 a[48:51], v5, s[4:5] offset:64
	global_load_dwordx4 a[52:55], v5, s[4:5] offset:80
	global_load_dwordx4 a[56:59], v5, s[4:5] offset:96
	global_load_dwordx4 a[60:63], v5, s[4:5] offset:112
	s_lshl_b32 s11, s10, 12
	v_add_u32_e32 v6, s11, v3
	global_load_dwordx2 a[70:71], v6, s[6:7]
	v_accvgpr_read_b32 v10, a228
	v_add_u32_e32 v10, v10, v1
	global_load_dwordx4 v[128:131], v10, s[2:3]
	v_accvgpr_read_b32 v11, a230
	v_add_u32_e32 v11, v11, v1
	global_load_dwordx4 v[132:135], v11, s[2:3]
	v_accvgpr_read_b32 v12, a232
	v_add_u32_e32 v12, v12, v1
	global_load_dwordx4 v[136:139], v12, s[2:3]
	v_accvgpr_read_b32 v13, a234
	v_add_u32_e32 v13, v13, v1
	global_load_dwordx4 v[140:143], v13, s[2:3]
	v_accvgpr_read_b32 v10, a236
	v_add_u32_e32 v10, v10, v1
	global_load_dwordx4 v[144:147], v10, s[2:3]
	v_accvgpr_read_b32 v11, a238
	v_add_u32_e32 v11, v11, v1
	global_load_dwordx4 v[148:151], v11, s[2:3]
	v_accvgpr_read_b32 v12, a240
	v_add_u32_e32 v12, v12, v1
	global_load_dwordx4 v[152:155], v12, s[2:3]
	v_accvgpr_read_b32 v13, a242
	v_add_u32_e32 v13, v13, v1
	global_load_dwordx4 v[156:159], v13, s[2:3]
	v_accvgpr_read_b32 v10, a244
	v_add_u32_e32 v10, v10, v1
	global_load_dwordx4 v[160:163], v10, s[2:3]
	v_accvgpr_read_b32 v11, a246
	v_add_u32_e32 v11, v11, v1
	global_load_dwordx4 v[164:167], v11, s[2:3]
	v_accvgpr_read_b32 v12, a248
	v_add_u32_e32 v12, v12, v1
	global_load_dwordx4 v[168:171], v12, s[2:3]
	v_accvgpr_read_b32 v13, a250
	v_add_u32_e32 v13, v13, v1
	global_load_dwordx4 v[172:175], v13, s[2:3]
	v_accvgpr_read_b32 v10, a252
	v_add_u32_e32 v10, v10, v1
	global_load_dwordx4 v[176:179], v10, s[2:3]
	v_accvgpr_read_b32 v11, a254
	v_add_u32_e32 v11, v11, v1
	global_load_dwordx4 v[180:183], v11, s[2:3]
	v_accvgpr_read_b32 v12, a64
	v_add_u32_e32 v12, v12, v1
	global_load_dwordx4 v[184:187], v12, s[2:3]
	v_accvgpr_read_b32 v13, a66
	v_add_u32_e32 v13, v13, v1
	global_load_dwordx4 v[188:191], v13, s[2:3]
	s_add_u32 s12, s8, s21
	s_waitcnt vmcnt(27)
	s_cmp_lt_u32 s12, 0x4200
	s_cbranch_scc0 .Lp5v_skip2
	v_accvgpr_read_b32 v40, a197
	v_cvt_pk_f32_fp8_e32 v[32:33], v64
	v_cvt_pk_f32_fp8_sdwa v[34:35], v64 src0_sel:WORD_1
	v_pk_mul_f32 v[16:17], v[32:33], v[40:41] op_sel_hi:[1,0]
	v_pk_mul_f32 v[18:19], v[34:35], v[40:41] op_sel_hi:[1,0]
	v_cvt_pk_f32_fp8_e32 v[36:37], v65
	v_cvt_pk_f32_fp8_sdwa v[38:39], v65 src0_sel:WORD_1
	v_pk_mul_f32 v[20:21], v[36:37], v[40:41] op_sel_hi:[1,0]
	v_pk_mul_f32 v[22:23], v[38:39], v[40:41] op_sel_hi:[1,0]
	v_cvt_pk_f32_fp8_e32 v[32:33], v66
	v_cvt_pk_f32_fp8_sdwa v[34:35], v66 src0_sel:WORD_1
	v_pk_mul_f32 v[24:25], v[32:33], v[40:41] op_sel_hi:[1,0]
	v_pk_mul_f32 v[26:27], v[34:35], v[40:41] op_sel_hi:[1,0]
	v_cvt_pk_f32_fp8_e32 v[36:37], v67
	v_cvt_pk_f32_fp8_sdwa v[38:39], v67 src0_sel:WORD_1
	v_pk_mul_f32 v[28:29], v[36:37], v[40:41] op_sel_hi:[1,0]
	v_pk_mul_f32 v[30:31], v[38:39], v[40:41] op_sel_hi:[1,0]
	v_accvgpr_read_b32 v42, a199
	v_cvt_pk_f32_fp8_e32 v[32:33], v68
	v_cvt_pk_f32_fp8_sdwa v[34:35], v68 src0_sel:WORD_1
	v_pk_fma_f32 v[16:17], v[32:33], v[42:43], v[16:17] op_sel_hi:[1,0,1]
	v_pk_fma_f32 v[18:19], v[34:35], v[42:43], v[18:19] op_sel_hi:[1,0,1]
	v_cvt_pk_f32_fp8_e32 v[36:37], v69
	v_cvt_pk_f32_fp8_sdwa v[38:39], v69 src0_sel:WORD_1
	v_pk_fma_f32 v[20:21], v[36:37], v[42:43], v[20:21] op_sel_hi:[1,0,1]
	v_pk_fma_f32 v[22:23], v[38:39], v[42:43], v[22:23] op_sel_hi:[1,0,1]
	v_cvt_pk_f32_fp8_e32 v[32:33], v70
	v_cvt_pk_f32_fp8_sdwa v[34:35], v70 src0_sel:WORD_1
	v_pk_fma_f32 v[24:25], v[32:33], v[42:43], v[24:25] op_sel_hi:[1,0,1]
	v_pk_fma_f32 v[26:27], v[34:35], v[42:43], v[26:27] op_sel_hi:[1,0,1]
	v_cvt_pk_f32_fp8_e32 v[36:37], v71
	v_cvt_pk_f32_fp8_sdwa v[38:39], v71 src0_sel:WORD_1
	v_pk_fma_f32 v[28:29], v[36:37], v[42:43], v[28:29] op_sel_hi:[1,0,1]
	v_pk_fma_f32 v[30:31], v[38:39], v[42:43], v[30:31] op_sel_hi:[1,0,1]
	v_accvgpr_read_b32 v40, a201
	v_cvt_pk_f32_fp8_e32 v[32:33], v72
	v_cvt_pk_f32_fp8_sdwa v[34:35], v72 src0_sel:WORD_1
	v_pk_fma_f32 v[16:17], v[32:33], v[40:41], v[16:17] op_sel_hi:[1,0,1]
	v_pk_fma_f32 v[18:19], v[34:35], v[40:41], v[18:19] op_sel_hi:[1,0,1]
	v_cvt_pk_f32_fp8_e32 v[36:37], v73
	v_cvt_pk_f32_fp8_sdwa v[38:39], v73 src0_sel:WORD_1
	v_pk_fma_f32 v[20:21], v[36:37], v[40:41], v[20:21] op_sel_hi:[1,0,1]
	v_pk_fma_f32 v[22:23], v[38:39], v[40:41], v[22:23] op_sel_hi:[1,0,1]
	v_cvt_pk_f32_fp8_e32 v[32:33], v74
	v_cvt_pk_f32_fp8_sdwa v[34:35], v74 src0_sel:WORD_1
	v_pk_fma_f32 v[24:25], v[32:33], v[40:41], v[24:25] op_sel_hi:[1,0,1]
	v_pk_fma_f32 v[26:27], v[34:35], v[40:41], v[26:27] op_sel_hi:[1,0,1]
	v_cvt_pk_f32_fp8_e32 v[36:37], v75
	v_cvt_pk_f32_fp8_sdwa v[38:39], v75 src0_sel:WORD_1
	v_pk_fma_f32 v[28:29], v[36:37], v[40:41], v[28:29] op_sel_hi:[1,0,1]
	v_pk_fma_f32 v[30:31], v[38:39], v[40:41], v[30:31] op_sel_hi:[1,0,1]
	v_accvgpr_read_b32 v42, a203
	v_cvt_pk_f32_fp8_e32 v[32:33], v76
	v_cvt_pk_f32_fp8_sdwa v[34:35], v76 src0_sel:WORD_1
	v_pk_fma_f32 v[16:17], v[32:33], v[42:43], v[16:17] op_sel_hi:[1,0,1]
	v_pk_fma_f32 v[18:19], v[34:35], v[42:43], v[18:19] op_sel_hi:[1,0,1]
	v_cvt_pk_f32_fp8_e32 v[36:37], v77
	v_cvt_pk_f32_fp8_sdwa v[38:39], v77 src0_sel:WORD_1
	v_pk_fma_f32 v[20:21], v[36:37], v[42:43], v[20:21] op_sel_hi:[1,0,1]
	v_pk_fma_f32 v[22:23], v[38:39], v[42:43], v[22:23] op_sel_hi:[1,0,1]
	v_cvt_pk_f32_fp8_e32 v[32:33], v78
	v_cvt_pk_f32_fp8_sdwa v[34:35], v78 src0_sel:WORD_1
	v_pk_fma_f32 v[24:25], v[32:33], v[42:43], v[24:25] op_sel_hi:[1,0,1]
	v_pk_fma_f32 v[26:27], v[34:35], v[42:43], v[26:27] op_sel_hi:[1,0,1]
	v_cvt_pk_f32_fp8_e32 v[36:37], v79
	v_cvt_pk_f32_fp8_sdwa v[38:39], v79 src0_sel:WORD_1
	v_pk_fma_f32 v[28:29], v[36:37], v[42:43], v[28:29] op_sel_hi:[1,0,1]
	v_pk_fma_f32 v[30:31], v[38:39], v[42:43], v[30:31] op_sel_hi:[1,0,1]
	v_accvgpr_read_b32 v40, a205
	v_cvt_pk_f32_fp8_e32 v[32:33], v80
	v_cvt_pk_f32_fp8_sdwa v[34:35], v80 src0_sel:WORD_1
	v_pk_fma_f32 v[16:17], v[32:33], v[40:41], v[16:17] op_sel_hi:[1,0,1]
	v_pk_fma_f32 v[18:19], v[34:35], v[40:41], v[18:19] op_sel_hi:[1,0,1]
	v_cvt_pk_f32_fp8_e32 v[36:37], v81
	v_cvt_pk_f32_fp8_sdwa v[38:39], v81 src0_sel:WORD_1
	v_pk_fma_f32 v[20:21], v[36:37], v[40:41], v[20:21] op_sel_hi:[1,0,1]
	v_pk_fma_f32 v[22:23], v[38:39], v[40:41], v[22:23] op_sel_hi:[1,0,1]
	v_cvt_pk_f32_fp8_e32 v[32:33], v82
	v_cvt_pk_f32_fp8_sdwa v[34:35], v82 src0_sel:WORD_1
	v_pk_fma_f32 v[24:25], v[32:33], v[40:41], v[24:25] op_sel_hi:[1,0,1]
	v_pk_fma_f32 v[26:27], v[34:35], v[40:41], v[26:27] op_sel_hi:[1,0,1]
	v_cvt_pk_f32_fp8_e32 v[36:37], v83
	v_cvt_pk_f32_fp8_sdwa v[38:39], v83 src0_sel:WORD_1
	v_pk_fma_f32 v[28:29], v[36:37], v[40:41], v[28:29] op_sel_hi:[1,0,1]
	v_pk_fma_f32 v[30:31], v[38:39], v[40:41], v[30:31] op_sel_hi:[1,0,1]
	v_accvgpr_read_b32 v42, a207
	v_cvt_pk_f32_fp8_e32 v[32:33], v84
	v_cvt_pk_f32_fp8_sdwa v[34:35], v84 src0_sel:WORD_1
	v_pk_fma_f32 v[16:17], v[32:33], v[42:43], v[16:17] op_sel_hi:[1,0,1]
	v_pk_fma_f32 v[18:19], v[34:35], v[42:43], v[18:19] op_sel_hi:[1,0,1]
	v_cvt_pk_f32_fp8_e32 v[36:37], v85
	v_cvt_pk_f32_fp8_sdwa v[38:39], v85 src0_sel:WORD_1
	v_pk_fma_f32 v[20:21], v[36:37], v[42:43], v[20:21] op_sel_hi:[1,0,1]
	v_pk_fma_f32 v[22:23], v[38:39], v[42:43], v[22:23] op_sel_hi:[1,0,1]
	v_cvt_pk_f32_fp8_e32 v[32:33], v86
	v_cvt_pk_f32_fp8_sdwa v[34:35], v86 src0_sel:WORD_1
	v_pk_fma_f32 v[24:25], v[32:33], v[42:43], v[24:25] op_sel_hi:[1,0,1]
	v_pk_fma_f32 v[26:27], v[34:35], v[42:43], v[26:27] op_sel_hi:[1,0,1]
	v_cvt_pk_f32_fp8_e32 v[36:37], v87
	v_cvt_pk_f32_fp8_sdwa v[38:39], v87 src0_sel:WORD_1
	v_pk_fma_f32 v[28:29], v[36:37], v[42:43], v[28:29] op_sel_hi:[1,0,1]
	v_pk_fma_f32 v[30:31], v[38:39], v[42:43], v[30:31] op_sel_hi:[1,0,1]
	v_accvgpr_read_b32 v40, a209
	v_cvt_pk_f32_fp8_e32 v[32:33], v88
	v_cvt_pk_f32_fp8_sdwa v[34:35], v88 src0_sel:WORD_1
	v_pk_fma_f32 v[16:17], v[32:33], v[40:41], v[16:17] op_sel_hi:[1,0,1]
	v_pk_fma_f32 v[18:19], v[34:35], v[40:41], v[18:19] op_sel_hi:[1,0,1]
	v_cvt_pk_f32_fp8_e32 v[36:37], v89
	v_cvt_pk_f32_fp8_sdwa v[38:39], v89 src0_sel:WORD_1
	v_pk_fma_f32 v[20:21], v[36:37], v[40:41], v[20:21] op_sel_hi:[1,0,1]
	v_pk_fma_f32 v[22:23], v[38:39], v[40:41], v[22:23] op_sel_hi:[1,0,1]
	v_cvt_pk_f32_fp8_e32 v[32:33], v90
	v_cvt_pk_f32_fp8_sdwa v[34:35], v90 src0_sel:WORD_1
	v_pk_fma_f32 v[24:25], v[32:33], v[40:41], v[24:25] op_sel_hi:[1,0,1]
	v_pk_fma_f32 v[26:27], v[34:35], v[40:41], v[26:27] op_sel_hi:[1,0,1]
	v_cvt_pk_f32_fp8_e32 v[36:37], v91
	v_cvt_pk_f32_fp8_sdwa v[38:39], v91 src0_sel:WORD_1
	v_pk_fma_f32 v[28:29], v[36:37], v[40:41], v[28:29] op_sel_hi:[1,0,1]
	v_pk_fma_f32 v[30:31], v[38:39], v[40:41], v[30:31] op_sel_hi:[1,0,1]
	v_accvgpr_read_b32 v42, a211
	v_cvt_pk_f32_fp8_e32 v[32:33], v92
	v_cvt_pk_f32_fp8_sdwa v[34:35], v92 src0_sel:WORD_1
	v_pk_fma_f32 v[16:17], v[32:33], v[42:43], v[16:17] op_sel_hi:[1,0,1]
	v_pk_fma_f32 v[18:19], v[34:35], v[42:43], v[18:19] op_sel_hi:[1,0,1]
	v_cvt_pk_f32_fp8_e32 v[36:37], v93
	v_cvt_pk_f32_fp8_sdwa v[38:39], v93 src0_sel:WORD_1
	v_pk_fma_f32 v[20:21], v[36:37], v[42:43], v[20:21] op_sel_hi:[1,0,1]
	v_pk_fma_f32 v[22:23], v[38:39], v[42:43], v[22:23] op_sel_hi:[1,0,1]
	v_cvt_pk_f32_fp8_e32 v[32:33], v94
	v_cvt_pk_f32_fp8_sdwa v[34:35], v94 src0_sel:WORD_1
	v_pk_fma_f32 v[24:25], v[32:33], v[42:43], v[24:25] op_sel_hi:[1,0,1]
	v_pk_fma_f32 v[26:27], v[34:35], v[42:43], v[26:27] op_sel_hi:[1,0,1]
	v_cvt_pk_f32_fp8_e32 v[36:37], v95
	v_cvt_pk_f32_fp8_sdwa v[38:39], v95 src0_sel:WORD_1
	v_pk_fma_f32 v[28:29], v[36:37], v[42:43], v[28:29] op_sel_hi:[1,0,1]
	v_pk_fma_f32 v[30:31], v[38:39], v[42:43], v[30:31] op_sel_hi:[1,0,1]
	v_accvgpr_read_b32 v40, a213
	v_cvt_pk_f32_fp8_e32 v[32:33], v96
	v_cvt_pk_f32_fp8_sdwa v[34:35], v96 src0_sel:WORD_1
	v_pk_fma_f32 v[16:17], v[32:33], v[40:41], v[16:17] op_sel_hi:[1,0,1]
	v_pk_fma_f32 v[18:19], v[34:35], v[40:41], v[18:19] op_sel_hi:[1,0,1]
	v_cvt_pk_f32_fp8_e32 v[36:37], v97
	v_cvt_pk_f32_fp8_sdwa v[38:39], v97 src0_sel:WORD_1
	v_pk_fma_f32 v[20:21], v[36:37], v[40:41], v[20:21] op_sel_hi:[1,0,1]
	v_pk_fma_f32 v[22:23], v[38:39], v[40:41], v[22:23] op_sel_hi:[1,0,1]
	v_cvt_pk_f32_fp8_e32 v[32:33], v98
	v_cvt_pk_f32_fp8_sdwa v[34:35], v98 src0_sel:WORD_1
	v_pk_fma_f32 v[24:25], v[32:33], v[40:41], v[24:25] op_sel_hi:[1,0,1]
	v_pk_fma_f32 v[26:27], v[34:35], v[40:41], v[26:27] op_sel_hi:[1,0,1]
	v_cvt_pk_f32_fp8_e32 v[36:37], v99
	v_cvt_pk_f32_fp8_sdwa v[38:39], v99 src0_sel:WORD_1
	v_pk_fma_f32 v[28:29], v[36:37], v[40:41], v[28:29] op_sel_hi:[1,0,1]
	v_pk_fma_f32 v[30:31], v[38:39], v[40:41], v[30:31] op_sel_hi:[1,0,1]
	v_accvgpr_read_b32 v42, a215
	v_cvt_pk_f32_fp8_e32 v[32:33], v100
	v_cvt_pk_f32_fp8_sdwa v[34:35], v100 src0_sel:WORD_1
	v_pk_fma_f32 v[16:17], v[32:33], v[42:43], v[16:17] op_sel_hi:[1,0,1]
	v_pk_fma_f32 v[18:19], v[34:35], v[42:43], v[18:19] op_sel_hi:[1,0,1]
	v_cvt_pk_f32_fp8_e32 v[36:37], v101
	v_cvt_pk_f32_fp8_sdwa v[38:39], v101 src0_sel:WORD_1
	v_pk_fma_f32 v[20:21], v[36:37], v[42:43], v[20:21] op_sel_hi:[1,0,1]
	v_pk_fma_f32 v[22:23], v[38:39], v[42:43], v[22:23] op_sel_hi:[1,0,1]
	v_cvt_pk_f32_fp8_e32 v[32:33], v102
	v_cvt_pk_f32_fp8_sdwa v[34:35], v102 src0_sel:WORD_1
	v_pk_fma_f32 v[24:25], v[32:33], v[42:43], v[24:25] op_sel_hi:[1,0,1]
	v_pk_fma_f32 v[26:27], v[34:35], v[42:43], v[26:27] op_sel_hi:[1,0,1]
	v_cvt_pk_f32_fp8_e32 v[36:37], v103
	v_cvt_pk_f32_fp8_sdwa v[38:39], v103 src0_sel:WORD_1
	v_pk_fma_f32 v[28:29], v[36:37], v[42:43], v[28:29] op_sel_hi:[1,0,1]
	v_pk_fma_f32 v[30:31], v[38:39], v[42:43], v[30:31] op_sel_hi:[1,0,1]
	v_accvgpr_read_b32 v40, a217
	v_cvt_pk_f32_fp8_e32 v[32:33], v104
	v_cvt_pk_f32_fp8_sdwa v[34:35], v104 src0_sel:WORD_1
	v_pk_fma_f32 v[16:17], v[32:33], v[40:41], v[16:17] op_sel_hi:[1,0,1]
	v_pk_fma_f32 v[18:19], v[34:35], v[40:41], v[18:19] op_sel_hi:[1,0,1]
	v_cvt_pk_f32_fp8_e32 v[36:37], v105
	v_cvt_pk_f32_fp8_sdwa v[38:39], v105 src0_sel:WORD_1
	v_pk_fma_f32 v[20:21], v[36:37], v[40:41], v[20:21] op_sel_hi:[1,0,1]
	v_pk_fma_f32 v[22:23], v[38:39], v[40:41], v[22:23] op_sel_hi:[1,0,1]
	v_cvt_pk_f32_fp8_e32 v[32:33], v106
	v_cvt_pk_f32_fp8_sdwa v[34:35], v106 src0_sel:WORD_1
	v_pk_fma_f32 v[24:25], v[32:33], v[40:41], v[24:25] op_sel_hi:[1,0,1]
	v_pk_fma_f32 v[26:27], v[34:35], v[40:41], v[26:27] op_sel_hi:[1,0,1]
	v_cvt_pk_f32_fp8_e32 v[36:37], v107
	v_cvt_pk_f32_fp8_sdwa v[38:39], v107 src0_sel:WORD_1
	v_pk_fma_f32 v[28:29], v[36:37], v[40:41], v[28:29] op_sel_hi:[1,0,1]
	v_pk_fma_f32 v[30:31], v[38:39], v[40:41], v[30:31] op_sel_hi:[1,0,1]
	v_accvgpr_read_b32 v42, a219
	v_cvt_pk_f32_fp8_e32 v[32:33], v108
	v_cvt_pk_f32_fp8_sdwa v[34:35], v108 src0_sel:WORD_1
	v_pk_fma_f32 v[16:17], v[32:33], v[42:43], v[16:17] op_sel_hi:[1,0,1]
	v_pk_fma_f32 v[18:19], v[34:35], v[42:43], v[18:19] op_sel_hi:[1,0,1]
	v_cvt_pk_f32_fp8_e32 v[36:37], v109
	v_cvt_pk_f32_fp8_sdwa v[38:39], v109 src0_sel:WORD_1
	v_pk_fma_f32 v[20:21], v[36:37], v[42:43], v[20:21] op_sel_hi:[1,0,1]
	v_pk_fma_f32 v[22:23], v[38:39], v[42:43], v[22:23] op_sel_hi:[1,0,1]
	v_cvt_pk_f32_fp8_e32 v[32:33], v110
	v_cvt_pk_f32_fp8_sdwa v[34:35], v110 src0_sel:WORD_1
	v_pk_fma_f32 v[24:25], v[32:33], v[42:43], v[24:25] op_sel_hi:[1,0,1]
	v_pk_fma_f32 v[26:27], v[34:35], v[42:43], v[26:27] op_sel_hi:[1,0,1]
	v_cvt_pk_f32_fp8_e32 v[36:37], v111
	v_cvt_pk_f32_fp8_sdwa v[38:39], v111 src0_sel:WORD_1
	v_pk_fma_f32 v[28:29], v[36:37], v[42:43], v[28:29] op_sel_hi:[1,0,1]
	v_pk_fma_f32 v[30:31], v[38:39], v[42:43], v[30:31] op_sel_hi:[1,0,1]
	v_accvgpr_read_b32 v40, a221
	v_cvt_pk_f32_fp8_e32 v[32:33], v112
	v_cvt_pk_f32_fp8_sdwa v[34:35], v112 src0_sel:WORD_1
	v_pk_fma_f32 v[16:17], v[32:33], v[40:41], v[16:17] op_sel_hi:[1,0,1]
	v_pk_fma_f32 v[18:19], v[34:35], v[40:41], v[18:19] op_sel_hi:[1,0,1]
	v_cvt_pk_f32_fp8_e32 v[36:37], v113
	v_cvt_pk_f32_fp8_sdwa v[38:39], v113 src0_sel:WORD_1
	v_pk_fma_f32 v[20:21], v[36:37], v[40:41], v[20:21] op_sel_hi:[1,0,1]
	v_pk_fma_f32 v[22:23], v[38:39], v[40:41], v[22:23] op_sel_hi:[1,0,1]
	v_cvt_pk_f32_fp8_e32 v[32:33], v114
	v_cvt_pk_f32_fp8_sdwa v[34:35], v114 src0_sel:WORD_1
	v_pk_fma_f32 v[24:25], v[32:33], v[40:41], v[24:25] op_sel_hi:[1,0,1]
	v_pk_fma_f32 v[26:27], v[34:35], v[40:41], v[26:27] op_sel_hi:[1,0,1]
	v_cvt_pk_f32_fp8_e32 v[36:37], v115
	v_cvt_pk_f32_fp8_sdwa v[38:39], v115 src0_sel:WORD_1
	v_pk_fma_f32 v[28:29], v[36:37], v[40:41], v[28:29] op_sel_hi:[1,0,1]
	v_pk_fma_f32 v[30:31], v[38:39], v[40:41], v[30:31] op_sel_hi:[1,0,1]
	v_accvgpr_read_b32 v42, a223
	v_cvt_pk_f32_fp8_e32 v[32:33], v116
	v_cvt_pk_f32_fp8_sdwa v[34:35], v116 src0_sel:WORD_1
	v_pk_fma_f32 v[16:17], v[32:33], v[42:43], v[16:17] op_sel_hi:[1,0,1]
	v_pk_fma_f32 v[18:19], v[34:35], v[42:43], v[18:19] op_sel_hi:[1,0,1]
	v_cvt_pk_f32_fp8_e32 v[36:37], v117
	v_cvt_pk_f32_fp8_sdwa v[38:39], v117 src0_sel:WORD_1
	v_pk_fma_f32 v[20:21], v[36:37], v[42:43], v[20:21] op_sel_hi:[1,0,1]
	v_pk_fma_f32 v[22:23], v[38:39], v[42:43], v[22:23] op_sel_hi:[1,0,1]
	v_cvt_pk_f32_fp8_e32 v[32:33], v118
	v_cvt_pk_f32_fp8_sdwa v[34:35], v118 src0_sel:WORD_1
	v_pk_fma_f32 v[24:25], v[32:33], v[42:43], v[24:25] op_sel_hi:[1,0,1]
	v_pk_fma_f32 v[26:27], v[34:35], v[42:43], v[26:27] op_sel_hi:[1,0,1]
	v_cvt_pk_f32_fp8_e32 v[36:37], v119
	v_cvt_pk_f32_fp8_sdwa v[38:39], v119 src0_sel:WORD_1
	v_pk_fma_f32 v[28:29], v[36:37], v[42:43], v[28:29] op_sel_hi:[1,0,1]
	v_pk_fma_f32 v[30:31], v[38:39], v[42:43], v[30:31] op_sel_hi:[1,0,1]
	v_accvgpr_read_b32 v40, a225
	v_cvt_pk_f32_fp8_e32 v[32:33], v120
	v_cvt_pk_f32_fp8_sdwa v[34:35], v120 src0_sel:WORD_1
	v_pk_fma_f32 v[16:17], v[32:33], v[40:41], v[16:17] op_sel_hi:[1,0,1]
	v_pk_fma_f32 v[18:19], v[34:35], v[40:41], v[18:19] op_sel_hi:[1,0,1]
	v_cvt_pk_f32_fp8_e32 v[36:37], v121
	v_cvt_pk_f32_fp8_sdwa v[38:39], v121 src0_sel:WORD_1
	v_pk_fma_f32 v[20:21], v[36:37], v[40:41], v[20:21] op_sel_hi:[1,0,1]
	v_pk_fma_f32 v[22:23], v[38:39], v[40:41], v[22:23] op_sel_hi:[1,0,1]
	v_cvt_pk_f32_fp8_e32 v[32:33], v122
	v_cvt_pk_f32_fp8_sdwa v[34:35], v122 src0_sel:WORD_1
	v_pk_fma_f32 v[24:25], v[32:33], v[40:41], v[24:25] op_sel_hi:[1,0,1]
	v_pk_fma_f32 v[26:27], v[34:35], v[40:41], v[26:27] op_sel_hi:[1,0,1]
	v_cvt_pk_f32_fp8_e32 v[36:37], v123
	v_cvt_pk_f32_fp8_sdwa v[38:39], v123 src0_sel:WORD_1
	v_pk_fma_f32 v[28:29], v[36:37], v[40:41], v[28:29] op_sel_hi:[1,0,1]
	v_pk_fma_f32 v[30:31], v[38:39], v[40:41], v[30:31] op_sel_hi:[1,0,1]
	v_accvgpr_read_b32 v42, a227
	v_cvt_pk_f32_fp8_e32 v[32:33], v124
	v_cvt_pk_f32_fp8_sdwa v[34:35], v124 src0_sel:WORD_1
	v_pk_fma_f32 v[16:17], v[32:33], v[42:43], v[16:17] op_sel_hi:[1,0,1]
	v_pk_fma_f32 v[18:19], v[34:35], v[42:43], v[18:19] op_sel_hi:[1,0,1]
	v_cvt_pk_f32_fp8_e32 v[36:37], v125
; __device__ __forceinline__ float wsum(float v) { v = dpp_row_sum16(v); v += __shfl_xor(v, 16); v += __shfl_xor(v, 32); return v; }
; __device__ __forceinline__ void phase5(const Params& p, char* smem, const bool store_x = true) {
;     ...
;     float x2[16];
; #pragma unroll
;     for (int i = 0; i < 4; i++) {
;       const float4 xv = i == 0 ? xv0 : i == 1 ? xv1 : i == 2 ? xv2 : xv3;
;       x2[4 * i] = xv.x + o2[2 * i].x; x2[4 * i + 1] = xv.y + o2[2 * i].y; x2[4 * i + 2] = xv.z + o2[2 * i + 1].x; x2[4 * i + 3] = xv.w + o2[2 * i + 1].y;
;     }
;     float ss = 0.f;
; #pragma unroll
;     for (int i = 0; i < 16; i++) ss += x2[i] * x2[i];
;     ss = wsum(ss);
;     const float rs = rsqrtf(ss * (1.f / 1024.f) + EPSF);
;     if (store_x) {
; #pragma unroll
;       for (int i = 0; i < 4; i++) *(float4*)(xr + i * 4) = make_float4(x2[4 * i], x2[4 * i + 1], x2[4 * i + 2], x2[4 * i + 3]);
;     }
	v_cvt_pk_f32_fp8_sdwa v[38:39], v125 src0_sel:WORD_1
	v_pk_fma_f32 v[20:21], v[36:37], v[42:43], v[20:21] op_sel_hi:[1,0,1]
	v_pk_fma_f32 v[22:23], v[38:39], v[42:43], v[22:23] op_sel_hi:[1,0,1]
	v_cvt_pk_f32_fp8_e32 v[32:33], v126
	v_cvt_pk_f32_fp8_sdwa v[34:35], v126 src0_sel:WORD_1
	v_pk_fma_f32 v[24:25], v[32:33], v[42:43], v[24:25] op_sel_hi:[1,0,1]
	v_pk_fma_f32 v[26:27], v[34:35], v[42:43], v[26:27] op_sel_hi:[1,0,1]
	v_cvt_pk_f32_fp8_e32 v[36:37], v127
	v_cvt_pk_f32_fp8_sdwa v[38:39], v127 src0_sel:WORD_1
	v_pk_fma_f32 v[28:29], v[36:37], v[42:43], v[28:29] op_sel_hi:[1,0,1]
	v_pk_fma_f32 v[30:31], v[38:39], v[42:43], v[30:31] op_sel_hi:[1,0,1]
	s_nop 1
	v_permlane32_swap_b32_e32 v16, v24
	v_permlane32_swap_b32_e32 v17, v25
	v_permlane32_swap_b32_e32 v18, v26
	v_permlane32_swap_b32_e32 v19, v27
	v_permlane32_swap_b32_e32 v20, v28
	v_permlane32_swap_b32_e32 v21, v29
	v_permlane32_swap_b32_e32 v22, v30
	v_permlane32_swap_b32_e32 v23, v31
	v_add_f32_e32 v16, v16, v24
	v_add_f32_e32 v17, v17, v25
	v_add_f32_e32 v18, v18, v26
	v_add_f32_e32 v19, v19, v27
	v_add_f32_e32 v20, v20, v28
	v_add_f32_e32 v21, v21, v29
	v_add_f32_e32 v22, v22, v30
	v_add_f32_e32 v23, v23, v31
	s_nop 1
	v_permlane16_swap_b32_e32 v16, v20
	v_permlane16_swap_b32_e32 v17, v21
	v_permlane16_swap_b32_e32 v18, v22
	v_permlane16_swap_b32_e32 v19, v23
	v_add_f32_e32 v16, v16, v20
	v_add_f32_e32 v17, v17, v21
	v_add_f32_e32 v18, v18, v22
	v_add_f32_e32 v19, v19, v23
	v_accvgpr_read_b32 v50, a72
	v_accvgpr_read_b32 v51, a73
	v_add_f32_dpp v44, v16, v16 row_ror:8 row_mask:0xf bank_mask:0xf
	v_add_f32_dpp v45, v18, v18 row_ror:8 row_mask:0xf bank_mask:0xf
	v_add_f32_dpp v46, v17, v17 row_ror:8 row_mask:0xf bank_mask:0xf
	v_add_f32_dpp v47, v19, v19 row_ror:8 row_mask:0xf bank_mask:0xf
	v_cndmask_b32_e64 v48, v44, v45, s[14:15]
	v_cndmask_b32_e64 v49, v46, v47, s[14:15]
	v_add_f32_e32 v48, v50, v48
	v_add_f32_e32 v49, v51, v49
	s_lshl_b32 s11, s12, 12
	v_add_u32_e32 v6, s11, v3
	global_store_dwordx2 v6, v[48:49], s[6:7]
	v_mul_f32_e32 v52, v48, v48
	v_fmac_f32_e32 v52, v49, v49
	s_lshl_b32 s11, s12, 2
	s_add_u32 s11, s11, 0x1100000
	v_mov_b32_e32 v7, s11
	v_add_f32_dpp v52, v52, v52 quad_perm:[1,0,3,2] row_mask:0xf bank_mask:0xf
	s_nop 1
	v_add_f32_dpp v52, v52, v52 quad_perm:[2,3,0,1] row_mask:0xf bank_mask:0xf
	s_nop 1
	v_add_f32_dpp v52, v52, v52 row_half_mirror row_mask:0xf bank_mask:0xf
	s_nop 1
	v_add_f32_dpp v52, v52, v52 row_mirror row_mask:0xf bank_mask:0xf
	s_nop 1
	v_add_f32_dpp v52, v52, v52 row_bcast:15 row_mask:0xa bank_mask:0xf
	s_nop 1
	v_add_f32_dpp v52, v52, v52 row_bcast:31 row_mask:0xc bank_mask:0xf
	s_mov_b32 exec_lo, 0
	s_brev_b32 exec_hi, 1
	global_atomic_add_f32 v7, v52, s[4:5]
	s_mov_b64 exec, -1
.Lp5v_skip2:
	s_add_u32 s10, s8, s25
	s_min_u32 s10, s10, s13
	s_lshl_b32 s11, s10, 10
	v_add_u32_e32 v5, s11, v2
	global_load_dwordx4 a[196:199], v5, s[4:5] offset:0
	global_load_dwordx4 a[200:203], v5, s[4:5] offset:16
	global_load_dwordx4 a[204:207], v5, s[4:5] offset:32
	global_load_dwordx4 a[208:211], v5, s[4:5] offset:48
	global_load_dwordx4 a[212:215], v5, s[4:5] offset:64
	global_load_dwordx4 a[216:219], v5, s[4:5] offset:80
	global_load_dwordx4 a[220:223], v5, s[4:5] offset:96
	global_load_dwordx4 a[224:227], v5, s[4:5] offset:112
	s_lshl_b32 s11, s10, 12
	v_add_u32_e32 v6, s11, v3
	global_load_dwordx2 a[72:73], v6, s[6:7]
	v_accvgpr_read_b32 v10, a0
	v_add_u32_e32 v10, v10, v1
	global_load_dwordx4 v[64:67], v10, s[2:3]
	v_accvgpr_read_b32 v11, a2
	v_add_u32_e32 v11, v11, v1
	global_load_dwordx4 v[68:71], v11, s[2:3]
	v_accvgpr_read_b32 v12, a4
	v_add_u32_e32 v12, v12, v1
	global_load_dwordx4 v[72:75], v12, s[2:3]
	v_accvgpr_read_b32 v13, a6
	v_add_u32_e32 v13, v13, v1
	global_load_dwordx4 v[76:79], v13, s[2:3]
	v_accvgpr_read_b32 v10, a8
	v_add_u32_e32 v10, v10, v1
	global_load_dwordx4 v[80:83], v10, s[2:3]
	v_accvgpr_read_b32 v11, a10
	v_add_u32_e32 v11, v11, v1
	global_load_dwordx4 v[84:87], v11, s[2:3]
	v_accvgpr_read_b32 v12, a12
	v_add_u32_e32 v12, v12, v1
	global_load_dwordx4 v[88:91], v12, s[2:3]
	v_accvgpr_read_b32 v13, a14
	v_add_u32_e32 v13, v13, v1
	global_load_dwordx4 v[92:95], v13, s[2:3]
	v_accvgpr_read_b32 v10, a16
	v_add_u32_e32 v10, v10, v1
	global_load_dwordx4 v[96:99], v10, s[2:3]
	v_accvgpr_read_b32 v11, a18
	v_add_u32_e32 v11, v11, v1
	global_load_dwordx4 v[100:103], v11, s[2:3]
	v_accvgpr_read_b32 v12, a20
	v_add_u32_e32 v12, v12, v1
	global_load_dwordx4 v[104:107], v12, s[2:3]
	v_accvgpr_read_b32 v13, a22
	v_add_u32_e32 v13, v13, v1
	global_load_dwordx4 v[108:111], v13, s[2:3]
	v_accvgpr_read_b32 v10, a24
	v_add_u32_e32 v10, v10, v1
	global_load_dwordx4 v[112:115], v10, s[2:3]
	v_accvgpr_read_b32 v11, a26
	v_add_u32_e32 v11, v11, v1
	global_load_dwordx4 v[116:119], v11, s[2:3]
	v_accvgpr_read_b32 v12, a28
	v_add_u32_e32 v12, v12, v1
	global_load_dwordx4 v[120:123], v12, s[2:3]
	v_accvgpr_read_b32 v13, a30
	v_add_u32_e32 v13, v13, v1
	global_load_dwordx4 v[124:127], v13, s[2:3]
	s_add_u32 s12, s8, s22
	s_waitcnt vmcnt(27)
	s_cmp_lt_u32 s12, 0x4200
	s_cbranch_scc0 .Lp5v_skip3
	v_accvgpr_read_b32 v40, a229
	v_cvt_pk_f32_fp8_e32 v[32:33], v128
	v_cvt_pk_f32_fp8_sdwa v[34:35], v128 src0_sel:WORD_1
	v_pk_mul_f32 v[16:17], v[32:33], v[40:41] op_sel_hi:[1,0]
	v_pk_mul_f32 v[18:19], v[34:35], v[40:41] op_sel_hi:[1,0]
	v_cvt_pk_f32_fp8_e32 v[36:37], v129
	v_cvt_pk_f32_fp8_sdwa v[38:39], v129 src0_sel:WORD_1
	v_pk_mul_f32 v[20:21], v[36:37], v[40:41] op_sel_hi:[1,0]
	v_pk_mul_f32 v[22:23], v[38:39], v[40:41] op_sel_hi:[1,0]
	v_cvt_pk_f32_fp8_e32 v[32:33], v130
	v_cvt_pk_f32_fp8_sdwa v[34:35], v130 src0_sel:WORD_1
	v_pk_mul_f32 v[24:25], v[32:33], v[40:41] op_sel_hi:[1,0]
	v_pk_mul_f32 v[26:27], v[34:35], v[40:41] op_sel_hi:[1,0]
	v_cvt_pk_f32_fp8_e32 v[36:37], v131
	v_cvt_pk_f32_fp8_sdwa v[38:39], v131 src0_sel:WORD_1
	v_pk_mul_f32 v[28:29], v[36:37], v[40:41] op_sel_hi:[1,0]
	v_pk_mul_f32 v[30:31], v[38:39], v[40:41] op_sel_hi:[1,0]
	v_accvgpr_read_b32 v42, a231
	v_cvt_pk_f32_fp8_e32 v[32:33], v132
	v_cvt_pk_f32_fp8_sdwa v[34:35], v132 src0_sel:WORD_1
	v_pk_fma_f32 v[16:17], v[32:33], v[42:43], v[16:17] op_sel_hi:[1,0,1]
	v_pk_fma_f32 v[18:19], v[34:35], v[42:43], v[18:19] op_sel_hi:[1,0,1]
	v_cvt_pk_f32_fp8_e32 v[36:37], v133
	v_cvt_pk_f32_fp8_sdwa v[38:39], v133 src0_sel:WORD_1
	v_pk_fma_f32 v[20:21], v[36:37], v[42:43], v[20:21] op_sel_hi:[1,0,1]
	v_pk_fma_f32 v[22:23], v[38:39], v[42:43], v[22:23] op_sel_hi:[1,0,1]
	v_cvt_pk_f32_fp8_e32 v[32:33], v134
	v_cvt_pk_f32_fp8_sdwa v[34:35], v134 src0_sel:WORD_1
	v_pk_fma_f32 v[24:25], v[32:33], v[42:43], v[24:25] op_sel_hi:[1,0,1]
	v_pk_fma_f32 v[26:27], v[34:35], v[42:43], v[26:27] op_sel_hi:[1,0,1]
	v_cvt_pk_f32_fp8_e32 v[36:37], v135
	v_cvt_pk_f32_fp8_sdwa v[38:39], v135 src0_sel:WORD_1
	v_pk_fma_f32 v[28:29], v[36:37], v[42:43], v[28:29] op_sel_hi:[1,0,1]
	v_pk_fma_f32 v[30:31], v[38:39], v[42:43], v[30:31] op_sel_hi:[1,0,1]
	v_accvgpr_read_b32 v40, a233
	v_cvt_pk_f32_fp8_e32 v[32:33], v136
	v_cvt_pk_f32_fp8_sdwa v[34:35], v136 src0_sel:WORD_1
	v_pk_fma_f32 v[16:17], v[32:33], v[40:41], v[16:17] op_sel_hi:[1,0,1]
	v_pk_fma_f32 v[18:19], v[34:35], v[40:41], v[18:19] op_sel_hi:[1,0,1]
	v_cvt_pk_f32_fp8_e32 v[36:37], v137
	v_cvt_pk_f32_fp8_sdwa v[38:39], v137 src0_sel:WORD_1
	v_pk_fma_f32 v[20:21], v[36:37], v[40:41], v[20:21] op_sel_hi:[1,0,1]
	v_pk_fma_f32 v[22:23], v[38:39], v[40:41], v[22:23] op_sel_hi:[1,0,1]
	v_cvt_pk_f32_fp8_e32 v[32:33], v138
	v_cvt_pk_f32_fp8_sdwa v[34:35], v138 src0_sel:WORD_1
	v_pk_fma_f32 v[24:25], v[32:33], v[40:41], v[24:25] op_sel_hi:[1,0,1]
	v_pk_fma_f32 v[26:27], v[34:35], v[40:41], v[26:27] op_sel_hi:[1,0,1]
	v_cvt_pk_f32_fp8_e32 v[36:37], v139
	v_cvt_pk_f32_fp8_sdwa v[38:39], v139 src0_sel:WORD_1
	v_pk_fma_f32 v[28:29], v[36:37], v[40:41], v[28:29] op_sel_hi:[1,0,1]
	v_pk_fma_f32 v[30:31], v[38:39], v[40:41], v[30:31] op_sel_hi:[1,0,1]
	v_accvgpr_read_b32 v42, a235
	v_cvt_pk_f32_fp8_e32 v[32:33], v140
	v_cvt_pk_f32_fp8_sdwa v[34:35], v140 src0_sel:WORD_1
	v_pk_fma_f32 v[16:17], v[32:33], v[42:43], v[16:17] op_sel_hi:[1,0,1]
	v_pk_fma_f32 v[18:19], v[34:35], v[42:43], v[18:19] op_sel_hi:[1,0,1]
	v_cvt_pk_f32_fp8_e32 v[36:37], v141
	v_cvt_pk_f32_fp8_sdwa v[38:39], v141 src0_sel:WORD_1
	v_pk_fma_f32 v[20:21], v[36:37], v[42:43], v[20:21] op_sel_hi:[1,0,1]
	v_pk_fma_f32 v[22:23], v[38:39], v[42:43], v[22:23] op_sel_hi:[1,0,1]
	v_cvt_pk_f32_fp8_e32 v[32:33], v142
	v_cvt_pk_f32_fp8_sdwa v[34:35], v142 src0_sel:WORD_1
	v_pk_fma_f32 v[24:25], v[32:33], v[42:43], v[24:25] op_sel_hi:[1,0,1]
	v_pk_fma_f32 v[26:27], v[34:35], v[42:43], v[26:27] op_sel_hi:[1,0,1]
	v_cvt_pk_f32_fp8_e32 v[36:37], v143
	v_cvt_pk_f32_fp8_sdwa v[38:39], v143 src0_sel:WORD_1
	v_pk_fma_f32 v[28:29], v[36:37], v[42:43], v[28:29] op_sel_hi:[1,0,1]
	v_pk_fma_f32 v[30:31], v[38:39], v[42:43], v[30:31] op_sel_hi:[1,0,1]
	v_accvgpr_read_b32 v40, a237
	v_cvt_pk_f32_fp8_e32 v[32:33], v144
	v_cvt_pk_f32_fp8_sdwa v[34:35], v144 src0_sel:WORD_1
	v_pk_fma_f32 v[16:17], v[32:33], v[40:41], v[16:17] op_sel_hi:[1,0,1]
	v_pk_fma_f32 v[18:19], v[34:35], v[40:41], v[18:19] op_sel_hi:[1,0,1]
	v_cvt_pk_f32_fp8_e32 v[36:37], v145
	v_cvt_pk_f32_fp8_sdwa v[38:39], v145 src0_sel:WORD_1
	v_pk_fma_f32 v[20:21], v[36:37], v[40:41], v[20:21] op_sel_hi:[1,0,1]
	v_pk_fma_f32 v[22:23], v[38:39], v[40:41], v[22:23] op_sel_hi:[1,0,1]
	v_cvt_pk_f32_fp8_e32 v[32:33], v146
	v_cvt_pk_f32_fp8_sdwa v[34:35], v146 src0_sel:WORD_1
	v_pk_fma_f32 v[24:25], v[32:33], v[40:41], v[24:25] op_sel_hi:[1,0,1]
	v_pk_fma_f32 v[26:27], v[34:35], v[40:41], v[26:27] op_sel_hi:[1,0,1]
	v_cvt_pk_f32_fp8_e32 v[36:37], v147
	v_cvt_pk_f32_fp8_sdwa v[38:39], v147 src0_sel:WORD_1
	v_pk_fma_f32 v[28:29], v[36:37], v[40:41], v[28:29] op_sel_hi:[1,0,1]
	v_pk_fma_f32 v[30:31], v[38:39], v[40:41], v[30:31] op_sel_hi:[1,0,1]
	v_accvgpr_read_b32 v42, a239
	v_cvt_pk_f32_fp8_e32 v[32:33], v148
	v_cvt_pk_f32_fp8_sdwa v[34:35], v148 src0_sel:WORD_1
	v_pk_fma_f32 v[16:17], v[32:33], v[42:43], v[16:17] op_sel_hi:[1,0,1]
	v_pk_fma_f32 v[18:19], v[34:35], v[42:43], v[18:19] op_sel_hi:[1,0,1]
	v_cvt_pk_f32_fp8_e32 v[36:37], v149
	v_cvt_pk_f32_fp8_sdwa v[38:39], v149 src0_sel:WORD_1
	v_pk_fma_f32 v[20:21], v[36:37], v[42:43], v[20:21] op_sel_hi:[1,0,1]
	v_pk_fma_f32 v[22:23], v[38:39], v[42:43], v[22:23] op_sel_hi:[1,0,1]
	v_cvt_pk_f32_fp8_e32 v[32:33], v150
	v_cvt_pk_f32_fp8_sdwa v[34:35], v150 src0_sel:WORD_1
	v_pk_fma_f32 v[24:25], v[32:33], v[42:43], v[24:25] op_sel_hi:[1,0,1]
	v_pk_fma_f32 v[26:27], v[34:35], v[42:43], v[26:27] op_sel_hi:[1,0,1]
	v_cvt_pk_f32_fp8_e32 v[36:37], v151
	v_cvt_pk_f32_fp8_sdwa v[38:39], v151 src0_sel:WORD_1
	v_pk_fma_f32 v[28:29], v[36:37], v[42:43], v[28:29] op_sel_hi:[1,0,1]
	v_pk_fma_f32 v[30:31], v[38:39], v[42:43], v[30:31] op_sel_hi:[1,0,1]
	v_accvgpr_read_b32 v40, a241
	v_cvt_pk_f32_fp8_e32 v[32:33], v152
	v_cvt_pk_f32_fp8_sdwa v[34:35], v152 src0_sel:WORD_1
	v_pk_fma_f32 v[16:17], v[32:33], v[40:41], v[16:17] op_sel_hi:[1,0,1]
	v_pk_fma_f32 v[18:19], v[34:35], v[40:41], v[18:19] op_sel_hi:[1,0,1]
	v_cvt_pk_f32_fp8_e32 v[36:37], v153
	v_cvt_pk_f32_fp8_sdwa v[38:39], v153 src0_sel:WORD_1
	v_pk_fma_f32 v[20:21], v[36:37], v[40:41], v[20:21] op_sel_hi:[1,0,1]
	v_pk_fma_f32 v[22:23], v[38:39], v[40:41], v[22:23] op_sel_hi:[1,0,1]
	v_cvt_pk_f32_fp8_e32 v[32:33], v154
	v_cvt_pk_f32_fp8_sdwa v[34:35], v154 src0_sel:WORD_1
	v_pk_fma_f32 v[24:25], v[32:33], v[40:41], v[24:25] op_sel_hi:[1,0,1]
	v_pk_fma_f32 v[26:27], v[34:35], v[40:41], v[26:27] op_sel_hi:[1,0,1]
	v_cvt_pk_f32_fp8_e32 v[36:37], v155
	v_cvt_pk_f32_fp8_sdwa v[38:39], v155 src0_sel:WORD_1
	v_pk_fma_f32 v[28:29], v[36:37], v[40:41], v[28:29] op_sel_hi:[1,0,1]
	v_pk_fma_f32 v[30:31], v[38:39], v[40:41], v[30:31] op_sel_hi:[1,0,1]
	v_accvgpr_read_b32 v42, a243
	v_cvt_pk_f32_fp8_e32 v[32:33], v156
	v_cvt_pk_f32_fp8_sdwa v[34:35], v156 src0_sel:WORD_1
	v_pk_fma_f32 v[16:17], v[32:33], v[42:43], v[16:17] op_sel_hi:[1,0,1]
	v_pk_fma_f32 v[18:19], v[34:35], v[42:43], v[18:19] op_sel_hi:[1,0,1]
	v_cvt_pk_f32_fp8_e32 v[36:37], v157
	v_cvt_pk_f32_fp8_sdwa v[38:39], v157 src0_sel:WORD_1
	v_pk_fma_f32 v[20:21], v[36:37], v[42:43], v[20:21] op_sel_hi:[1,0,1]
	v_pk_fma_f32 v[22:23], v[38:39], v[42:43], v[22:23] op_sel_hi:[1,0,1]
	v_cvt_pk_f32_fp8_e32 v[32:33], v158
	v_cvt_pk_f32_fp8_sdwa v[34:35], v158 src0_sel:WORD_1
	v_pk_fma_f32 v[24:25], v[32:33], v[42:43], v[24:25] op_sel_hi:[1,0,1]
	v_pk_fma_f32 v[26:27], v[34:35], v[42:43], v[26:27] op_sel_hi:[1,0,1]
	v_cvt_pk_f32_fp8_e32 v[36:37], v159
	v_cvt_pk_f32_fp8_sdwa v[38:39], v159 src0_sel:WORD_1
	v_pk_fma_f32 v[28:29], v[36:37], v[42:43], v[28:29] op_sel_hi:[1,0,1]
	v_pk_fma_f32 v[30:31], v[38:39], v[42:43], v[30:31] op_sel_hi:[1,0,1]
	v_accvgpr_read_b32 v40, a245
	v_cvt_pk_f32_fp8_e32 v[32:33], v160
	v_cvt_pk_f32_fp8_sdwa v[34:35], v160 src0_sel:WORD_1
	v_pk_fma_f32 v[16:17], v[32:33], v[40:41], v[16:17] op_sel_hi:[1,0,1]
	v_pk_fma_f32 v[18:19], v[34:35], v[40:41], v[18:19] op_sel_hi:[1,0,1]
	v_cvt_pk_f32_fp8_e32 v[36:37], v161
	v_cvt_pk_f32_fp8_sdwa v[38:39], v161 src0_sel:WORD_1
	v_pk_fma_f32 v[20:21], v[36:37], v[40:41], v[20:21] op_sel_hi:[1,0,1]
	v_pk_fma_f32 v[22:23], v[38:39], v[40:41], v[22:23] op_sel_hi:[1,0,1]
	v_cvt_pk_f32_fp8_e32 v[32:33], v162
	v_cvt_pk_f32_fp8_sdwa v[34:35], v162 src0_sel:WORD_1
	v_pk_fma_f32 v[24:25], v[32:33], v[40:41], v[24:25] op_sel_hi:[1,0,1]
	v_pk_fma_f32 v[26:27], v[34:35], v[40:41], v[26:27] op_sel_hi:[1,0,1]
	v_cvt_pk_f32_fp8_e32 v[36:37], v163
	v_cvt_pk_f32_fp8_sdwa v[38:39], v163 src0_sel:WORD_1
	v_pk_fma_f32 v[28:29], v[36:37], v[40:41], v[28:29] op_sel_hi:[1,0,1]
	v_pk_fma_f32 v[30:31], v[38:39], v[40:41], v[30:31] op_sel_hi:[1,0,1]
	v_accvgpr_read_b32 v42, a247
	v_cvt_pk_f32_fp8_e32 v[32:33], v164
	v_cvt_pk_f32_fp8_sdwa v[34:35], v164 src0_sel:WORD_1
	v_pk_fma_f32 v[16:17], v[32:33], v[42:43], v[16:17] op_sel_hi:[1,0,1]
	v_pk_fma_f32 v[18:19], v[34:35], v[42:43], v[18:19] op_sel_hi:[1,0,1]
	v_cvt_pk_f32_fp8_e32 v[36:37], v165
	v_cvt_pk_f32_fp8_sdwa v[38:39], v165 src0_sel:WORD_1
	v_pk_fma_f32 v[20:21], v[36:37], v[42:43], v[20:21] op_sel_hi:[1,0,1]
	v_pk_fma_f32 v[22:23], v[38:39], v[42:43], v[22:23] op_sel_hi:[1,0,1]
	v_cvt_pk_f32_fp8_e32 v[32:33], v166
	v_cvt_pk_f32_fp8_sdwa v[34:35], v166 src0_sel:WORD_1
	v_pk_fma_f32 v[24:25], v[32:33], v[42:43], v[24:25] op_sel_hi:[1,0,1]
	v_pk_fma_f32 v[26:27], v[34:35], v[42:43], v[26:27] op_sel_hi:[1,0,1]
	v_cvt_pk_f32_fp8_e32 v[36:37], v167
	v_cvt_pk_f32_fp8_sdwa v[38:39], v167 src0_sel:WORD_1
	v_pk_fma_f32 v[28:29], v[36:37], v[42:43], v[28:29] op_sel_hi:[1,0,1]
	v_pk_fma_f32 v[30:31], v[38:39], v[42:43], v[30:31] op_sel_hi:[1,0,1]
	v_accvgpr_read_b32 v40, a249
	v_cvt_pk_f32_fp8_e32 v[32:33], v168
	v_cvt_pk_f32_fp8_sdwa v[34:35], v168 src0_sel:WORD_1
	v_pk_fma_f32 v[16:17], v[32:33], v[40:41], v[16:17] op_sel_hi:[1,0,1]
	v_pk_fma_f32 v[18:19], v[34:35], v[40:41], v[18:19] op_sel_hi:[1,0,1]
	v_cvt_pk_f32_fp8_e32 v[36:37], v169
	v_cvt_pk_f32_fp8_sdwa v[38:39], v169 src0_sel:WORD_1
	v_pk_fma_f32 v[20:21], v[36:37], v[40:41], v[20:21] op_sel_hi:[1,0,1]
	v_pk_fma_f32 v[22:23], v[38:39], v[40:41], v[22:23] op_sel_hi:[1,0,1]
	v_cvt_pk_f32_fp8_e32 v[32:33], v170
	v_cvt_pk_f32_fp8_sdwa v[34:35], v170 src0_sel:WORD_1
	v_pk_fma_f32 v[24:25], v[32:33], v[40:41], v[24:25] op_sel_hi:[1,0,1]
	v_pk_fma_f32 v[26:27], v[34:35], v[40:41], v[26:27] op_sel_hi:[1,0,1]
	v_cvt_pk_f32_fp8_e32 v[36:37], v171
	v_cvt_pk_f32_fp8_sdwa v[38:39], v171 src0_sel:WORD_1
	v_pk_fma_f32 v[28:29], v[36:37], v[40:41], v[28:29] op_sel_hi:[1,0,1]
	v_pk_fma_f32 v[30:31], v[38:39], v[40:41], v[30:31] op_sel_hi:[1,0,1]
	v_accvgpr_read_b32 v42, a251
	v_cvt_pk_f32_fp8_e32 v[32:33], v172
	v_cvt_pk_f32_fp8_sdwa v[34:35], v172 src0_sel:WORD_1
	v_pk_fma_f32 v[16:17], v[32:33], v[42:43], v[16:17] op_sel_hi:[1,0,1]
	v_pk_fma_f32 v[18:19], v[34:35], v[42:43], v[18:19] op_sel_hi:[1,0,1]
	v_cvt_pk_f32_fp8_e32 v[36:37], v173
	v_cvt_pk_f32_fp8_sdwa v[38:39], v173 src0_sel:WORD_1
	v_pk_fma_f32 v[20:21], v[36:37], v[42:43], v[20:21] op_sel_hi:[1,0,1]
	v_pk_fma_f32 v[22:23], v[38:39], v[42:43], v[22:23] op_sel_hi:[1,0,1]
	v_cvt_pk_f32_fp8_e32 v[32:33], v174
	v_cvt_pk_f32_fp8_sdwa v[34:35], v174 src0_sel:WORD_1
	v_pk_fma_f32 v[24:25], v[32:33], v[42:43], v[24:25] op_sel_hi:[1,0,1]
	v_pk_fma_f32 v[26:27], v[34:35], v[42:43], v[26:27] op_sel_hi:[1,0,1]
	v_cvt_pk_f32_fp8_e32 v[36:37], v175
; __device__ __forceinline__ float wsum(float v) { v = dpp_row_sum16(v); v += __shfl_xor(v, 16); v += __shfl_xor(v, 32); return v; }
; __device__ __forceinline__ void phase5(const Params& p, char* smem, const bool store_x = true) {
;     ...
;     float x2[16];
; #pragma unroll
;     for (int i = 0; i < 4; i++) {
;       const float4 xv = i == 0 ? xv0 : i == 1 ? xv1 : i == 2 ? xv2 : xv3;
;       x2[4 * i] = xv.x + o2[2 * i].x; x2[4 * i + 1] = xv.y + o2[2 * i].y; x2[4 * i + 2] = xv.z + o2[2 * i + 1].x; x2[4 * i + 3] = xv.w + o2[2 * i + 1].y;
;     }
;     float ss = 0.f;
; #pragma unroll
;     for (int i = 0; i < 16; i++) ss += x2[i] * x2[i];
;     ss = wsum(ss);
;     const float rs = rsqrtf(ss * (1.f / 1024.f) + EPSF);
;     if (store_x) {
; #pragma unroll
;       for (int i = 0; i < 4; i++) *(float4*)(xr + i * 4) = make_float4(x2[4 * i], x2[4 * i + 1], x2[4 * i + 2], x2[4 * i + 3]);
;     }
; __device__ __forceinline__ void xcd_barrier(const XcdBarrier& b) {
;     asm volatile("s_waitcnt vmcnt(0)" ::: "memory");
;     __syncthreads();
;     if (threadIdx.x == 0) {
	v_cvt_pk_f32_fp8_sdwa v[38:39], v175 src0_sel:WORD_1
	v_pk_fma_f32 v[28:29], v[36:37], v[42:43], v[28:29] op_sel_hi:[1,0,1]
	v_pk_fma_f32 v[30:31], v[38:39], v[42:43], v[30:31] op_sel_hi:[1,0,1]
	v_accvgpr_read_b32 v40, a253
	v_cvt_pk_f32_fp8_e32 v[32:33], v176
	v_cvt_pk_f32_fp8_sdwa v[34:35], v176 src0_sel:WORD_1
	v_pk_fma_f32 v[16:17], v[32:33], v[40:41], v[16:17] op_sel_hi:[1,0,1]
	v_pk_fma_f32 v[18:19], v[34:35], v[40:41], v[18:19] op_sel_hi:[1,0,1]
	v_cvt_pk_f32_fp8_e32 v[36:37], v177
	v_cvt_pk_f32_fp8_sdwa v[38:39], v177 src0_sel:WORD_1
	v_pk_fma_f32 v[20:21], v[36:37], v[40:41], v[20:21] op_sel_hi:[1,0,1]
	v_pk_fma_f32 v[22:23], v[38:39], v[40:41], v[22:23] op_sel_hi:[1,0,1]
	v_cvt_pk_f32_fp8_e32 v[32:33], v178
	v_cvt_pk_f32_fp8_sdwa v[34:35], v178 src0_sel:WORD_1
	v_pk_fma_f32 v[24:25], v[32:33], v[40:41], v[24:25] op_sel_hi:[1,0,1]
	v_pk_fma_f32 v[26:27], v[34:35], v[40:41], v[26:27] op_sel_hi:[1,0,1]
	v_cvt_pk_f32_fp8_e32 v[36:37], v179
	v_cvt_pk_f32_fp8_sdwa v[38:39], v179 src0_sel:WORD_1
	v_pk_fma_f32 v[28:29], v[36:37], v[40:41], v[28:29] op_sel_hi:[1,0,1]
	v_pk_fma_f32 v[30:31], v[38:39], v[40:41], v[30:31] op_sel_hi:[1,0,1]
	v_accvgpr_read_b32 v42, a255
	v_cvt_pk_f32_fp8_e32 v[32:33], v180
	v_cvt_pk_f32_fp8_sdwa v[34:35], v180 src0_sel:WORD_1
	v_pk_fma_f32 v[16:17], v[32:33], v[42:43], v[16:17] op_sel_hi:[1,0,1]
	v_pk_fma_f32 v[18:19], v[34:35], v[42:43], v[18:19] op_sel_hi:[1,0,1]
	v_cvt_pk_f32_fp8_e32 v[36:37], v181
	v_cvt_pk_f32_fp8_sdwa v[38:39], v181 src0_sel:WORD_1
	v_pk_fma_f32 v[20:21], v[36:37], v[42:43], v[20:21] op_sel_hi:[1,0,1]
	v_pk_fma_f32 v[22:23], v[38:39], v[42:43], v[22:23] op_sel_hi:[1,0,1]
	v_cvt_pk_f32_fp8_e32 v[32:33], v182
	v_cvt_pk_f32_fp8_sdwa v[34:35], v182 src0_sel:WORD_1
	v_pk_fma_f32 v[24:25], v[32:33], v[42:43], v[24:25] op_sel_hi:[1,0,1]
	v_pk_fma_f32 v[26:27], v[34:35], v[42:43], v[26:27] op_sel_hi:[1,0,1]
	v_cvt_pk_f32_fp8_e32 v[36:37], v183
	v_cvt_pk_f32_fp8_sdwa v[38:39], v183 src0_sel:WORD_1
	v_pk_fma_f32 v[28:29], v[36:37], v[42:43], v[28:29] op_sel_hi:[1,0,1]
	v_pk_fma_f32 v[30:31], v[38:39], v[42:43], v[30:31] op_sel_hi:[1,0,1]
	v_accvgpr_read_b32 v40, a65
	v_cvt_pk_f32_fp8_e32 v[32:33], v184
	v_cvt_pk_f32_fp8_sdwa v[34:35], v184 src0_sel:WORD_1
	v_pk_fma_f32 v[16:17], v[32:33], v[40:41], v[16:17] op_sel_hi:[1,0,1]
	v_pk_fma_f32 v[18:19], v[34:35], v[40:41], v[18:19] op_sel_hi:[1,0,1]
	v_cvt_pk_f32_fp8_e32 v[36:37], v185
	v_cvt_pk_f32_fp8_sdwa v[38:39], v185 src0_sel:WORD_1
	v_pk_fma_f32 v[20:21], v[36:37], v[40:41], v[20:21] op_sel_hi:[1,0,1]
	v_pk_fma_f32 v[22:23], v[38:39], v[40:41], v[22:23] op_sel_hi:[1,0,1]
	v_cvt_pk_f32_fp8_e32 v[32:33], v186
	v_cvt_pk_f32_fp8_sdwa v[34:35], v186 src0_sel:WORD_1
	v_pk_fma_f32 v[24:25], v[32:33], v[40:41], v[24:25] op_sel_hi:[1,0,1]
	v_pk_fma_f32 v[26:27], v[34:35], v[40:41], v[26:27] op_sel_hi:[1,0,1]
	v_cvt_pk_f32_fp8_e32 v[36:37], v187
	v_cvt_pk_f32_fp8_sdwa v[38:39], v187 src0_sel:WORD_1
	v_pk_fma_f32 v[28:29], v[36:37], v[40:41], v[28:29] op_sel_hi:[1,0,1]
	v_pk_fma_f32 v[30:31], v[38:39], v[40:41], v[30:31] op_sel_hi:[1,0,1]
	v_accvgpr_read_b32 v42, a67
	v_cvt_pk_f32_fp8_e32 v[32:33], v188
	v_cvt_pk_f32_fp8_sdwa v[34:35], v188 src0_sel:WORD_1
	v_pk_fma_f32 v[16:17], v[32:33], v[42:43], v[16:17] op_sel_hi:[1,0,1]
	v_pk_fma_f32 v[18:19], v[34:35], v[42:43], v[18:19] op_sel_hi:[1,0,1]
	v_cvt_pk_f32_fp8_e32 v[36:37], v189
	v_cvt_pk_f32_fp8_sdwa v[38:39], v189 src0_sel:WORD_1
	v_pk_fma_f32 v[20:21], v[36:37], v[42:43], v[20:21] op_sel_hi:[1,0,1]
	v_pk_fma_f32 v[22:23], v[38:39], v[42:43], v[22:23] op_sel_hi:[1,0,1]
	v_cvt_pk_f32_fp8_e32 v[32:33], v190
	v_cvt_pk_f32_fp8_sdwa v[34:35], v190 src0_sel:WORD_1
	v_pk_fma_f32 v[24:25], v[32:33], v[42:43], v[24:25] op_sel_hi:[1,0,1]
	v_pk_fma_f32 v[26:27], v[34:35], v[42:43], v[26:27] op_sel_hi:[1,0,1]
	v_cvt_pk_f32_fp8_e32 v[36:37], v191
	v_cvt_pk_f32_fp8_sdwa v[38:39], v191 src0_sel:WORD_1
	v_pk_fma_f32 v[28:29], v[36:37], v[42:43], v[28:29] op_sel_hi:[1,0,1]
	v_pk_fma_f32 v[30:31], v[38:39], v[42:43], v[30:31] op_sel_hi:[1,0,1]
	s_nop 1
	v_permlane32_swap_b32_e32 v16, v24
	v_permlane32_swap_b32_e32 v17, v25
	v_permlane32_swap_b32_e32 v18, v26
	v_permlane32_swap_b32_e32 v19, v27
	v_permlane32_swap_b32_e32 v20, v28
	v_permlane32_swap_b32_e32 v21, v29
	v_permlane32_swap_b32_e32 v22, v30
	v_permlane32_swap_b32_e32 v23, v31
	v_add_f32_e32 v16, v16, v24
	v_add_f32_e32 v17, v17, v25
	v_add_f32_e32 v18, v18, v26
	v_add_f32_e32 v19, v19, v27
	v_add_f32_e32 v20, v20, v28
	v_add_f32_e32 v21, v21, v29
	v_add_f32_e32 v22, v22, v30
	v_add_f32_e32 v23, v23, v31
	s_nop 1
	v_permlane16_swap_b32_e32 v16, v20
	v_permlane16_swap_b32_e32 v17, v21
	v_permlane16_swap_b32_e32 v18, v22
	v_permlane16_swap_b32_e32 v19, v23
	v_add_f32_e32 v16, v16, v20
	v_add_f32_e32 v17, v17, v21
	v_add_f32_e32 v18, v18, v22
	v_add_f32_e32 v19, v19, v23
	v_accvgpr_read_b32 v50, a74
	v_accvgpr_read_b32 v51, a75
	v_add_f32_dpp v44, v16, v16 row_ror:8 row_mask:0xf bank_mask:0xf
	v_add_f32_dpp v45, v18, v18 row_ror:8 row_mask:0xf bank_mask:0xf
	v_add_f32_dpp v46, v17, v17 row_ror:8 row_mask:0xf bank_mask:0xf
	v_add_f32_dpp v47, v19, v19 row_ror:8 row_mask:0xf bank_mask:0xf
	v_cndmask_b32_e64 v48, v44, v45, s[14:15]
	v_cndmask_b32_e64 v49, v46, v47, s[14:15]
	v_add_f32_e32 v48, v50, v48
	v_add_f32_e32 v49, v51, v49
	s_lshl_b32 s11, s12, 12
	v_add_u32_e32 v6, s11, v3
	global_store_dwordx2 v6, v[48:49], s[6:7]
	v_mul_f32_e32 v52, v48, v48
	v_fmac_f32_e32 v52, v49, v49
	s_lshl_b32 s11, s12, 2
	s_add_u32 s11, s11, 0x1100000
	v_mov_b32_e32 v7, s11
	v_add_f32_dpp v52, v52, v52 quad_perm:[1,0,3,2] row_mask:0xf bank_mask:0xf
	s_nop 1
	v_add_f32_dpp v52, v52, v52 quad_perm:[2,3,0,1] row_mask:0xf bank_mask:0xf
	s_nop 1
	v_add_f32_dpp v52, v52, v52 row_half_mirror row_mask:0xf bank_mask:0xf
	s_nop 1
	v_add_f32_dpp v52, v52, v52 row_mirror row_mask:0xf bank_mask:0xf
	s_nop 1
	v_add_f32_dpp v52, v52, v52 row_bcast:15 row_mask:0xa bank_mask:0xf
	s_nop 1
	v_add_f32_dpp v52, v52, v52 row_bcast:31 row_mask:0xc bank_mask:0xf
	s_mov_b32 exec_lo, 0
	s_brev_b32 exec_hi, 1
	global_atomic_add_f32 v7, v52, s[4:5]
	s_mov_b64 exec, -1
.Lp5v_skip3:
	s_add_u32 s8, s8, s23
	s_cmp_lt_u32 s8, 0x4200
	s_cbranch_scc1 .Lp5v_loop
	s_waitcnt vmcnt(0)
.Lpb2_1523:
	s_waitcnt vmcnt(0)
	s_barrier
	s_and_saveexec_b64 s[0:1], s[72:73]
	s_cbranch_execz .Lpb2_1575

; __device__ __forceinline__ void xcd_barrier(const XcdBarrier& b) {
;     ...
;         unsigned* bar = b.bar;
;         __builtin_amdgcn_s_waitcnt(0);
;         unsigned nloc = b.st[0], nx = b.st[1];
;         if (nloc == 0u) { xcd_barrier_complete(bar, b.x, nloc, nx); b.st[0] = nloc; b.st[1] = nx; }
	v_mov_b32_e32 v0, 0x23800
	s_waitcnt vmcnt(0) expcnt(0) lgkmcnt(0)
	ds_read_b32 v2, v0
	v_mov_b32_e32 v0, 0x23804
	ds_read_b32 v0, v0
	s_waitcnt lgkmcnt(1)
	v_cmp_ne_u32_e32 vcc, 0, v2
	s_cbranch_vccnz .Lpb2_1539

; __device__ __forceinline__ unsigned xb_ld(unsigned* p)              { return __hip_atomic_load(p, __ATOMIC_RELAXED, __HIP_MEMORY_SCOPE_AGENT); }
; __device__ __forceinline__ void xcd_barrier_complete(unsigned* bar, unsigned x, unsigned& nloc, unsigned& nx) {
;     const unsigned G = gridDim.x * gridDim.y * gridDim.z;
;     unsigned sum, cnt, mine, sp = 0u;
;     for (;;) {
;         sum = 0u; cnt = 0u; mine = 0u;
; #pragma unroll
;         for (unsigned j = 0; j < 16; ++j) { const unsigned c = xb_ld(&bar[XB_XCNT(j)]); sum += c; cnt += (c > 0u) ? 1u : 0u; mine = (j == x) ? c : mine; }
	v_readlane_b32 s4, v254, 0
	s_mul_i32 s33, s83, s4
	s_add_u32 s4, s80, 0x12f35200
	s_addc_u32 s5, s81, 0
	s_add_u32 s6, s80, 0x12f35400
	s_addc_u32 s7, s81, 0
	s_add_u32 s8, s80, 0x12f35500
	s_addc_u32 s9, s81, 0
	s_add_u32 s10, s80, 0x12f35600
	s_addc_u32 s11, s81, 0
	s_add_u32 s12, s80, 0x12f35700
	s_addc_u32 s13, s81, 0
	s_add_u32 s14, s80, 0x12f35800
	s_addc_u32 s15, s81, 0
	s_add_u32 s16, s80, 0x12f35900
	s_addc_u32 s17, s81, 0
	s_add_u32 s18, s80, 0x12f35a00
	s_addc_u32 s19, s81, 0
	s_add_u32 s20, s80, 0x12f35b00
	s_addc_u32 s21, s81, 0
	s_add_u32 s22, s80, 0x12f35c00
	s_addc_u32 s23, s81, 0
	s_add_u32 s24, s80, 0x12f35d00
	s_addc_u32 s25, s81, 0
	s_add_u32 s26, s80, 0x12f35e00
	s_addc_u32 s27, s81, 0
	s_add_u32 s28, s80, 0x12f35f00
	s_addc_u32 s29, s81, 0
	s_add_u32 s34, s80, 0x12f36000
	s_addc_u32 s35, s81, 0
	s_add_u32 s36, s80, 0x12f36100
	s_addc_u32 s37, s81, 0
	s_add_u32 s38, s80, 0x12f36200
	s_addc_u32 s39, s81, 0
	s_add_u32 s40, s80, 0x12f36300
	s_mul_i32 s33, s33, s82
	s_addc_u32 s41, s81, 0
	s_mov_b32 s48, 1
	v_mov_b32_e32 v16, 0
	s_branch .Lpb2_1527

; __device__ __forceinline__ float wsum(float v) { v = dpp_row_sum16(v); v += __shfl_xor(v, 16); v += __shfl_xor(v, 32); return v; }
; __device__ __forceinline__ void phase5(const Params& p, char* smem, const bool store_x = true) {
;     ...
;     float ss = 0.f;
; #pragma unroll
;     for (int i = 0; i < 16; i++) ss += x2[i] * x2[i];
;     ss = wsum(ss);
;     const float rs = rsqrtf(ss * (1.f / 1024.f) + EPSF);
;     if (store_x) {
; #pragma unroll
;       for (int i = 0; i < 4; i++) *(float4*)(xr + i * 4) = make_float4(x2[4 * i], x2[4 * i + 1], x2[4 * i + 2], x2[4 * i + 3]);
;     }
;     unsigned hp[8];
; #pragma unroll
;     for (int i = 0; i < 4; i++) {
;       const float4 g = *(const float4*)(p.g_ple + lane * 16 + i * 4);
;       hp[2 * i] = pack2(x2[4 * i] * rs * g.x, x2[4 * i + 1] * rs * g.y);
;       hp[2 * i + 1] = pack2(x2[4 * i + 2] * rs * g.z, x2[4 * i + 3] * rs * g.w);
;     }
;     *(uint4*)(H3 + (size_t)tok * 1024 + lane * 16) = make_uint4(hp[0], hp[1], hp[2], hp[3]);
;     *(uint4*)(H3 + (size_t)tok * 1024 + lane * 16 + 8) = make_uint4(hp[4], hp[5], hp[6], hp[7]);
.Lpb2_1574:
	s_or_b64 exec, exec, s[8:9]
	s_waitcnt vmcnt(0)
.Lpb2_1575:
	s_or_b64 exec, exec, s[0:1]
	s_waitcnt lgkmcnt(0)
	s_barrier
.Lp5h_start:
	v_mbcnt_lo_u32_b32 v0, -1, 0
	v_mbcnt_hi_u32_b32 v0, -1, v0
	v_accvgpr_read_b32 v4, a129
	v_readlane_b32 s70, v254, 33
	v_readlane_b32 s71, v254, 34
	v_lshlrev_b32_e32 v1, 6, v0
	v_lshlrev_b32_e32 v2, 5, v0
	v_readfirstlane_b32 s8, v4
	s_lshl_b32 s10, s96, 2
	s_add_u32 s8, s8, s10
	s_lshl_b32 s9, s82, 2
	s_add_u32 s4, s80, 0x3bb5000
	s_addc_u32 s5, s81, 0
	s_add_u32 s2, s80, 0x8e35000
	s_addc_u32 s3, s81, 0
	global_load_dwordx4 v[112:115], v1, s[70:71]
	global_load_dwordx4 v[116:119], v1, s[70:71] offset:16
	global_load_dwordx4 v[120:123], v1, s[70:71] offset:32
	global_load_dwordx4 v[124:127], v1, s[70:71] offset:48
	v_mov_b32_e32 v105, 0x358637bd
	s_mov_b32 s39, 0x800000
	s_cmp_lt_u32 s8, 0x4200
	s_cbranch_scc0 .Lp5h_done
	s_lshl_b32 s11, s8, 12
	v_add_u32_e32 v5, s11, v1
	global_load_dwordx4 v[64:67], v5, s[78:79] offset:0
	global_load_dwordx4 v[68:71], v5, s[78:79] offset:16
	global_load_dwordx4 v[72:75], v5, s[78:79] offset:32
	global_load_dwordx4 v[76:79], v5, s[78:79] offset:48
	s_lshl_b32 s11, s8, 2
	s_add_u32 s11, s11, 0x1100000
	v_mov_b32_e32 v6, s11
	global_load_dword v80, v6, s[4:5]
.Lp5h_loop:
	s_add_u32 s12, s8, s9
	s_cmp_lt_u32 s12, 0x4200
	s_cbranch_scc0 .Lp5h_last0
	s_lshl_b32 s11, s12, 12
	v_add_u32_e32 v5, s11, v1
	global_load_dwordx4 v[88:91], v5, s[78:79] offset:0
	global_load_dwordx4 v[92:95], v5, s[78:79] offset:16
	global_load_dwordx4 v[96:99], v5, s[78:79] offset:32
	global_load_dwordx4 v[100:103], v5, s[78:79] offset:48
	s_lshl_b32 s11, s12, 2
	s_add_u32 s11, s11, 0x1100000
	v_mov_b32_e32 v6, s11
	global_load_dword v104, v6, s[4:5]
	s_waitcnt vmcnt(5)
	v_fmamk_f32 v8, v80, 0x3a800000, v105
	v_mul_f32_e32 v9, 0x4b800000, v8
	v_cmp_gt_f32_e64 s[0:1], s39, v8
	s_nop 1
	v_cndmask_b32_e64 v8, v8, v9, s[0:1]
	v_rsq_f32_e32 v8, v8
	s_nop 0
	v_mul_f32_e32 v9, 0x45800000, v8
	v_cndmask_b32_e64 v8, v8, v9, s[0:1]
	v_pk_mul_f32 v[16:17], v[64:65], v[8:9] op_sel_hi:[1,0]
	v_pk_mul_f32 v[18:19], v[66:67], v[8:9] op_sel_hi:[1,0]
	v_pk_mul_f32 v[20:21], v[68:69], v[8:9] op_sel_hi:[1,0]
	v_pk_mul_f32 v[22:23], v[70:71], v[8:9] op_sel_hi:[1,0]
	v_pk_mul_f32 v[24:25], v[72:73], v[8:9] op_sel_hi:[1,0]
	v_pk_mul_f32 v[26:27], v[74:75], v[8:9] op_sel_hi:[1,0]
	v_pk_mul_f32 v[28:29], v[76:77], v[8:9] op_sel_hi:[1,0]
	v_pk_mul_f32 v[30:31], v[78:79], v[8:9] op_sel_hi:[1,0]
	v_pk_mul_f32 v[16:17], v[16:17], v[112:113]
	v_pk_mul_f32 v[18:19], v[18:19], v[114:115]
	v_pk_mul_f32 v[20:21], v[20:21], v[116:117]
	v_pk_mul_f32 v[22:23], v[22:23], v[118:119]
	v_pk_mul_f32 v[24:25], v[24:25], v[120:121]
	v_pk_mul_f32 v[26:27], v[26:27], v[122:123]
	v_pk_mul_f32 v[28:29], v[28:29], v[124:125]
	v_pk_mul_f32 v[30:31], v[30:31], v[126:127]
	v_cvt_pk_bf16_f32 v40, v16, v17
	v_cvt_pk_bf16_f32 v41, v18, v19
	v_cvt_pk_bf16_f32 v42, v20, v21
	v_cvt_pk_bf16_f32 v43, v22, v23
	v_cvt_pk_bf16_f32 v44, v24, v25
	v_cvt_pk_bf16_f32 v45, v26, v27
	v_cvt_pk_bf16_f32 v46, v28, v29
	v_cvt_pk_bf16_f32 v47, v30, v31
	s_lshl_b32 s11, s8, 11
	v_add_u32_e32 v7, s11, v2
	global_store_dwordx4 v7, v[40:43], s[2:3]
	global_store_dwordx4 v7, v[44:47], s[2:3] offset:16
	s_add_u32 s8, s12, s9
	s_cmp_lt_u32 s8, 0x4200
	s_cbranch_scc0 .Lp5h_last1
	s_lshl_b32 s11, s8, 12
	v_add_u32_e32 v5, s11, v1
	global_load_dwordx4 v[64:67], v5, s[78:79] offset:0
	global_load_dwordx4 v[68:71], v5, s[78:79] offset:16
	global_load_dwordx4 v[72:75], v5, s[78:79] offset:32
	global_load_dwordx4 v[76:79], v5, s[78:79] offset:48
	s_lshl_b32 s11, s8, 2
	s_add_u32 s11, s11, 0x1100000
	v_mov_b32_e32 v6, s11
	global_load_dword v80, v6, s[4:5]
	s_waitcnt vmcnt(5)
	v_fmamk_f32 v8, v104, 0x3a800000, v105
	v_mul_f32_e32 v9, 0x4b800000, v8
	v_cmp_gt_f32_e64 s[0:1], s39, v8
	s_nop 1
	v_cndmask_b32_e64 v8, v8, v9, s[0:1]
	v_rsq_f32_e32 v8, v8
	s_nop 0
	v_mul_f32_e32 v9, 0x45800000, v8
	v_cndmask_b32_e64 v8, v8, v9, s[0:1]
	v_pk_mul_f32 v[16:17], v[88:89], v[8:9] op_sel_hi:[1,0]
	v_pk_mul_f32 v[18:19], v[90:91], v[8:9] op_sel_hi:[1,0]
	v_pk_mul_f32 v[20:21], v[92:93], v[8:9] op_sel_hi:[1,0]
	v_pk_mul_f32 v[22:23], v[94:95], v[8:9] op_sel_hi:[1,0]
	v_pk_mul_f32 v[24:25], v[96:97], v[8:9] op_sel_hi:[1,0]
	v_pk_mul_f32 v[26:27], v[98:99], v[8:9] op_sel_hi:[1,0]
	v_pk_mul_f32 v[28:29], v[100:101], v[8:9] op_sel_hi:[1,0]
	v_pk_mul_f32 v[30:31], v[102:103], v[8:9] op_sel_hi:[1,0]
	v_pk_mul_f32 v[16:17], v[16:17], v[112:113]
	v_pk_mul_f32 v[18:19], v[18:19], v[114:115]
	v_pk_mul_f32 v[20:21], v[20:21], v[116:117]
	v_pk_mul_f32 v[22:23], v[22:23], v[118:119]
	v_pk_mul_f32 v[24:25], v[24:25], v[120:121]
	v_pk_mul_f32 v[26:27], v[26:27], v[122:123]
	v_pk_mul_f32 v[28:29], v[28:29], v[124:125]
	v_pk_mul_f32 v[30:31], v[30:31], v[126:127]
	v_cvt_pk_bf16_f32 v40, v16, v17
	v_cvt_pk_bf16_f32 v41, v18, v19
	v_cvt_pk_bf16_f32 v42, v20, v21
	v_cvt_pk_bf16_f32 v43, v22, v23
	v_cvt_pk_bf16_f32 v44, v24, v25
	v_cvt_pk_bf16_f32 v45, v26, v27
	v_cvt_pk_bf16_f32 v46, v28, v29
	v_cvt_pk_bf16_f32 v47, v30, v31
	s_lshl_b32 s11, s12, 11
	v_add_u32_e32 v7, s11, v2
	global_store_dwordx4 v7, v[40:43], s[2:3]
	global_store_dwordx4 v7, v[44:47], s[2:3] offset:16
	s_branch .Lp5h_loop
; __device__ __forceinline__ void phase5(const Params& p, char* smem, const bool store_x = true) {
;     ...
;     unsigned hp[8];
; #pragma unroll
;     for (int i = 0; i < 4; i++) {
;       const float4 g = *(const float4*)(p.g_ple + lane * 16 + i * 4);
;       hp[2 * i] = pack2(x2[4 * i] * rs * g.x, x2[4 * i + 1] * rs * g.y);
;       hp[2 * i + 1] = pack2(x2[4 * i + 2] * rs * g.z, x2[4 * i + 3] * rs * g.w);
;     }
;     *(uint4*)(H3 + (size_t)tok * 1024 + lane * 16) = make_uint4(hp[0], hp[1], hp[2], hp[3]);
;     *(uint4*)(H3 + (size_t)tok * 1024 + lane * 16 + 8) = make_uint4(hp[4], hp[5], hp[6], hp[7]);
.Lp5h_last0:
	s_waitcnt vmcnt(0)
	v_fmamk_f32 v8, v80, 0x3a800000, v105
	v_mul_f32_e32 v9, 0x4b800000, v8
	v_cmp_gt_f32_e64 s[0:1], s39, v8
	s_nop 1
	v_cndmask_b32_e64 v8, v8, v9, s[0:1]
	v_rsq_f32_e32 v8, v8
	s_nop 0
	v_mul_f32_e32 v9, 0x45800000, v8
	v_cndmask_b32_e64 v8, v8, v9, s[0:1]
	v_pk_mul_f32 v[16:17], v[64:65], v[8:9] op_sel_hi:[1,0]
	v_pk_mul_f32 v[18:19], v[66:67], v[8:9] op_sel_hi:[1,0]
	v_pk_mul_f32 v[20:21], v[68:69], v[8:9] op_sel_hi:[1,0]
	v_pk_mul_f32 v[22:23], v[70:71], v[8:9] op_sel_hi:[1,0]
	v_pk_mul_f32 v[24:25], v[72:73], v[8:9] op_sel_hi:[1,0]
	v_pk_mul_f32 v[26:27], v[74:75], v[8:9] op_sel_hi:[1,0]
	v_pk_mul_f32 v[28:29], v[76:77], v[8:9] op_sel_hi:[1,0]
	v_pk_mul_f32 v[30:31], v[78:79], v[8:9] op_sel_hi:[1,0]
	v_pk_mul_f32 v[16:17], v[16:17], v[112:113]
	v_pk_mul_f32 v[18:19], v[18:19], v[114:115]
	v_pk_mul_f32 v[20:21], v[20:21], v[116:117]
	v_pk_mul_f32 v[22:23], v[22:23], v[118:119]
	v_pk_mul_f32 v[24:25], v[24:25], v[120:121]
	v_pk_mul_f32 v[26:27], v[26:27], v[122:123]
	v_pk_mul_f32 v[28:29], v[28:29], v[124:125]
	v_pk_mul_f32 v[30:31], v[30:31], v[126:127]
	v_cvt_pk_bf16_f32 v40, v16, v17
	v_cvt_pk_bf16_f32 v41, v18, v19
	v_cvt_pk_bf16_f32 v42, v20, v21
	v_cvt_pk_bf16_f32 v43, v22, v23
	v_cvt_pk_bf16_f32 v44, v24, v25
	v_cvt_pk_bf16_f32 v45, v26, v27
	v_cvt_pk_bf16_f32 v46, v28, v29
	v_cvt_pk_bf16_f32 v47, v30, v31
	s_lshl_b32 s11, s8, 11
	v_add_u32_e32 v7, s11, v2
	global_store_dwordx4 v7, v[40:43], s[2:3]
	global_store_dwordx4 v7, v[44:47], s[2:3] offset:16
	s_branch .Lp5h_done
.Lp5h_last1:
	s_waitcnt vmcnt(0)
	v_fmamk_f32 v8, v104, 0x3a800000, v105
	v_mul_f32_e32 v9, 0x4b800000, v8
	v_cmp_gt_f32_e64 s[0:1], s39, v8
	s_nop 1
	v_cndmask_b32_e64 v8, v8, v9, s[0:1]
	v_rsq_f32_e32 v8, v8
	s_nop 0
	v_mul_f32_e32 v9, 0x45800000, v8
	v_cndmask_b32_e64 v8, v8, v9, s[0:1]
	v_pk_mul_f32 v[16:17], v[88:89], v[8:9] op_sel_hi:[1,0]
	v_pk_mul_f32 v[18:19], v[90:91], v[8:9] op_sel_hi:[1,0]
	v_pk_mul_f32 v[20:21], v[92:93], v[8:9] op_sel_hi:[1,0]
	v_pk_mul_f32 v[22:23], v[94:95], v[8:9] op_sel_hi:[1,0]
	v_pk_mul_f32 v[24:25], v[96:97], v[8:9] op_sel_hi:[1,0]
	v_pk_mul_f32 v[26:27], v[98:99], v[8:9] op_sel_hi:[1,0]
	v_pk_mul_f32 v[28:29], v[100:101], v[8:9] op_sel_hi:[1,0]
	v_pk_mul_f32 v[30:31], v[102:103], v[8:9] op_sel_hi:[1,0]
	v_pk_mul_f32 v[16:17], v[16:17], v[112:113]
	v_pk_mul_f32 v[18:19], v[18:19], v[114:115]
	v_pk_mul_f32 v[20:21], v[20:21], v[116:117]
	v_pk_mul_f32 v[22:23], v[22:23], v[118:119]
	v_pk_mul_f32 v[24:25], v[24:25], v[120:121]
	v_pk_mul_f32 v[26:27], v[26:27], v[122:123]
	v_pk_mul_f32 v[28:29], v[28:29], v[124:125]
	v_pk_mul_f32 v[30:31], v[30:31], v[126:127]
	v_cvt_pk_bf16_f32 v40, v16, v17
	v_cvt_pk_bf16_f32 v41, v18, v19
	v_cvt_pk_bf16_f32 v42, v20, v21
	v_cvt_pk_bf16_f32 v43, v22, v23
	v_cvt_pk_bf16_f32 v44, v24, v25
	v_cvt_pk_bf16_f32 v45, v26, v27
	v_cvt_pk_bf16_f32 v46, v28, v29
	v_cvt_pk_bf16_f32 v47, v30, v31
	s_lshl_b32 s11, s12, 11
	v_add_u32_e32 v7, s11, v2
	global_store_dwordx4 v7, v[40:43], s[2:3]
	global_store_dwordx4 v7, v[44:47], s[2:3] offset:16
.Lp5h_done:
.LBB0_1522:
	v_accvgpr_read_b32 v234, a124
	v_accvgpr_read_b32 v237, a125
	v_accvgpr_read_b32 v240, a130
